# v42 + back-edge rotation (7.11) in 6 GEMM K-loops: loop-back barrier becomes the loop head, counter/exit test runs before it
# baseline (speedup 1.0000x reference)
.LBB0_187:
	s_add_u32 s14, s4, 0x100
	s_addc_u32 s15, s5, 0
	s_mov_b32 s16, -2
	ds_read_b128 v[128:131], v168
	ds_read_b128 v[152:155], v168 offset:1024
	ds_read_b128 v[180:183], v168 offset:2048
	ds_read_b128 v[184:187], v168 offset:3072
	ds_read_b128 v[188:191], v169
	ds_read_b128 v[192:195], v169 offset:1024
	ds_read_b128 v[196:199], v169 offset:2048
	ds_read_b128 v[200:203], v169 offset:3072
	s_add_u32 s4, s0, 0x100
	s_addc_u32 s5, s1, 0
	s_cmp_eq_u32 s16, 12
	s_cselect_b32 s13, s95, s5
	s_cselect_b32 s12, s94, s4
	s_cselect_b32 s11, s97, s15
	s_cselect_b32 s10, s96, s14
	v_lshl_add_u64 v[156:157], s[0:1], 0, v[144:145]
	s_add_i32 m0, s89, 0xc000
	ds_read_b128 v[204:207], v170
	ds_read_b128 v[208:211], v170 offset:1024
	ds_read_b128 v[212:215], v170 offset:2048
	ds_read_b128 v[216:219], v170 offset:3072
	ds_read_b128 v[220:223], v170 offset:4096
	ds_read_b128 v[224:227], v170 offset:5120
	ds_read_b128 v[228:231], v170 offset:6144
	ds_read_b128 v[232:235], v170 offset:7168
	global_load_lds_dwordx4 v[156:157], off
	v_lshl_add_u64 v[156:157], s[0:1], 0, v[146:147]
	s_add_i32 m0, s89, 0xe000
	s_nop 0
	global_load_lds_dwordx4 v[156:157], off
	s_waitcnt vmcnt(8)
	s_waitcnt lgkmcnt(0)
	s_barrier
	s_waitcnt lgkmcnt(0)
	v_mfma_f32_16x16x32_f16 v[84:87], v[128:131], v[204:207], 0
	v_mfma_f32_16x16x32_f16 v[92:95], v[180:183], v[204:207], 0
	v_mfma_f32_16x16x32_f16 v[68:71], v[128:131], v[212:215], 0
	v_mfma_f32_16x16x32_f16 v[76:79], v[180:183], v[212:215], 0
	v_mfma_f32_16x16x32_f16 v[52:55], v[128:131], v[220:223], 0
	v_mfma_f32_16x16x32_f16 v[124:127], v[180:183], v[220:223], 0
	v_mfma_f32_16x16x32_f16 v[60:63], v[128:131], v[228:231], 0
	v_mfma_f32_16x16x32_f16 v[116:119], v[180:183], v[228:231], 0
	v_mfma_f32_16x16x32_f16 v[84:87], v[152:155], v[208:211], v[84:87]
	v_mfma_f32_16x16x32_f16 v[92:95], v[184:187], v[208:211], v[92:95]
	v_mfma_f32_16x16x32_f16 v[68:71], v[152:155], v[216:219], v[68:71]
	v_mfma_f32_16x16x32_f16 v[76:79], v[184:187], v[216:219], v[76:79]
	v_mfma_f32_16x16x32_f16 v[52:55], v[152:155], v[224:227], v[52:55]
	v_mfma_f32_16x16x32_f16 v[124:127], v[184:187], v[224:227], v[124:127]
	v_mfma_f32_16x16x32_f16 v[60:63], v[152:155], v[232:235], v[60:63]
	v_mfma_f32_16x16x32_f16 v[116:119], v[184:187], v[232:235], v[116:119]
	v_mfma_f32_16x16x32_f16 v[88:91], v[188:191], v[204:207], 0
	v_mfma_f32_16x16x32_f16 v[80:83], v[196:199], v[204:207], 0
	v_mfma_f32_16x16x32_f16 v[72:75], v[188:191], v[212:215], 0
	v_mfma_f32_16x16x32_f16 v[64:67], v[196:199], v[212:215], 0
	v_mfma_f32_16x16x32_f16 v[120:123], v[188:191], v[220:223], 0
	v_mfma_f32_16x16x32_f16 v[48:51], v[196:199], v[220:223], 0
	v_mfma_f32_16x16x32_f16 v[112:115], v[188:191], v[228:231], 0
	v_mfma_f32_16x16x32_f16 v[56:59], v[196:199], v[228:231], 0
	v_mfma_f32_16x16x32_f16 v[88:91], v[192:195], v[208:211], v[88:91]
	v_mfma_f32_16x16x32_f16 v[80:83], v[200:203], v[208:211], v[80:83]
	v_mfma_f32_16x16x32_f16 v[72:75], v[192:195], v[216:219], v[72:75]
	v_mfma_f32_16x16x32_f16 v[64:67], v[200:203], v[216:219], v[64:67]
	v_mfma_f32_16x16x32_f16 v[120:123], v[192:195], v[224:227], v[120:123]
	v_mfma_f32_16x16x32_f16 v[48:51], v[200:203], v[224:227], v[48:51]
	v_mfma_f32_16x16x32_f16 v[112:115], v[192:195], v[232:235], v[112:115]
	v_mfma_f32_16x16x32_f16 v[56:59], v[200:203], v[232:235], v[56:59]
	s_barrier
	s_add_i32 s0, s23, s88
	v_lshl_add_u64 v[156:157], s[10:11], 0, v[134:135]
	s_mov_b32 m0, s0
	ds_read_b128 v[204:207], v170 offset:16384
	ds_read_b128 v[208:211], v170 offset:17408
	ds_read_b128 v[212:215], v170 offset:18432
	ds_read_b128 v[216:219], v170 offset:19456
	ds_read_b128 v[220:223], v170 offset:20480
	ds_read_b128 v[224:227], v170 offset:21504
	ds_read_b128 v[228:231], v170 offset:22528
	ds_read_b128 v[232:235], v170 offset:23552
	global_load_lds_dwordx4 v[156:157], off
	s_add_i32 m0, s0, 0x2000
	s_add_u32 s0, s10, 0x40000
	v_lshl_add_u64 v[236:237], s[10:11], 0, v[138:139]
	s_addc_u32 s1, s11, 0
	s_add_i32 s17, s22, s88
	global_load_lds_dwordx4 v[236:237], off
	v_lshl_add_u64 v[238:239], s[0:1], 0, v[134:135]
	s_mov_b32 m0, s17
	v_lshl_add_u64 v[240:241], s[12:13], 0, v[136:137]
	global_load_lds_dwordx4 v[238:239], off
	v_lshl_add_u64 v[238:239], s[0:1], 0, v[138:139]
	s_add_i32 m0, s17, 0x2000
	s_nop 0
	global_load_lds_dwordx4 v[238:239], off
	v_lshl_add_u64 v[238:239], s[12:13], 0, v[132:133]
	s_mov_b32 m0, s89
	s_nop 0
	global_load_lds_dwordx4 v[238:239], off
	s_mov_b32 m0, s3
	s_nop 0
	global_load_lds_dwordx4 v[240:241], off
	s_waitcnt vmcnt(8)
	s_waitcnt lgkmcnt(0)
	s_barrier
	s_waitcnt lgkmcnt(0)
	v_mfma_f32_16x16x32_f16 v[36:39], v[128:131], v[204:207], 0
	v_mfma_f32_16x16x32_f16 v[44:47], v[180:183], v[204:207], 0
	v_mfma_f32_16x16x32_f16 v[20:23], v[128:131], v[212:215], 0
	v_mfma_f32_16x16x32_f16 v[32:35], v[180:183], v[212:215], 0
	v_mfma_f32_16x16x32_f16 v[4:7], v[128:131], v[220:223], 0
	v_mfma_f32_16x16x32_f16 v[108:111], v[180:183], v[220:223], 0
	v_mfma_f32_16x16x32_f16 v[12:15], v[128:131], v[228:231], 0
	v_mfma_f32_16x16x32_f16 v[100:103], v[180:183], v[228:231], 0
	v_mfma_f32_16x16x32_f16 v[36:39], v[152:155], v[208:211], v[36:39]
	v_mfma_f32_16x16x32_f16 v[44:47], v[184:187], v[208:211], v[44:47]
	v_mfma_f32_16x16x32_f16 v[20:23], v[152:155], v[216:219], v[20:23]
	v_mfma_f32_16x16x32_f16 v[32:35], v[184:187], v[216:219], v[32:35]
	v_mfma_f32_16x16x32_f16 v[4:7], v[152:155], v[224:227], v[4:7]
	v_mfma_f32_16x16x32_f16 v[108:111], v[184:187], v[224:227], v[108:111]
	v_mfma_f32_16x16x32_f16 v[12:15], v[152:155], v[232:235], v[12:15]
	v_mfma_f32_16x16x32_f16 v[100:103], v[184:187], v[232:235], v[100:103]
	v_mfma_f32_16x16x32_f16 v[40:43], v[188:191], v[204:207], 0
	v_mfma_f32_16x16x32_f16 v[28:31], v[196:199], v[204:207], 0
	v_mfma_f32_16x16x32_f16 v[24:27], v[188:191], v[212:215], 0
	v_mfma_f32_16x16x32_f16 v[16:19], v[196:199], v[212:215], 0
	v_mfma_f32_16x16x32_f16 v[104:107], v[188:191], v[220:223], 0
	v_mfma_f32_16x16x32_f16 v[0:3], v[196:199], v[220:223], 0
	v_mfma_f32_16x16x32_f16 v[96:99], v[188:191], v[228:231], 0
	v_mfma_f32_16x16x32_f16 v[8:11], v[196:199], v[228:231], 0
	v_mfma_f32_16x16x32_f16 v[40:43], v[192:195], v[208:211], v[40:43]
	v_mfma_f32_16x16x32_f16 v[28:31], v[200:203], v[208:211], v[28:31]
	v_mfma_f32_16x16x32_f16 v[24:27], v[192:195], v[216:219], v[24:27]
	v_mfma_f32_16x16x32_f16 v[16:19], v[200:203], v[216:219], v[16:19]
	v_mfma_f32_16x16x32_f16 v[104:107], v[192:195], v[224:227], v[104:107]
	v_mfma_f32_16x16x32_f16 v[0:3], v[200:203], v[224:227], v[0:3]
	v_mfma_f32_16x16x32_f16 v[96:99], v[192:195], v[232:235], v[96:99]
	v_mfma_f32_16x16x32_f16 v[8:11], v[200:203], v[232:235], v[8:11]
	s_barrier
	ds_read_b128 v[128:131], v171
	ds_read_b128 v[152:155], v171 offset:1024
	ds_read_b128 v[180:183], v171 offset:2048
	ds_read_b128 v[184:187], v171 offset:3072
	ds_read_b128 v[188:191], v172
	ds_read_b128 v[192:195], v172 offset:1024
	ds_read_b128 v[196:199], v172 offset:2048
	ds_read_b128 v[200:203], v172 offset:3072
	s_add_u32 s0, s12, 0x40000
	s_addc_u32 s1, s13, 0
	s_mov_b32 m0, s33
	v_lshl_add_u64 v[242:243], s[0:1], 0, v[132:133]
	ds_read_b128 v[204:207], v170 offset:32768
	ds_read_b128 v[208:211], v170 offset:33792
	ds_read_b128 v[212:215], v170 offset:34816
	ds_read_b128 v[216:219], v170 offset:35840
	ds_read_b128 v[220:223], v170 offset:36864
	ds_read_b128 v[224:227], v170 offset:37888
	ds_read_b128 v[228:231], v170 offset:38912
	ds_read_b128 v[232:235], v170 offset:39936
	global_load_lds_dwordx4 v[242:243], off
	v_lshl_add_u64 v[242:243], s[0:1], 0, v[136:137]
	s_mov_b32 m0, s50
	s_nop 0
	global_load_lds_dwordx4 v[242:243], off
	s_waitcnt vmcnt(8)
	s_waitcnt lgkmcnt(0)
	s_barrier
	s_waitcnt lgkmcnt(0)
	v_mfma_f32_16x16x32_f16 v[84:87], v[128:131], v[204:207], v[84:87]
	v_mfma_f32_16x16x32_f16 v[92:95], v[180:183], v[204:207], v[92:95]
	v_mfma_f32_16x16x32_f16 v[68:71], v[128:131], v[212:215], v[68:71]
	v_mfma_f32_16x16x32_f16 v[76:79], v[180:183], v[212:215], v[76:79]
	v_mfma_f32_16x16x32_f16 v[52:55], v[128:131], v[220:223], v[52:55]
	v_mfma_f32_16x16x32_f16 v[124:127], v[180:183], v[220:223], v[124:127]
	v_mfma_f32_16x16x32_f16 v[60:63], v[128:131], v[228:231], v[60:63]
	v_mfma_f32_16x16x32_f16 v[116:119], v[180:183], v[228:231], v[116:119]
	v_mfma_f32_16x16x32_f16 v[84:87], v[152:155], v[208:211], v[84:87]
	v_mfma_f32_16x16x32_f16 v[92:95], v[184:187], v[208:211], v[92:95]
	v_mfma_f32_16x16x32_f16 v[68:71], v[152:155], v[216:219], v[68:71]
	v_mfma_f32_16x16x32_f16 v[76:79], v[184:187], v[216:219], v[76:79]
	v_mfma_f32_16x16x32_f16 v[52:55], v[152:155], v[224:227], v[52:55]
	v_mfma_f32_16x16x32_f16 v[124:127], v[184:187], v[224:227], v[124:127]
	v_mfma_f32_16x16x32_f16 v[60:63], v[152:155], v[232:235], v[60:63]
	v_mfma_f32_16x16x32_f16 v[116:119], v[184:187], v[232:235], v[116:119]
	v_mfma_f32_16x16x32_f16 v[88:91], v[188:191], v[204:207], v[88:91]
	v_mfma_f32_16x16x32_f16 v[80:83], v[196:199], v[204:207], v[80:83]
	v_mfma_f32_16x16x32_f16 v[72:75], v[188:191], v[212:215], v[72:75]
	v_mfma_f32_16x16x32_f16 v[64:67], v[196:199], v[212:215], v[64:67]
	v_mfma_f32_16x16x32_f16 v[120:123], v[188:191], v[220:223], v[120:123]
	v_mfma_f32_16x16x32_f16 v[48:51], v[196:199], v[220:223], v[48:51]
	v_mfma_f32_16x16x32_f16 v[112:115], v[188:191], v[228:231], v[112:115]
	v_mfma_f32_16x16x32_f16 v[56:59], v[196:199], v[228:231], v[56:59]
	v_mfma_f32_16x16x32_f16 v[88:91], v[192:195], v[208:211], v[88:91]
	v_mfma_f32_16x16x32_f16 v[80:83], v[200:203], v[208:211], v[80:83]
	v_mfma_f32_16x16x32_f16 v[72:75], v[192:195], v[216:219], v[72:75]
	v_mfma_f32_16x16x32_f16 v[64:67], v[200:203], v[216:219], v[64:67]
	v_mfma_f32_16x16x32_f16 v[120:123], v[192:195], v[224:227], v[120:123]
	v_mfma_f32_16x16x32_f16 v[48:51], v[200:203], v[224:227], v[48:51]
	v_mfma_f32_16x16x32_f16 v[112:115], v[192:195], v[232:235], v[112:115]
	v_mfma_f32_16x16x32_f16 v[56:59], v[200:203], v[232:235], v[56:59]
	s_barrier
	s_add_i32 s0, s36, s88
	v_lshl_add_u64 v[156:157], v[156:157], 0, s[26:27]
	s_mov_b32 m0, s0
	ds_read_b128 v[204:207], v170 offset:49152
	ds_read_b128 v[208:211], v170 offset:50176
	ds_read_b128 v[212:215], v170 offset:51200
	ds_read_b128 v[216:219], v170 offset:52224
	ds_read_b128 v[220:223], v170 offset:53248
	ds_read_b128 v[224:227], v170 offset:54272
	ds_read_b128 v[228:231], v170 offset:55296
	ds_read_b128 v[232:235], v170 offset:56320
	global_load_lds_dwordx4 v[156:157], off
	s_add_i32 m0, s0, 0x2000
	s_add_u32 s0, s10, 0x40080
	v_lshl_add_u64 v[156:157], v[236:237], 0, s[26:27]
	s_addc_u32 s1, s11, 0
	s_add_i32 s10, s37, s88
	global_load_lds_dwordx4 v[156:157], off
	v_lshl_add_u64 v[156:157], s[0:1], 0, v[134:135]
	s_mov_b32 m0, s10
	s_nop 0
	global_load_lds_dwordx4 v[156:157], off
	v_lshl_add_u64 v[156:157], s[0:1], 0, v[138:139]
	s_add_i32 m0, s10, 0x2000
	s_nop 0
	global_load_lds_dwordx4 v[156:157], off
	v_lshl_add_u64 v[156:157], v[238:239], 0, s[26:27]
	s_mov_b32 m0, s51
	s_nop 0
	global_load_lds_dwordx4 v[156:157], off
	v_lshl_add_u64 v[156:157], v[240:241], 0, s[26:27]
	s_mov_b32 m0, s82
	s_nop 0
	global_load_lds_dwordx4 v[156:157], off
	s_waitcnt vmcnt(8)
	s_waitcnt lgkmcnt(0)
	s_barrier
	s_waitcnt lgkmcnt(0)
	v_mfma_f32_16x16x32_f16 v[36:39], v[128:131], v[204:207], v[36:39]
	v_mfma_f32_16x16x32_f16 v[44:47], v[180:183], v[204:207], v[44:47]
	v_mfma_f32_16x16x32_f16 v[20:23], v[128:131], v[212:215], v[20:23]
	v_mfma_f32_16x16x32_f16 v[32:35], v[180:183], v[212:215], v[32:35]
	v_mfma_f32_16x16x32_f16 v[4:7], v[128:131], v[220:223], v[4:7]
	v_mfma_f32_16x16x32_f16 v[108:111], v[180:183], v[220:223], v[108:111]
	v_mfma_f32_16x16x32_f16 v[12:15], v[128:131], v[228:231], v[12:15]
	v_mfma_f32_16x16x32_f16 v[100:103], v[180:183], v[228:231], v[100:103]
	v_mfma_f32_16x16x32_f16 v[36:39], v[152:155], v[208:211], v[36:39]
	v_mfma_f32_16x16x32_f16 v[44:47], v[184:187], v[208:211], v[44:47]
	v_mfma_f32_16x16x32_f16 v[20:23], v[152:155], v[216:219], v[20:23]
	v_mfma_f32_16x16x32_f16 v[32:35], v[184:187], v[216:219], v[32:35]
	v_mfma_f32_16x16x32_f16 v[4:7], v[152:155], v[224:227], v[4:7]
	v_mfma_f32_16x16x32_f16 v[108:111], v[184:187], v[224:227], v[108:111]
	v_mfma_f32_16x16x32_f16 v[12:15], v[152:155], v[232:235], v[12:15]
	v_mfma_f32_16x16x32_f16 v[100:103], v[184:187], v[232:235], v[100:103]
	v_mfma_f32_16x16x32_f16 v[40:43], v[188:191], v[204:207], v[40:43]
	v_mfma_f32_16x16x32_f16 v[28:31], v[196:199], v[204:207], v[28:31]
	v_mfma_f32_16x16x32_f16 v[24:27], v[188:191], v[212:215], v[24:27]
	v_mfma_f32_16x16x32_f16 v[16:19], v[196:199], v[212:215], v[16:19]
	v_mfma_f32_16x16x32_f16 v[104:107], v[188:191], v[220:223], v[104:107]
	v_mfma_f32_16x16x32_f16 v[0:3], v[196:199], v[220:223], v[0:3]
	v_mfma_f32_16x16x32_f16 v[96:99], v[188:191], v[228:231], v[96:99]
	v_mfma_f32_16x16x32_f16 v[8:11], v[196:199], v[228:231], v[8:11]
	v_mfma_f32_16x16x32_f16 v[40:43], v[192:195], v[208:211], v[40:43]
	v_mfma_f32_16x16x32_f16 v[28:31], v[200:203], v[208:211], v[28:31]
	v_mfma_f32_16x16x32_f16 v[24:27], v[192:195], v[216:219], v[24:27]
	v_mfma_f32_16x16x32_f16 v[16:19], v[200:203], v[216:219], v[16:19]
	v_mfma_f32_16x16x32_f16 v[104:107], v[192:195], v[224:227], v[104:107]
	v_mfma_f32_16x16x32_f16 v[0:3], v[200:203], v[224:227], v[0:3]
	v_mfma_f32_16x16x32_f16 v[96:99], v[192:195], v[232:235], v[96:99]
	v_mfma_f32_16x16x32_f16 v[8:11], v[200:203], v[232:235], v[8:11]
	s_add_i32 s16, s16, 2
	s_add_u32 s14, s14, 0x100
	s_addc_u32 s15, s15, 0
	s_cmp_gt_u32 s16, 13
	s_mov_b64 s[0:1], s[4:5]
.LBB0_188:
	s_barrier
	ds_read_b128 v[128:131], v168
	ds_read_b128 v[152:155], v168 offset:1024
	ds_read_b128 v[180:183], v168 offset:2048
	ds_read_b128 v[184:187], v168 offset:3072
	ds_read_b128 v[188:191], v169
	ds_read_b128 v[192:195], v169 offset:1024
	ds_read_b128 v[196:199], v169 offset:2048
	ds_read_b128 v[200:203], v169 offset:3072
	s_add_u32 s4, s0, 0x100
	s_addc_u32 s5, s1, 0
	s_cmp_eq_u32 s16, 12
	s_cselect_b32 s13, s95, s5
	s_cselect_b32 s12, s94, s4
	s_cselect_b32 s11, s97, s15
	s_cselect_b32 s10, s96, s14
	v_lshl_add_u64 v[156:157], s[0:1], 0, v[144:145]
	s_add_i32 m0, s89, 0xc000
	ds_read_b128 v[204:207], v170
	ds_read_b128 v[208:211], v170 offset:1024
	ds_read_b128 v[212:215], v170 offset:2048
	ds_read_b128 v[216:219], v170 offset:3072
	ds_read_b128 v[220:223], v170 offset:4096
	ds_read_b128 v[224:227], v170 offset:5120
	ds_read_b128 v[228:231], v170 offset:6144
	ds_read_b128 v[232:235], v170 offset:7168
	global_load_lds_dwordx4 v[156:157], off
	v_lshl_add_u64 v[156:157], s[0:1], 0, v[146:147]
	s_add_i32 m0, s89, 0xe000
	s_nop 0
	global_load_lds_dwordx4 v[156:157], off
	s_waitcnt vmcnt(8)
	s_waitcnt lgkmcnt(0)
	s_barrier
	s_waitcnt lgkmcnt(0)
	v_mfma_f32_16x16x32_f16 v[84:87], v[128:131], v[204:207], v[84:87]
	v_mfma_f32_16x16x32_f16 v[92:95], v[180:183], v[204:207], v[92:95]
	v_mfma_f32_16x16x32_f16 v[68:71], v[128:131], v[212:215], v[68:71]
	v_mfma_f32_16x16x32_f16 v[76:79], v[180:183], v[212:215], v[76:79]
	v_mfma_f32_16x16x32_f16 v[52:55], v[128:131], v[220:223], v[52:55]
	v_mfma_f32_16x16x32_f16 v[124:127], v[180:183], v[220:223], v[124:127]
	v_mfma_f32_16x16x32_f16 v[60:63], v[128:131], v[228:231], v[60:63]
	v_mfma_f32_16x16x32_f16 v[116:119], v[180:183], v[228:231], v[116:119]
	v_mfma_f32_16x16x32_f16 v[84:87], v[152:155], v[208:211], v[84:87]
	v_mfma_f32_16x16x32_f16 v[92:95], v[184:187], v[208:211], v[92:95]
	v_mfma_f32_16x16x32_f16 v[68:71], v[152:155], v[216:219], v[68:71]
	v_mfma_f32_16x16x32_f16 v[76:79], v[184:187], v[216:219], v[76:79]
	v_mfma_f32_16x16x32_f16 v[52:55], v[152:155], v[224:227], v[52:55]
	v_mfma_f32_16x16x32_f16 v[124:127], v[184:187], v[224:227], v[124:127]
	v_mfma_f32_16x16x32_f16 v[60:63], v[152:155], v[232:235], v[60:63]
	v_mfma_f32_16x16x32_f16 v[116:119], v[184:187], v[232:235], v[116:119]
	v_mfma_f32_16x16x32_f16 v[88:91], v[188:191], v[204:207], v[88:91]
	v_mfma_f32_16x16x32_f16 v[80:83], v[196:199], v[204:207], v[80:83]
	v_mfma_f32_16x16x32_f16 v[72:75], v[188:191], v[212:215], v[72:75]
	v_mfma_f32_16x16x32_f16 v[64:67], v[196:199], v[212:215], v[64:67]
	v_mfma_f32_16x16x32_f16 v[120:123], v[188:191], v[220:223], v[120:123]
	v_mfma_f32_16x16x32_f16 v[48:51], v[196:199], v[220:223], v[48:51]
	v_mfma_f32_16x16x32_f16 v[112:115], v[188:191], v[228:231], v[112:115]
	v_mfma_f32_16x16x32_f16 v[56:59], v[196:199], v[228:231], v[56:59]
	v_mfma_f32_16x16x32_f16 v[88:91], v[192:195], v[208:211], v[88:91]
	v_mfma_f32_16x16x32_f16 v[80:83], v[200:203], v[208:211], v[80:83]
	v_mfma_f32_16x16x32_f16 v[72:75], v[192:195], v[216:219], v[72:75]
	v_mfma_f32_16x16x32_f16 v[64:67], v[200:203], v[216:219], v[64:67]
	v_mfma_f32_16x16x32_f16 v[120:123], v[192:195], v[224:227], v[120:123]
	v_mfma_f32_16x16x32_f16 v[48:51], v[200:203], v[224:227], v[48:51]
	v_mfma_f32_16x16x32_f16 v[112:115], v[192:195], v[232:235], v[112:115]
	v_mfma_f32_16x16x32_f16 v[56:59], v[200:203], v[232:235], v[56:59]
	s_barrier
	s_add_i32 s0, s23, s88
	v_lshl_add_u64 v[156:157], s[10:11], 0, v[134:135]
	s_mov_b32 m0, s0
	ds_read_b128 v[204:207], v170 offset:16384
	ds_read_b128 v[208:211], v170 offset:17408
	ds_read_b128 v[212:215], v170 offset:18432
	ds_read_b128 v[216:219], v170 offset:19456
	ds_read_b128 v[220:223], v170 offset:20480
	ds_read_b128 v[224:227], v170 offset:21504
	ds_read_b128 v[228:231], v170 offset:22528
	ds_read_b128 v[232:235], v170 offset:23552
	global_load_lds_dwordx4 v[156:157], off
	s_add_i32 m0, s0, 0x2000
	s_add_u32 s0, s10, 0x40000
	v_lshl_add_u64 v[236:237], s[10:11], 0, v[138:139]
	s_addc_u32 s1, s11, 0
	s_add_i32 s17, s22, s88
	global_load_lds_dwordx4 v[236:237], off
	v_lshl_add_u64 v[238:239], s[0:1], 0, v[134:135]
	s_mov_b32 m0, s17
	v_lshl_add_u64 v[240:241], s[12:13], 0, v[136:137]
	global_load_lds_dwordx4 v[238:239], off
	v_lshl_add_u64 v[238:239], s[0:1], 0, v[138:139]
	s_add_i32 m0, s17, 0x2000
	s_nop 0
	global_load_lds_dwordx4 v[238:239], off
	v_lshl_add_u64 v[238:239], s[12:13], 0, v[132:133]
	s_mov_b32 m0, s89
	s_nop 0
	global_load_lds_dwordx4 v[238:239], off
	s_mov_b32 m0, s3
	s_nop 0
	global_load_lds_dwordx4 v[240:241], off
	s_waitcnt vmcnt(8)
	s_waitcnt lgkmcnt(0)
	s_barrier
	s_waitcnt lgkmcnt(0)
	v_mfma_f32_16x16x32_f16 v[36:39], v[128:131], v[204:207], v[36:39]
	v_mfma_f32_16x16x32_f16 v[44:47], v[180:183], v[204:207], v[44:47]
	v_mfma_f32_16x16x32_f16 v[20:23], v[128:131], v[212:215], v[20:23]
	v_mfma_f32_16x16x32_f16 v[32:35], v[180:183], v[212:215], v[32:35]
	v_mfma_f32_16x16x32_f16 v[4:7], v[128:131], v[220:223], v[4:7]
	v_mfma_f32_16x16x32_f16 v[108:111], v[180:183], v[220:223], v[108:111]
	v_mfma_f32_16x16x32_f16 v[12:15], v[128:131], v[228:231], v[12:15]
	v_mfma_f32_16x16x32_f16 v[100:103], v[180:183], v[228:231], v[100:103]
	v_mfma_f32_16x16x32_f16 v[36:39], v[152:155], v[208:211], v[36:39]
	v_mfma_f32_16x16x32_f16 v[44:47], v[184:187], v[208:211], v[44:47]
	v_mfma_f32_16x16x32_f16 v[20:23], v[152:155], v[216:219], v[20:23]
	v_mfma_f32_16x16x32_f16 v[32:35], v[184:187], v[216:219], v[32:35]
	v_mfma_f32_16x16x32_f16 v[4:7], v[152:155], v[224:227], v[4:7]
	v_mfma_f32_16x16x32_f16 v[108:111], v[184:187], v[224:227], v[108:111]
	v_mfma_f32_16x16x32_f16 v[12:15], v[152:155], v[232:235], v[12:15]
	v_mfma_f32_16x16x32_f16 v[100:103], v[184:187], v[232:235], v[100:103]
	v_mfma_f32_16x16x32_f16 v[40:43], v[188:191], v[204:207], v[40:43]
	v_mfma_f32_16x16x32_f16 v[28:31], v[196:199], v[204:207], v[28:31]
	v_mfma_f32_16x16x32_f16 v[24:27], v[188:191], v[212:215], v[24:27]
	v_mfma_f32_16x16x32_f16 v[16:19], v[196:199], v[212:215], v[16:19]
	v_mfma_f32_16x16x32_f16 v[104:107], v[188:191], v[220:223], v[104:107]
	v_mfma_f32_16x16x32_f16 v[0:3], v[196:199], v[220:223], v[0:3]
	v_mfma_f32_16x16x32_f16 v[96:99], v[188:191], v[228:231], v[96:99]
	v_mfma_f32_16x16x32_f16 v[8:11], v[196:199], v[228:231], v[8:11]
	v_mfma_f32_16x16x32_f16 v[40:43], v[192:195], v[208:211], v[40:43]
	v_mfma_f32_16x16x32_f16 v[28:31], v[200:203], v[208:211], v[28:31]
	v_mfma_f32_16x16x32_f16 v[24:27], v[192:195], v[216:219], v[24:27]
	v_mfma_f32_16x16x32_f16 v[16:19], v[200:203], v[216:219], v[16:19]
	v_mfma_f32_16x16x32_f16 v[104:107], v[192:195], v[224:227], v[104:107]
	v_mfma_f32_16x16x32_f16 v[0:3], v[200:203], v[224:227], v[0:3]
	v_mfma_f32_16x16x32_f16 v[96:99], v[192:195], v[232:235], v[96:99]
	v_mfma_f32_16x16x32_f16 v[8:11], v[200:203], v[232:235], v[8:11]
	s_barrier
	ds_read_b128 v[128:131], v171
	ds_read_b128 v[152:155], v171 offset:1024
	ds_read_b128 v[180:183], v171 offset:2048
	ds_read_b128 v[184:187], v171 offset:3072
	ds_read_b128 v[188:191], v172
	ds_read_b128 v[192:195], v172 offset:1024
	ds_read_b128 v[196:199], v172 offset:2048
	ds_read_b128 v[200:203], v172 offset:3072
	s_add_u32 s0, s12, 0x40000
	s_addc_u32 s1, s13, 0
	s_mov_b32 m0, s33
	v_lshl_add_u64 v[242:243], s[0:1], 0, v[132:133]
	ds_read_b128 v[204:207], v170 offset:32768
	ds_read_b128 v[208:211], v170 offset:33792
	ds_read_b128 v[212:215], v170 offset:34816
	ds_read_b128 v[216:219], v170 offset:35840
	ds_read_b128 v[220:223], v170 offset:36864
	ds_read_b128 v[224:227], v170 offset:37888
	ds_read_b128 v[228:231], v170 offset:38912
	ds_read_b128 v[232:235], v170 offset:39936
	global_load_lds_dwordx4 v[242:243], off
	v_lshl_add_u64 v[242:243], s[0:1], 0, v[136:137]
	s_mov_b32 m0, s50
	s_nop 0
	global_load_lds_dwordx4 v[242:243], off
	s_waitcnt vmcnt(8)
	s_waitcnt lgkmcnt(0)
	s_barrier
	s_waitcnt lgkmcnt(0)
	v_mfma_f32_16x16x32_f16 v[84:87], v[128:131], v[204:207], v[84:87]
	v_mfma_f32_16x16x32_f16 v[92:95], v[180:183], v[204:207], v[92:95]
	v_mfma_f32_16x16x32_f16 v[68:71], v[128:131], v[212:215], v[68:71]
	v_mfma_f32_16x16x32_f16 v[76:79], v[180:183], v[212:215], v[76:79]
	v_mfma_f32_16x16x32_f16 v[52:55], v[128:131], v[220:223], v[52:55]
	v_mfma_f32_16x16x32_f16 v[124:127], v[180:183], v[220:223], v[124:127]
	v_mfma_f32_16x16x32_f16 v[60:63], v[128:131], v[228:231], v[60:63]
	v_mfma_f32_16x16x32_f16 v[116:119], v[180:183], v[228:231], v[116:119]
	v_mfma_f32_16x16x32_f16 v[84:87], v[152:155], v[208:211], v[84:87]
	v_mfma_f32_16x16x32_f16 v[92:95], v[184:187], v[208:211], v[92:95]
	v_mfma_f32_16x16x32_f16 v[68:71], v[152:155], v[216:219], v[68:71]
	v_mfma_f32_16x16x32_f16 v[76:79], v[184:187], v[216:219], v[76:79]
	v_mfma_f32_16x16x32_f16 v[52:55], v[152:155], v[224:227], v[52:55]
	v_mfma_f32_16x16x32_f16 v[124:127], v[184:187], v[224:227], v[124:127]
	v_mfma_f32_16x16x32_f16 v[60:63], v[152:155], v[232:235], v[60:63]
	v_mfma_f32_16x16x32_f16 v[116:119], v[184:187], v[232:235], v[116:119]
	v_mfma_f32_16x16x32_f16 v[88:91], v[188:191], v[204:207], v[88:91]
	v_mfma_f32_16x16x32_f16 v[80:83], v[196:199], v[204:207], v[80:83]
	v_mfma_f32_16x16x32_f16 v[72:75], v[188:191], v[212:215], v[72:75]
	v_mfma_f32_16x16x32_f16 v[64:67], v[196:199], v[212:215], v[64:67]
	v_mfma_f32_16x16x32_f16 v[120:123], v[188:191], v[220:223], v[120:123]
	v_mfma_f32_16x16x32_f16 v[48:51], v[196:199], v[220:223], v[48:51]
	v_mfma_f32_16x16x32_f16 v[112:115], v[188:191], v[228:231], v[112:115]
	v_mfma_f32_16x16x32_f16 v[56:59], v[196:199], v[228:231], v[56:59]
	v_mfma_f32_16x16x32_f16 v[88:91], v[192:195], v[208:211], v[88:91]
	v_mfma_f32_16x16x32_f16 v[80:83], v[200:203], v[208:211], v[80:83]
	v_mfma_f32_16x16x32_f16 v[72:75], v[192:195], v[216:219], v[72:75]
	v_mfma_f32_16x16x32_f16 v[64:67], v[200:203], v[216:219], v[64:67]
	v_mfma_f32_16x16x32_f16 v[120:123], v[192:195], v[224:227], v[120:123]
	v_mfma_f32_16x16x32_f16 v[48:51], v[200:203], v[224:227], v[48:51]
	v_mfma_f32_16x16x32_f16 v[112:115], v[192:195], v[232:235], v[112:115]
	v_mfma_f32_16x16x32_f16 v[56:59], v[200:203], v[232:235], v[56:59]
	s_barrier
	s_add_i32 s0, s36, s88
	v_lshl_add_u64 v[156:157], v[156:157], 0, s[26:27]
	s_mov_b32 m0, s0
	ds_read_b128 v[204:207], v170 offset:49152
	ds_read_b128 v[208:211], v170 offset:50176
	ds_read_b128 v[212:215], v170 offset:51200
	ds_read_b128 v[216:219], v170 offset:52224
	ds_read_b128 v[220:223], v170 offset:53248
	ds_read_b128 v[224:227], v170 offset:54272
	ds_read_b128 v[228:231], v170 offset:55296
	ds_read_b128 v[232:235], v170 offset:56320
	global_load_lds_dwordx4 v[156:157], off
	s_add_i32 m0, s0, 0x2000
	s_add_u32 s0, s10, 0x40080
	v_lshl_add_u64 v[156:157], v[236:237], 0, s[26:27]
	s_addc_u32 s1, s11, 0
	s_add_i32 s10, s37, s88
	global_load_lds_dwordx4 v[156:157], off
	v_lshl_add_u64 v[156:157], s[0:1], 0, v[134:135]
	s_mov_b32 m0, s10
	s_nop 0
	global_load_lds_dwordx4 v[156:157], off
	v_lshl_add_u64 v[156:157], s[0:1], 0, v[138:139]
	s_add_i32 m0, s10, 0x2000
	s_nop 0
	global_load_lds_dwordx4 v[156:157], off
	v_lshl_add_u64 v[156:157], v[238:239], 0, s[26:27]
	s_mov_b32 m0, s51
	s_nop 0
	global_load_lds_dwordx4 v[156:157], off
	v_lshl_add_u64 v[156:157], v[240:241], 0, s[26:27]
	s_mov_b32 m0, s82
	s_nop 0
	global_load_lds_dwordx4 v[156:157], off
	s_waitcnt vmcnt(8)
	s_waitcnt lgkmcnt(0)
	s_barrier
	s_waitcnt lgkmcnt(0)
	v_mfma_f32_16x16x32_f16 v[36:39], v[128:131], v[204:207], v[36:39]
	v_mfma_f32_16x16x32_f16 v[44:47], v[180:183], v[204:207], v[44:47]
	v_mfma_f32_16x16x32_f16 v[20:23], v[128:131], v[212:215], v[20:23]
	v_mfma_f32_16x16x32_f16 v[32:35], v[180:183], v[212:215], v[32:35]
	v_mfma_f32_16x16x32_f16 v[4:7], v[128:131], v[220:223], v[4:7]
	v_mfma_f32_16x16x32_f16 v[108:111], v[180:183], v[220:223], v[108:111]
	v_mfma_f32_16x16x32_f16 v[12:15], v[128:131], v[228:231], v[12:15]
	v_mfma_f32_16x16x32_f16 v[100:103], v[180:183], v[228:231], v[100:103]
	v_mfma_f32_16x16x32_f16 v[36:39], v[152:155], v[208:211], v[36:39]
	v_mfma_f32_16x16x32_f16 v[44:47], v[184:187], v[208:211], v[44:47]
	v_mfma_f32_16x16x32_f16 v[20:23], v[152:155], v[216:219], v[20:23]
	v_mfma_f32_16x16x32_f16 v[32:35], v[184:187], v[216:219], v[32:35]
	v_mfma_f32_16x16x32_f16 v[4:7], v[152:155], v[224:227], v[4:7]
	v_mfma_f32_16x16x32_f16 v[108:111], v[184:187], v[224:227], v[108:111]
	v_mfma_f32_16x16x32_f16 v[12:15], v[152:155], v[232:235], v[12:15]
	v_mfma_f32_16x16x32_f16 v[100:103], v[184:187], v[232:235], v[100:103]
	v_mfma_f32_16x16x32_f16 v[40:43], v[188:191], v[204:207], v[40:43]
	v_mfma_f32_16x16x32_f16 v[28:31], v[196:199], v[204:207], v[28:31]
	v_mfma_f32_16x16x32_f16 v[24:27], v[188:191], v[212:215], v[24:27]
	v_mfma_f32_16x16x32_f16 v[16:19], v[196:199], v[212:215], v[16:19]
	v_mfma_f32_16x16x32_f16 v[104:107], v[188:191], v[220:223], v[104:107]
	v_mfma_f32_16x16x32_f16 v[0:3], v[196:199], v[220:223], v[0:3]
	v_mfma_f32_16x16x32_f16 v[96:99], v[188:191], v[228:231], v[96:99]
	v_mfma_f32_16x16x32_f16 v[8:11], v[196:199], v[228:231], v[8:11]
	v_mfma_f32_16x16x32_f16 v[40:43], v[192:195], v[208:211], v[40:43]
	v_mfma_f32_16x16x32_f16 v[28:31], v[200:203], v[208:211], v[28:31]
	v_mfma_f32_16x16x32_f16 v[24:27], v[192:195], v[216:219], v[24:27]
	v_mfma_f32_16x16x32_f16 v[16:19], v[200:203], v[216:219], v[16:19]
	v_mfma_f32_16x16x32_f16 v[104:107], v[192:195], v[224:227], v[104:107]
	v_mfma_f32_16x16x32_f16 v[0:3], v[200:203], v[224:227], v[0:3]
	v_mfma_f32_16x16x32_f16 v[96:99], v[192:195], v[232:235], v[96:99]
	v_mfma_f32_16x16x32_f16 v[8:11], v[200:203], v[232:235], v[8:11]
	s_add_i32 s16, s16, 2
	s_add_u32 s14, s14, 0x100
	s_addc_u32 s15, s15, 0
	s_cmp_gt_u32 s16, 13
	s_mov_b64 s[0:1], s[4:5]
	s_cbranch_scc0 .LBB0_188
	s_barrier
	s_and_b64 vcc, exec, s[72:73]
	s_cbranch_vccz .LBB0_191
	s_barrier

.LBB0_641:
	v_and_b32_e32 v142, 15, v2
	v_and_b32_e32 v143, 48, v2
	v_lshlrev_b32_e32 v2, 2, v2
	s_lshl_b32 s14, s14, 21
	v_lshl_or_b32 v7, v142, 6, v143
	v_and_b32_e32 v2, 32, v2
	s_and_b32 s14, s14, 0x3800000
	s_lshl_b32 s15, s15, 19
	v_bitop3_b32 v8, v7, s52, v2 bitop3:0xde
	v_bitop3_b32 v145, v7, s53, v2 bitop3:0xde
	s_add_i32 s14, s14, s15
	v_lshlrev_b32_e32 v2, 14, v0
	s_add_u32 s40, s76, s14
	v_and_b32_e32 v2, 0xffff8000, v2
	s_addc_u32 s41, s77, 0
	v_lshl_add_u32 v1, v1, 11, v2
	v_and_b32_e32 v0, 1, v0
	v_lshl_or_b32 v0, v0, 6, v1
	s_add_u32 s14, s3, s14
	v_lshl_add_u32 v0, v3, 1, v0
	v_mov_b32_e32 v1, v129
	s_addc_u32 s15, s28, 0
	v_lshl_add_u64 v[136:137], s[14:15], 0, v[0:1]
	v_lshlrev_b32_e32 v0, 14, v4
	v_and_b32_e32 v0, 0xffff8000, v0
	v_lshl_add_u32 v0, v5, 11, v0
	v_and_b32_e32 v1, 1, v4
	v_lshl_or_b32 v0, v1, 6, v0
	s_waitcnt vmcnt(8)
	s_barrier
	s_waitcnt vmcnt(6)
	v_lshl_add_u32 v0, v6, 1, v0
	v_mov_b32_e32 v1, v129
	v_lshl_add_u64 v[138:139], s[14:15], 0, v[0:1]
	s_add_u32 s42, s29, s16
	s_addc_u32 s43, s33, 0
	s_mov_b32 s46, -2
	s_mov_b64 s[14:15], 0
	v_add_u32_e32 v146, 0, v8
	s_barrier
	s_add_u32 s16, s40, s14
	s_addc_u32 s17, s41, s15
	s_add_u32 s16, s16, 0x13d00100
	s_addc_u32 s17, s17, 0
	s_add_u32 s47, s42, s14
	s_addc_u32 s48, s43, s15
	s_cmpk_eq_i32 s14, 0x700
	s_cselect_b32 s19, s11, s17
	s_cselect_b32 s18, s10, s16
	v_add_u32_e32 v147, s67, v145
	s_cselect_b32 s17, s13, s48
	s_cselect_b32 s16, s12, s47
	s_add_i32 s47, 0, 0x14000
	ds_read_b128 v[148:151], v147
	ds_read_b128 v[152:155], v147 offset:1024
	ds_read_b128 v[156:159], v147 offset:2048
	ds_read_b128 v[160:163], v147 offset:3072
	v_add_u32_e32 v147, s47, v145
	ds_read_b128 v[164:167], v147
	ds_read_b128 v[168:171], v147 offset:1024
	ds_read_b128 v[172:175], v147 offset:2048
	ds_read_b128 v[176:179], v147 offset:3072
	v_lshl_add_u64 v[212:213], v[136:137], 0, s[14:15]
	s_add_i32 m0, s30, 0xc000
	ds_read_b128 v[180:183], v146
	ds_read_b128 v[184:187], v146 offset:1024
	ds_read_b128 v[188:191], v146 offset:2048
	ds_read_b128 v[192:195], v146 offset:3072
	ds_read_b128 v[196:199], v146 offset:4096
	ds_read_b128 v[200:203], v146 offset:5120
	ds_read_b128 v[204:207], v146 offset:6144
	ds_read_b128 v[208:211], v146 offset:7168
	global_load_lds_dwordx4 v[212:213], off
	v_lshl_add_u64 v[212:213], v[138:139], 0, s[14:15]
	s_add_i32 m0, s30, 0xe000
	s_nop 0
	global_load_lds_dwordx4 v[212:213], off
	s_waitcnt vmcnt(8)
	s_waitcnt lgkmcnt(0)
	s_barrier
	s_waitcnt lgkmcnt(0)
	v_mfma_f32_16x16x32_f16 v[124:127], v[148:151], v[180:183], 0
	v_mfma_f32_16x16x32_f16 v[120:123], v[156:159], v[180:183], 0
	v_mfma_f32_16x16x32_f16 v[108:111], v[148:151], v[188:191], 0
	v_mfma_f32_16x16x32_f16 v[104:107], v[156:159], v[188:191], 0
	v_mfma_f32_16x16x32_f16 v[92:95], v[148:151], v[196:199], 0
	v_mfma_f32_16x16x32_f16 v[88:91], v[156:159], v[196:199], 0
	v_mfma_f32_16x16x32_f16 v[76:79], v[148:151], v[204:207], 0
	v_mfma_f32_16x16x32_f16 v[72:75], v[156:159], v[204:207], 0
	v_mfma_f32_16x16x32_f16 v[124:127], v[152:155], v[184:187], v[124:127]
	v_mfma_f32_16x16x32_f16 v[120:123], v[160:163], v[184:187], v[120:123]
	v_mfma_f32_16x16x32_f16 v[108:111], v[152:155], v[192:195], v[108:111]
	v_mfma_f32_16x16x32_f16 v[104:107], v[160:163], v[192:195], v[104:107]
	v_mfma_f32_16x16x32_f16 v[92:95], v[152:155], v[200:203], v[92:95]
	v_mfma_f32_16x16x32_f16 v[88:91], v[160:163], v[200:203], v[88:91]
	v_mfma_f32_16x16x32_f16 v[76:79], v[152:155], v[208:211], v[76:79]
	v_mfma_f32_16x16x32_f16 v[72:75], v[160:163], v[208:211], v[72:75]
	v_mfma_f32_16x16x32_f16 v[116:119], v[164:167], v[180:183], 0
	v_mfma_f32_16x16x32_f16 v[112:115], v[172:175], v[180:183], 0
	v_mfma_f32_16x16x32_f16 v[100:103], v[164:167], v[188:191], 0
	v_mfma_f32_16x16x32_f16 v[96:99], v[172:175], v[188:191], 0
	v_mfma_f32_16x16x32_f16 v[84:87], v[164:167], v[196:199], 0
	v_mfma_f32_16x16x32_f16 v[80:83], v[172:175], v[196:199], 0
	v_mfma_f32_16x16x32_f16 v[68:71], v[164:167], v[204:207], 0
	v_mfma_f32_16x16x32_f16 v[64:67], v[172:175], v[204:207], 0
	v_mfma_f32_16x16x32_f16 v[116:119], v[168:171], v[184:187], v[116:119]
	v_mfma_f32_16x16x32_f16 v[112:115], v[176:179], v[184:187], v[112:115]
	v_mfma_f32_16x16x32_f16 v[100:103], v[168:171], v[192:195], v[100:103]
	v_mfma_f32_16x16x32_f16 v[96:99], v[176:179], v[192:195], v[96:99]
	v_mfma_f32_16x16x32_f16 v[84:87], v[168:171], v[200:203], v[84:87]
	v_mfma_f32_16x16x32_f16 v[80:83], v[176:179], v[200:203], v[80:83]
	v_mfma_f32_16x16x32_f16 v[68:71], v[168:171], v[208:211], v[68:71]
	v_mfma_f32_16x16x32_f16 v[64:67], v[176:179], v[208:211], v[64:67]
	s_barrier
	s_add_i32 s48, s67, s66
	v_lshl_add_u64 v[212:213], s[16:17], 0, v[128:129]
	s_mov_b32 m0, s48
	ds_read_b128 v[180:183], v146 offset:16384
	ds_read_b128 v[184:187], v146 offset:17408
	ds_read_b128 v[188:191], v146 offset:18432
	ds_read_b128 v[192:195], v146 offset:19456
	ds_read_b128 v[196:199], v146 offset:20480
	ds_read_b128 v[200:203], v146 offset:21504
	ds_read_b128 v[204:207], v146 offset:22528
	ds_read_b128 v[208:211], v146 offset:23552
	global_load_lds_dwordx4 v[212:213], off
	s_add_i32 m0, s48, 0x2000
	s_add_u32 s48, s16, 0x40000
	v_lshl_add_u64 v[214:215], s[16:17], 0, v[134:135]
	s_addc_u32 s49, s17, 0
	s_add_i32 s47, s47, s66
	global_load_lds_dwordx4 v[214:215], off
	v_lshl_add_u64 v[216:217], s[48:49], 0, v[128:129]
	s_mov_b32 m0, s47
	v_lshl_add_u64 v[218:219], s[18:19], 0, v[132:133]
	global_load_lds_dwordx4 v[216:217], off
	v_lshl_add_u64 v[216:217], s[48:49], 0, v[134:135]
	s_add_i32 m0, s47, 0x2000
	s_nop 0
	global_load_lds_dwordx4 v[216:217], off
	v_lshl_add_u64 v[216:217], s[18:19], 0, v[130:131]
	s_mov_b32 m0, s30
	s_nop 0
	global_load_lds_dwordx4 v[216:217], off
	s_mov_b32 m0, s31
	s_nop 0
	global_load_lds_dwordx4 v[218:219], off
	s_waitcnt vmcnt(8)
	s_waitcnt lgkmcnt(0)
	s_barrier
	s_waitcnt lgkmcnt(0)
	v_mfma_f32_16x16x32_f16 v[60:63], v[148:151], v[180:183], 0
	v_mfma_f32_16x16x32_f16 v[56:59], v[156:159], v[180:183], 0
	v_mfma_f32_16x16x32_f16 v[44:47], v[148:151], v[188:191], 0
	v_mfma_f32_16x16x32_f16 v[40:43], v[156:159], v[188:191], 0
	v_mfma_f32_16x16x32_f16 v[28:31], v[148:151], v[196:199], 0
	v_mfma_f32_16x16x32_f16 v[24:27], v[156:159], v[196:199], 0
	v_mfma_f32_16x16x32_f16 v[12:15], v[148:151], v[204:207], 0
	v_mfma_f32_16x16x32_f16 v[8:11], v[156:159], v[204:207], 0
	v_mfma_f32_16x16x32_f16 v[60:63], v[152:155], v[184:187], v[60:63]
	v_mfma_f32_16x16x32_f16 v[56:59], v[160:163], v[184:187], v[56:59]
	v_mfma_f32_16x16x32_f16 v[44:47], v[152:155], v[192:195], v[44:47]
	v_mfma_f32_16x16x32_f16 v[40:43], v[160:163], v[192:195], v[40:43]
	v_mfma_f32_16x16x32_f16 v[28:31], v[152:155], v[200:203], v[28:31]
	v_mfma_f32_16x16x32_f16 v[24:27], v[160:163], v[200:203], v[24:27]
	v_mfma_f32_16x16x32_f16 v[12:15], v[152:155], v[208:211], v[12:15]
	v_mfma_f32_16x16x32_f16 v[8:11], v[160:163], v[208:211], v[8:11]
	v_mfma_f32_16x16x32_f16 v[52:55], v[164:167], v[180:183], 0
	v_mfma_f32_16x16x32_f16 v[48:51], v[172:175], v[180:183], 0
	v_mfma_f32_16x16x32_f16 v[36:39], v[164:167], v[188:191], 0
	v_mfma_f32_16x16x32_f16 v[32:35], v[172:175], v[188:191], 0
	v_mfma_f32_16x16x32_f16 v[20:23], v[164:167], v[196:199], 0
	v_mfma_f32_16x16x32_f16 v[16:19], v[172:175], v[196:199], 0
	v_mfma_f32_16x16x32_f16 v[4:7], v[164:167], v[204:207], 0
	v_mfma_f32_16x16x32_f16 v[0:3], v[172:175], v[204:207], 0
	v_mfma_f32_16x16x32_f16 v[52:55], v[168:171], v[184:187], v[52:55]
	v_mfma_f32_16x16x32_f16 v[48:51], v[176:179], v[184:187], v[48:51]
	v_mfma_f32_16x16x32_f16 v[36:39], v[168:171], v[192:195], v[36:39]
	v_mfma_f32_16x16x32_f16 v[32:35], v[176:179], v[192:195], v[32:35]
	v_mfma_f32_16x16x32_f16 v[20:23], v[168:171], v[200:203], v[20:23]
	v_mfma_f32_16x16x32_f16 v[16:19], v[176:179], v[200:203], v[16:19]
	v_mfma_f32_16x16x32_f16 v[4:7], v[168:171], v[208:211], v[4:7]
	v_mfma_f32_16x16x32_f16 v[0:3], v[176:179], v[208:211], v[0:3]
	s_barrier
	s_add_i32 s47, 0, 0x18000
	v_add_u32_e32 v147, s47, v145
	s_add_i32 s48, 0, 0x1c000
	ds_read_b128 v[148:151], v147
	ds_read_b128 v[152:155], v147 offset:1024
	ds_read_b128 v[156:159], v147 offset:2048
	ds_read_b128 v[160:163], v147 offset:3072
	v_add_u32_e32 v147, s48, v145
	ds_read_b128 v[164:167], v147
	ds_read_b128 v[168:171], v147 offset:1024
	ds_read_b128 v[172:175], v147 offset:2048
	ds_read_b128 v[176:179], v147 offset:3072
	s_add_u32 s18, s18, 0x40000
	s_addc_u32 s19, s19, 0
	s_mov_b32 m0, s34
	v_lshl_add_u64 v[220:221], s[18:19], 0, v[130:131]
	ds_read_b128 v[180:183], v146 offset:32768
	ds_read_b128 v[184:187], v146 offset:33792
	ds_read_b128 v[188:191], v146 offset:34816
	ds_read_b128 v[192:195], v146 offset:35840
	ds_read_b128 v[196:199], v146 offset:36864
	ds_read_b128 v[200:203], v146 offset:37888
	ds_read_b128 v[204:207], v146 offset:38912
	ds_read_b128 v[208:211], v146 offset:39936
	global_load_lds_dwordx4 v[220:221], off
	v_lshl_add_u64 v[220:221], s[18:19], 0, v[132:133]
	s_mov_b32 m0, s35
	s_nop 0
	global_load_lds_dwordx4 v[220:221], off
	s_waitcnt vmcnt(8)
	s_waitcnt lgkmcnt(0)
	s_barrier
	s_waitcnt lgkmcnt(0)
	v_mfma_f32_16x16x32_f16 v[124:127], v[148:151], v[180:183], v[124:127]
	v_mfma_f32_16x16x32_f16 v[120:123], v[156:159], v[180:183], v[120:123]
	v_mfma_f32_16x16x32_f16 v[108:111], v[148:151], v[188:191], v[108:111]
	v_mfma_f32_16x16x32_f16 v[104:107], v[156:159], v[188:191], v[104:107]
	v_mfma_f32_16x16x32_f16 v[92:95], v[148:151], v[196:199], v[92:95]
	v_mfma_f32_16x16x32_f16 v[88:91], v[156:159], v[196:199], v[88:91]
	v_mfma_f32_16x16x32_f16 v[76:79], v[148:151], v[204:207], v[76:79]
	v_mfma_f32_16x16x32_f16 v[72:75], v[156:159], v[204:207], v[72:75]
	v_mfma_f32_16x16x32_f16 v[124:127], v[152:155], v[184:187], v[124:127]
	v_mfma_f32_16x16x32_f16 v[120:123], v[160:163], v[184:187], v[120:123]
	v_mfma_f32_16x16x32_f16 v[108:111], v[152:155], v[192:195], v[108:111]
	v_mfma_f32_16x16x32_f16 v[104:107], v[160:163], v[192:195], v[104:107]
	v_mfma_f32_16x16x32_f16 v[92:95], v[152:155], v[200:203], v[92:95]
	v_mfma_f32_16x16x32_f16 v[88:91], v[160:163], v[200:203], v[88:91]
	v_mfma_f32_16x16x32_f16 v[76:79], v[152:155], v[208:211], v[76:79]
	v_mfma_f32_16x16x32_f16 v[72:75], v[160:163], v[208:211], v[72:75]
	v_mfma_f32_16x16x32_f16 v[116:119], v[164:167], v[180:183], v[116:119]
	v_mfma_f32_16x16x32_f16 v[112:115], v[172:175], v[180:183], v[112:115]
	v_mfma_f32_16x16x32_f16 v[100:103], v[164:167], v[188:191], v[100:103]
	v_mfma_f32_16x16x32_f16 v[96:99], v[172:175], v[188:191], v[96:99]
	v_mfma_f32_16x16x32_f16 v[84:87], v[164:167], v[196:199], v[84:87]
	v_mfma_f32_16x16x32_f16 v[80:83], v[172:175], v[196:199], v[80:83]
	v_mfma_f32_16x16x32_f16 v[68:71], v[164:167], v[204:207], v[68:71]
	v_mfma_f32_16x16x32_f16 v[64:67], v[172:175], v[204:207], v[64:67]
	v_mfma_f32_16x16x32_f16 v[116:119], v[168:171], v[184:187], v[116:119]
	v_mfma_f32_16x16x32_f16 v[112:115], v[176:179], v[184:187], v[112:115]
	v_mfma_f32_16x16x32_f16 v[100:103], v[168:171], v[192:195], v[100:103]
	v_mfma_f32_16x16x32_f16 v[96:99], v[176:179], v[192:195], v[96:99]
	v_mfma_f32_16x16x32_f16 v[84:87], v[168:171], v[200:203], v[84:87]
	v_mfma_f32_16x16x32_f16 v[80:83], v[176:179], v[200:203], v[80:83]
	v_mfma_f32_16x16x32_f16 v[68:71], v[168:171], v[208:211], v[68:71]
	v_mfma_f32_16x16x32_f16 v[64:67], v[176:179], v[208:211], v[64:67]
	s_barrier
	s_add_i32 s18, s47, s66
	v_lshl_add_u64 v[212:213], v[212:213], 0, s[6:7]
	s_mov_b32 m0, s18
	ds_read_b128 v[180:183], v146 offset:49152
	ds_read_b128 v[184:187], v146 offset:50176
	ds_read_b128 v[188:191], v146 offset:51200
	ds_read_b128 v[192:195], v146 offset:52224
	ds_read_b128 v[196:199], v146 offset:53248
	ds_read_b128 v[200:203], v146 offset:54272
	ds_read_b128 v[204:207], v146 offset:55296
	ds_read_b128 v[208:211], v146 offset:56320
	global_load_lds_dwordx4 v[212:213], off
	s_add_i32 m0, s18, 0x2000
	s_add_u32 s16, s16, 0x40080
	v_lshl_add_u64 v[212:213], v[214:215], 0, s[6:7]
	s_addc_u32 s17, s17, 0
	s_add_i32 s18, s48, s66
	global_load_lds_dwordx4 v[212:213], off
	v_lshl_add_u64 v[212:213], s[16:17], 0, v[128:129]
	s_mov_b32 m0, s18
	s_nop 0
	global_load_lds_dwordx4 v[212:213], off
	v_lshl_add_u64 v[212:213], s[16:17], 0, v[134:135]
	s_add_i32 m0, s18, 0x2000
	s_nop 0
	global_load_lds_dwordx4 v[212:213], off
	v_lshl_add_u64 v[212:213], v[216:217], 0, s[6:7]
	s_mov_b32 m0, s38
	s_nop 0
	global_load_lds_dwordx4 v[212:213], off
	v_lshl_add_u64 v[212:213], v[218:219], 0, s[6:7]
	s_mov_b32 m0, s39
	s_nop 0
	global_load_lds_dwordx4 v[212:213], off
	s_waitcnt vmcnt(8)
	s_waitcnt lgkmcnt(0)
	s_barrier
	s_waitcnt lgkmcnt(0)
	v_mfma_f32_16x16x32_f16 v[60:63], v[148:151], v[180:183], v[60:63]
	v_mfma_f32_16x16x32_f16 v[56:59], v[156:159], v[180:183], v[56:59]
	v_mfma_f32_16x16x32_f16 v[44:47], v[148:151], v[188:191], v[44:47]
	v_mfma_f32_16x16x32_f16 v[40:43], v[156:159], v[188:191], v[40:43]
	v_mfma_f32_16x16x32_f16 v[28:31], v[148:151], v[196:199], v[28:31]
	v_mfma_f32_16x16x32_f16 v[24:27], v[156:159], v[196:199], v[24:27]
	v_mfma_f32_16x16x32_f16 v[12:15], v[148:151], v[204:207], v[12:15]
	v_mfma_f32_16x16x32_f16 v[8:11], v[156:159], v[204:207], v[8:11]
	v_mfma_f32_16x16x32_f16 v[60:63], v[152:155], v[184:187], v[60:63]
	v_mfma_f32_16x16x32_f16 v[56:59], v[160:163], v[184:187], v[56:59]
	v_mfma_f32_16x16x32_f16 v[44:47], v[152:155], v[192:195], v[44:47]
	v_mfma_f32_16x16x32_f16 v[40:43], v[160:163], v[192:195], v[40:43]
	v_mfma_f32_16x16x32_f16 v[28:31], v[152:155], v[200:203], v[28:31]
	v_mfma_f32_16x16x32_f16 v[24:27], v[160:163], v[200:203], v[24:27]
	v_mfma_f32_16x16x32_f16 v[12:15], v[152:155], v[208:211], v[12:15]
	v_mfma_f32_16x16x32_f16 v[8:11], v[160:163], v[208:211], v[8:11]
	v_mfma_f32_16x16x32_f16 v[52:55], v[164:167], v[180:183], v[52:55]
	v_mfma_f32_16x16x32_f16 v[48:51], v[172:175], v[180:183], v[48:51]
	v_mfma_f32_16x16x32_f16 v[36:39], v[164:167], v[188:191], v[36:39]
	v_mfma_f32_16x16x32_f16 v[32:35], v[172:175], v[188:191], v[32:35]
	v_mfma_f32_16x16x32_f16 v[20:23], v[164:167], v[196:199], v[20:23]
	v_mfma_f32_16x16x32_f16 v[16:19], v[172:175], v[196:199], v[16:19]
	v_mfma_f32_16x16x32_f16 v[4:7], v[164:167], v[204:207], v[4:7]
	v_mfma_f32_16x16x32_f16 v[0:3], v[172:175], v[204:207], v[0:3]
	v_mfma_f32_16x16x32_f16 v[52:55], v[168:171], v[184:187], v[52:55]
	v_mfma_f32_16x16x32_f16 v[48:51], v[176:179], v[184:187], v[48:51]
	v_mfma_f32_16x16x32_f16 v[36:39], v[168:171], v[192:195], v[36:39]
	v_mfma_f32_16x16x32_f16 v[32:35], v[176:179], v[192:195], v[32:35]
	v_mfma_f32_16x16x32_f16 v[20:23], v[168:171], v[200:203], v[20:23]
	v_mfma_f32_16x16x32_f16 v[16:19], v[176:179], v[200:203], v[16:19]
	v_mfma_f32_16x16x32_f16 v[4:7], v[168:171], v[208:211], v[4:7]
	v_mfma_f32_16x16x32_f16 v[0:3], v[176:179], v[208:211], v[0:3]
	s_add_i32 s46, s46, 2
	s_add_u32 s14, s14, 0x100
	s_addc_u32 s15, s15, 0
	s_cmp_gt_u32 s46, 13
.LBB0_642:
	s_barrier
	s_add_u32 s16, s40, s14
	s_addc_u32 s17, s41, s15
	s_add_u32 s16, s16, 0x13d00100
	s_addc_u32 s17, s17, 0
	s_add_u32 s47, s42, s14
	s_addc_u32 s48, s43, s15
	s_cmpk_eq_i32 s14, 0x700
	s_cselect_b32 s19, s11, s17
	s_cselect_b32 s18, s10, s16
	v_add_u32_e32 v147, s67, v145
	s_cselect_b32 s17, s13, s48
	s_cselect_b32 s16, s12, s47
	s_add_i32 s47, 0, 0x14000
	ds_read_b128 v[148:151], v147
	ds_read_b128 v[152:155], v147 offset:1024
	ds_read_b128 v[156:159], v147 offset:2048
	ds_read_b128 v[160:163], v147 offset:3072
	v_add_u32_e32 v147, s47, v145
	ds_read_b128 v[164:167], v147
	ds_read_b128 v[168:171], v147 offset:1024
	ds_read_b128 v[172:175], v147 offset:2048
	ds_read_b128 v[176:179], v147 offset:3072
	v_lshl_add_u64 v[212:213], v[136:137], 0, s[14:15]
	s_add_i32 m0, s30, 0xc000
	ds_read_b128 v[180:183], v146
	ds_read_b128 v[184:187], v146 offset:1024
	ds_read_b128 v[188:191], v146 offset:2048
	ds_read_b128 v[192:195], v146 offset:3072
	ds_read_b128 v[196:199], v146 offset:4096
	ds_read_b128 v[200:203], v146 offset:5120
	ds_read_b128 v[204:207], v146 offset:6144
	ds_read_b128 v[208:211], v146 offset:7168
	global_load_lds_dwordx4 v[212:213], off
	v_lshl_add_u64 v[212:213], v[138:139], 0, s[14:15]
	s_add_i32 m0, s30, 0xe000
	s_nop 0
	global_load_lds_dwordx4 v[212:213], off
	s_waitcnt vmcnt(8)
	s_waitcnt lgkmcnt(0)
	s_barrier
	s_waitcnt lgkmcnt(0)
	v_mfma_f32_16x16x32_f16 v[124:127], v[148:151], v[180:183], v[124:127]
	v_mfma_f32_16x16x32_f16 v[120:123], v[156:159], v[180:183], v[120:123]
	v_mfma_f32_16x16x32_f16 v[108:111], v[148:151], v[188:191], v[108:111]
	v_mfma_f32_16x16x32_f16 v[104:107], v[156:159], v[188:191], v[104:107]
	v_mfma_f32_16x16x32_f16 v[92:95], v[148:151], v[196:199], v[92:95]
	v_mfma_f32_16x16x32_f16 v[88:91], v[156:159], v[196:199], v[88:91]
	v_mfma_f32_16x16x32_f16 v[76:79], v[148:151], v[204:207], v[76:79]
	v_mfma_f32_16x16x32_f16 v[72:75], v[156:159], v[204:207], v[72:75]
	v_mfma_f32_16x16x32_f16 v[124:127], v[152:155], v[184:187], v[124:127]
	v_mfma_f32_16x16x32_f16 v[120:123], v[160:163], v[184:187], v[120:123]
	v_mfma_f32_16x16x32_f16 v[108:111], v[152:155], v[192:195], v[108:111]
	v_mfma_f32_16x16x32_f16 v[104:107], v[160:163], v[192:195], v[104:107]
	v_mfma_f32_16x16x32_f16 v[92:95], v[152:155], v[200:203], v[92:95]
	v_mfma_f32_16x16x32_f16 v[88:91], v[160:163], v[200:203], v[88:91]
	v_mfma_f32_16x16x32_f16 v[76:79], v[152:155], v[208:211], v[76:79]
	v_mfma_f32_16x16x32_f16 v[72:75], v[160:163], v[208:211], v[72:75]
	v_mfma_f32_16x16x32_f16 v[116:119], v[164:167], v[180:183], v[116:119]
	v_mfma_f32_16x16x32_f16 v[112:115], v[172:175], v[180:183], v[112:115]
	v_mfma_f32_16x16x32_f16 v[100:103], v[164:167], v[188:191], v[100:103]
	v_mfma_f32_16x16x32_f16 v[96:99], v[172:175], v[188:191], v[96:99]
	v_mfma_f32_16x16x32_f16 v[84:87], v[164:167], v[196:199], v[84:87]
	v_mfma_f32_16x16x32_f16 v[80:83], v[172:175], v[196:199], v[80:83]
	v_mfma_f32_16x16x32_f16 v[68:71], v[164:167], v[204:207], v[68:71]
	v_mfma_f32_16x16x32_f16 v[64:67], v[172:175], v[204:207], v[64:67]
	v_mfma_f32_16x16x32_f16 v[116:119], v[168:171], v[184:187], v[116:119]
	v_mfma_f32_16x16x32_f16 v[112:115], v[176:179], v[184:187], v[112:115]
	v_mfma_f32_16x16x32_f16 v[100:103], v[168:171], v[192:195], v[100:103]
	v_mfma_f32_16x16x32_f16 v[96:99], v[176:179], v[192:195], v[96:99]
	v_mfma_f32_16x16x32_f16 v[84:87], v[168:171], v[200:203], v[84:87]
	v_mfma_f32_16x16x32_f16 v[80:83], v[176:179], v[200:203], v[80:83]
	v_mfma_f32_16x16x32_f16 v[68:71], v[168:171], v[208:211], v[68:71]
	v_mfma_f32_16x16x32_f16 v[64:67], v[176:179], v[208:211], v[64:67]
	s_barrier
	s_add_i32 s48, s67, s66
	v_lshl_add_u64 v[212:213], s[16:17], 0, v[128:129]
	s_mov_b32 m0, s48
	ds_read_b128 v[180:183], v146 offset:16384
	ds_read_b128 v[184:187], v146 offset:17408
	ds_read_b128 v[188:191], v146 offset:18432
	ds_read_b128 v[192:195], v146 offset:19456
	ds_read_b128 v[196:199], v146 offset:20480
	ds_read_b128 v[200:203], v146 offset:21504
	ds_read_b128 v[204:207], v146 offset:22528
	ds_read_b128 v[208:211], v146 offset:23552
	global_load_lds_dwordx4 v[212:213], off
	s_add_i32 m0, s48, 0x2000
	s_add_u32 s48, s16, 0x40000
	v_lshl_add_u64 v[214:215], s[16:17], 0, v[134:135]
	s_addc_u32 s49, s17, 0
	s_add_i32 s47, s47, s66
	global_load_lds_dwordx4 v[214:215], off
	v_lshl_add_u64 v[216:217], s[48:49], 0, v[128:129]
	s_mov_b32 m0, s47
	v_lshl_add_u64 v[218:219], s[18:19], 0, v[132:133]
	global_load_lds_dwordx4 v[216:217], off
	v_lshl_add_u64 v[216:217], s[48:49], 0, v[134:135]
	s_add_i32 m0, s47, 0x2000
	s_nop 0
	global_load_lds_dwordx4 v[216:217], off
	v_lshl_add_u64 v[216:217], s[18:19], 0, v[130:131]
	s_mov_b32 m0, s30
	s_nop 0
	global_load_lds_dwordx4 v[216:217], off
	s_mov_b32 m0, s31
	s_nop 0
	global_load_lds_dwordx4 v[218:219], off
	s_waitcnt vmcnt(8)
	s_waitcnt lgkmcnt(0)
	s_barrier
	s_waitcnt lgkmcnt(0)
	v_mfma_f32_16x16x32_f16 v[60:63], v[148:151], v[180:183], v[60:63]
	v_mfma_f32_16x16x32_f16 v[56:59], v[156:159], v[180:183], v[56:59]
	v_mfma_f32_16x16x32_f16 v[44:47], v[148:151], v[188:191], v[44:47]
	v_mfma_f32_16x16x32_f16 v[40:43], v[156:159], v[188:191], v[40:43]
	v_mfma_f32_16x16x32_f16 v[28:31], v[148:151], v[196:199], v[28:31]
	v_mfma_f32_16x16x32_f16 v[24:27], v[156:159], v[196:199], v[24:27]
	v_mfma_f32_16x16x32_f16 v[12:15], v[148:151], v[204:207], v[12:15]
	v_mfma_f32_16x16x32_f16 v[8:11], v[156:159], v[204:207], v[8:11]
	v_mfma_f32_16x16x32_f16 v[60:63], v[152:155], v[184:187], v[60:63]
	v_mfma_f32_16x16x32_f16 v[56:59], v[160:163], v[184:187], v[56:59]
	v_mfma_f32_16x16x32_f16 v[44:47], v[152:155], v[192:195], v[44:47]
	v_mfma_f32_16x16x32_f16 v[40:43], v[160:163], v[192:195], v[40:43]
	v_mfma_f32_16x16x32_f16 v[28:31], v[152:155], v[200:203], v[28:31]
	v_mfma_f32_16x16x32_f16 v[24:27], v[160:163], v[200:203], v[24:27]
	v_mfma_f32_16x16x32_f16 v[12:15], v[152:155], v[208:211], v[12:15]
	v_mfma_f32_16x16x32_f16 v[8:11], v[160:163], v[208:211], v[8:11]
	v_mfma_f32_16x16x32_f16 v[52:55], v[164:167], v[180:183], v[52:55]
	v_mfma_f32_16x16x32_f16 v[48:51], v[172:175], v[180:183], v[48:51]
	v_mfma_f32_16x16x32_f16 v[36:39], v[164:167], v[188:191], v[36:39]
	v_mfma_f32_16x16x32_f16 v[32:35], v[172:175], v[188:191], v[32:35]
	v_mfma_f32_16x16x32_f16 v[20:23], v[164:167], v[196:199], v[20:23]
	v_mfma_f32_16x16x32_f16 v[16:19], v[172:175], v[196:199], v[16:19]
	v_mfma_f32_16x16x32_f16 v[4:7], v[164:167], v[204:207], v[4:7]
	v_mfma_f32_16x16x32_f16 v[0:3], v[172:175], v[204:207], v[0:3]
	v_mfma_f32_16x16x32_f16 v[52:55], v[168:171], v[184:187], v[52:55]
	v_mfma_f32_16x16x32_f16 v[48:51], v[176:179], v[184:187], v[48:51]
	v_mfma_f32_16x16x32_f16 v[36:39], v[168:171], v[192:195], v[36:39]
	v_mfma_f32_16x16x32_f16 v[32:35], v[176:179], v[192:195], v[32:35]
	v_mfma_f32_16x16x32_f16 v[20:23], v[168:171], v[200:203], v[20:23]
	v_mfma_f32_16x16x32_f16 v[16:19], v[176:179], v[200:203], v[16:19]
	v_mfma_f32_16x16x32_f16 v[4:7], v[168:171], v[208:211], v[4:7]
	v_mfma_f32_16x16x32_f16 v[0:3], v[176:179], v[208:211], v[0:3]
	s_barrier
	s_add_i32 s47, 0, 0x18000
	v_add_u32_e32 v147, s47, v145
	s_add_i32 s48, 0, 0x1c000
	ds_read_b128 v[148:151], v147
	ds_read_b128 v[152:155], v147 offset:1024
	ds_read_b128 v[156:159], v147 offset:2048
	ds_read_b128 v[160:163], v147 offset:3072
	v_add_u32_e32 v147, s48, v145
	ds_read_b128 v[164:167], v147
	ds_read_b128 v[168:171], v147 offset:1024
	ds_read_b128 v[172:175], v147 offset:2048
	ds_read_b128 v[176:179], v147 offset:3072
	s_add_u32 s18, s18, 0x40000
	s_addc_u32 s19, s19, 0
	s_mov_b32 m0, s34
	v_lshl_add_u64 v[220:221], s[18:19], 0, v[130:131]
	ds_read_b128 v[180:183], v146 offset:32768
	ds_read_b128 v[184:187], v146 offset:33792
	ds_read_b128 v[188:191], v146 offset:34816
	ds_read_b128 v[192:195], v146 offset:35840
	ds_read_b128 v[196:199], v146 offset:36864
	ds_read_b128 v[200:203], v146 offset:37888
	ds_read_b128 v[204:207], v146 offset:38912
	ds_read_b128 v[208:211], v146 offset:39936
	global_load_lds_dwordx4 v[220:221], off
	v_lshl_add_u64 v[220:221], s[18:19], 0, v[132:133]
	s_mov_b32 m0, s35
	s_nop 0
	global_load_lds_dwordx4 v[220:221], off
	s_waitcnt vmcnt(8)
	s_waitcnt lgkmcnt(0)
	s_barrier
	s_waitcnt lgkmcnt(0)
	v_mfma_f32_16x16x32_f16 v[124:127], v[148:151], v[180:183], v[124:127]
	v_mfma_f32_16x16x32_f16 v[120:123], v[156:159], v[180:183], v[120:123]
	v_mfma_f32_16x16x32_f16 v[108:111], v[148:151], v[188:191], v[108:111]
	v_mfma_f32_16x16x32_f16 v[104:107], v[156:159], v[188:191], v[104:107]
	v_mfma_f32_16x16x32_f16 v[92:95], v[148:151], v[196:199], v[92:95]
	v_mfma_f32_16x16x32_f16 v[88:91], v[156:159], v[196:199], v[88:91]
	v_mfma_f32_16x16x32_f16 v[76:79], v[148:151], v[204:207], v[76:79]
	v_mfma_f32_16x16x32_f16 v[72:75], v[156:159], v[204:207], v[72:75]
	v_mfma_f32_16x16x32_f16 v[124:127], v[152:155], v[184:187], v[124:127]
	v_mfma_f32_16x16x32_f16 v[120:123], v[160:163], v[184:187], v[120:123]
	v_mfma_f32_16x16x32_f16 v[108:111], v[152:155], v[192:195], v[108:111]
	v_mfma_f32_16x16x32_f16 v[104:107], v[160:163], v[192:195], v[104:107]
	v_mfma_f32_16x16x32_f16 v[92:95], v[152:155], v[200:203], v[92:95]
	v_mfma_f32_16x16x32_f16 v[88:91], v[160:163], v[200:203], v[88:91]
	v_mfma_f32_16x16x32_f16 v[76:79], v[152:155], v[208:211], v[76:79]
	v_mfma_f32_16x16x32_f16 v[72:75], v[160:163], v[208:211], v[72:75]
	v_mfma_f32_16x16x32_f16 v[116:119], v[164:167], v[180:183], v[116:119]
	v_mfma_f32_16x16x32_f16 v[112:115], v[172:175], v[180:183], v[112:115]
	v_mfma_f32_16x16x32_f16 v[100:103], v[164:167], v[188:191], v[100:103]
	v_mfma_f32_16x16x32_f16 v[96:99], v[172:175], v[188:191], v[96:99]
	v_mfma_f32_16x16x32_f16 v[84:87], v[164:167], v[196:199], v[84:87]
	v_mfma_f32_16x16x32_f16 v[80:83], v[172:175], v[196:199], v[80:83]
	v_mfma_f32_16x16x32_f16 v[68:71], v[164:167], v[204:207], v[68:71]
	v_mfma_f32_16x16x32_f16 v[64:67], v[172:175], v[204:207], v[64:67]
	v_mfma_f32_16x16x32_f16 v[116:119], v[168:171], v[184:187], v[116:119]
	v_mfma_f32_16x16x32_f16 v[112:115], v[176:179], v[184:187], v[112:115]
	v_mfma_f32_16x16x32_f16 v[100:103], v[168:171], v[192:195], v[100:103]
	v_mfma_f32_16x16x32_f16 v[96:99], v[176:179], v[192:195], v[96:99]
	v_mfma_f32_16x16x32_f16 v[84:87], v[168:171], v[200:203], v[84:87]
	v_mfma_f32_16x16x32_f16 v[80:83], v[176:179], v[200:203], v[80:83]
	v_mfma_f32_16x16x32_f16 v[68:71], v[168:171], v[208:211], v[68:71]
	v_mfma_f32_16x16x32_f16 v[64:67], v[176:179], v[208:211], v[64:67]
	s_barrier
	s_add_i32 s18, s47, s66
	v_lshl_add_u64 v[212:213], v[212:213], 0, s[6:7]
	s_mov_b32 m0, s18
	ds_read_b128 v[180:183], v146 offset:49152
	ds_read_b128 v[184:187], v146 offset:50176
	ds_read_b128 v[188:191], v146 offset:51200
	ds_read_b128 v[192:195], v146 offset:52224
	ds_read_b128 v[196:199], v146 offset:53248
	ds_read_b128 v[200:203], v146 offset:54272
	ds_read_b128 v[204:207], v146 offset:55296
	ds_read_b128 v[208:211], v146 offset:56320
	global_load_lds_dwordx4 v[212:213], off
	s_add_i32 m0, s18, 0x2000
	s_add_u32 s16, s16, 0x40080
	v_lshl_add_u64 v[212:213], v[214:215], 0, s[6:7]
	s_addc_u32 s17, s17, 0
	s_add_i32 s18, s48, s66
	global_load_lds_dwordx4 v[212:213], off
	v_lshl_add_u64 v[212:213], s[16:17], 0, v[128:129]
	s_mov_b32 m0, s18
	s_nop 0
	global_load_lds_dwordx4 v[212:213], off
	v_lshl_add_u64 v[212:213], s[16:17], 0, v[134:135]
	s_add_i32 m0, s18, 0x2000
	s_nop 0
	global_load_lds_dwordx4 v[212:213], off
	v_lshl_add_u64 v[212:213], v[216:217], 0, s[6:7]
	s_mov_b32 m0, s38
	s_nop 0
	global_load_lds_dwordx4 v[212:213], off
	v_lshl_add_u64 v[212:213], v[218:219], 0, s[6:7]
	s_mov_b32 m0, s39
	s_nop 0
	global_load_lds_dwordx4 v[212:213], off
	s_waitcnt vmcnt(8)
	s_waitcnt lgkmcnt(0)
	s_barrier
	s_waitcnt lgkmcnt(0)
	v_mfma_f32_16x16x32_f16 v[60:63], v[148:151], v[180:183], v[60:63]
	v_mfma_f32_16x16x32_f16 v[56:59], v[156:159], v[180:183], v[56:59]
	v_mfma_f32_16x16x32_f16 v[44:47], v[148:151], v[188:191], v[44:47]
	v_mfma_f32_16x16x32_f16 v[40:43], v[156:159], v[188:191], v[40:43]
	v_mfma_f32_16x16x32_f16 v[28:31], v[148:151], v[196:199], v[28:31]
	v_mfma_f32_16x16x32_f16 v[24:27], v[156:159], v[196:199], v[24:27]
	v_mfma_f32_16x16x32_f16 v[12:15], v[148:151], v[204:207], v[12:15]
	v_mfma_f32_16x16x32_f16 v[8:11], v[156:159], v[204:207], v[8:11]
	v_mfma_f32_16x16x32_f16 v[60:63], v[152:155], v[184:187], v[60:63]
	v_mfma_f32_16x16x32_f16 v[56:59], v[160:163], v[184:187], v[56:59]
	v_mfma_f32_16x16x32_f16 v[44:47], v[152:155], v[192:195], v[44:47]
	v_mfma_f32_16x16x32_f16 v[40:43], v[160:163], v[192:195], v[40:43]
	v_mfma_f32_16x16x32_f16 v[28:31], v[152:155], v[200:203], v[28:31]
	v_mfma_f32_16x16x32_f16 v[24:27], v[160:163], v[200:203], v[24:27]
	v_mfma_f32_16x16x32_f16 v[12:15], v[152:155], v[208:211], v[12:15]
	v_mfma_f32_16x16x32_f16 v[8:11], v[160:163], v[208:211], v[8:11]
	v_mfma_f32_16x16x32_f16 v[52:55], v[164:167], v[180:183], v[52:55]
	v_mfma_f32_16x16x32_f16 v[48:51], v[172:175], v[180:183], v[48:51]
	v_mfma_f32_16x16x32_f16 v[36:39], v[164:167], v[188:191], v[36:39]
	v_mfma_f32_16x16x32_f16 v[32:35], v[172:175], v[188:191], v[32:35]
	v_mfma_f32_16x16x32_f16 v[20:23], v[164:167], v[196:199], v[20:23]
	v_mfma_f32_16x16x32_f16 v[16:19], v[172:175], v[196:199], v[16:19]
	v_mfma_f32_16x16x32_f16 v[4:7], v[164:167], v[204:207], v[4:7]
	v_mfma_f32_16x16x32_f16 v[0:3], v[172:175], v[204:207], v[0:3]
	v_mfma_f32_16x16x32_f16 v[52:55], v[168:171], v[184:187], v[52:55]
	v_mfma_f32_16x16x32_f16 v[48:51], v[176:179], v[184:187], v[48:51]
	v_mfma_f32_16x16x32_f16 v[36:39], v[168:171], v[192:195], v[36:39]
	v_mfma_f32_16x16x32_f16 v[32:35], v[176:179], v[192:195], v[32:35]
	v_mfma_f32_16x16x32_f16 v[20:23], v[168:171], v[200:203], v[20:23]
	v_mfma_f32_16x16x32_f16 v[16:19], v[176:179], v[200:203], v[16:19]
	v_mfma_f32_16x16x32_f16 v[4:7], v[168:171], v[208:211], v[4:7]
	v_mfma_f32_16x16x32_f16 v[0:3], v[176:179], v[208:211], v[0:3]
	s_add_i32 s46, s46, 2
	s_add_u32 s14, s14, 0x100
	s_addc_u32 s15, s15, 0
	s_cmp_gt_u32 s46, 13
	s_cbranch_scc0 .LBB0_642
	s_barrier
	s_and_b64 vcc, exec, s[26:27]
	s_cbranch_vccz .LBB0_645
	s_barrier

.LBB0_1043:
	s_and_b64 s[44:45], s[40:41], exec
	s_cselect_b32 s5, s19, s35
	s_cselect_b32 s29, s18, s34
	s_cselect_b32 s33, s21, s43
	s_cselect_b32 s82, s20, s42
	s_add_u32 s34, s34, 0x40080
	s_addc_u32 s35, s35, 0
	s_add_u32 s83, s42, 0x100
	s_addc_u32 s84, s43, 0
	s_mov_b32 s85, -2
	v_add_u32_e32 v136, s67, v144
	ds_read_b128 v[156:159], v136
	ds_read_b128 v[160:163], v136 offset:1024
	ds_read_b128 v[164:167], v136 offset:2048
	ds_read_b128 v[168:171], v136 offset:3072
	ds_read_b128 v[172:175], v153
	ds_read_b128 v[176:179], v153 offset:1024
	ds_read_b128 v[180:183], v153 offset:2048
	ds_read_b128 v[184:187], v153 offset:3072
	s_add_u32 s42, s34, 0xfffc0080
	s_addc_u32 s43, s35, -1
	s_cmp_eq_u32 s85, 12
	s_cselect_b32 s45, s5, s43
	s_cselect_b32 s44, s29, s42
	s_cselect_b32 s43, s33, s84
	s_cselect_b32 s42, s82, s83
	v_lshl_add_u64 v[142:143], s[34:35], 0, v[138:139]
	s_add_i32 m0, s3, 0xc000
	ds_read_b128 v[188:191], v154
	ds_read_b128 v[192:195], v154 offset:1024
	ds_read_b128 v[196:199], v154 offset:2048
	ds_read_b128 v[200:203], v154 offset:3072
	ds_read_b128 v[204:207], v154 offset:4096
	ds_read_b128 v[208:211], v154 offset:5120
	ds_read_b128 v[212:215], v154 offset:6144
	ds_read_b128 v[216:219], v154 offset:7168
	global_load_lds_dwordx4 v[142:143], off
	v_lshl_add_u64 v[142:143], s[34:35], 0, v[140:141]
	s_add_i32 m0, s3, 0xe000
	s_nop 0
	global_load_lds_dwordx4 v[142:143], off
	s_waitcnt vmcnt(8)
	s_waitcnt lgkmcnt(0)
	s_barrier
	s_waitcnt lgkmcnt(0)
	v_mfma_f32_16x16x32_f16 v[124:127], v[156:159], v[188:191], 0
	v_mfma_f32_16x16x32_f16 v[120:123], v[164:167], v[188:191], 0
	v_mfma_f32_16x16x32_f16 v[108:111], v[156:159], v[196:199], 0
	v_mfma_f32_16x16x32_f16 v[104:107], v[164:167], v[196:199], 0
	v_mfma_f32_16x16x32_f16 v[92:95], v[156:159], v[204:207], 0
	v_mfma_f32_16x16x32_f16 v[88:91], v[164:167], v[204:207], 0
	v_mfma_f32_16x16x32_f16 v[76:79], v[156:159], v[212:215], 0
	v_mfma_f32_16x16x32_f16 v[72:75], v[164:167], v[212:215], 0
	v_mfma_f32_16x16x32_f16 v[124:127], v[160:163], v[192:195], v[124:127]
	v_mfma_f32_16x16x32_f16 v[120:123], v[168:171], v[192:195], v[120:123]
	v_mfma_f32_16x16x32_f16 v[108:111], v[160:163], v[200:203], v[108:111]
	v_mfma_f32_16x16x32_f16 v[104:107], v[168:171], v[200:203], v[104:107]
	v_mfma_f32_16x16x32_f16 v[92:95], v[160:163], v[208:211], v[92:95]
	v_mfma_f32_16x16x32_f16 v[88:91], v[168:171], v[208:211], v[88:91]
	v_mfma_f32_16x16x32_f16 v[76:79], v[160:163], v[216:219], v[76:79]
	v_mfma_f32_16x16x32_f16 v[72:75], v[168:171], v[216:219], v[72:75]
	v_mfma_f32_16x16x32_f16 v[116:119], v[172:175], v[188:191], 0
	v_mfma_f32_16x16x32_f16 v[112:115], v[180:183], v[188:191], 0
	v_mfma_f32_16x16x32_f16 v[100:103], v[172:175], v[196:199], 0
	v_mfma_f32_16x16x32_f16 v[96:99], v[180:183], v[196:199], 0
	v_mfma_f32_16x16x32_f16 v[84:87], v[172:175], v[204:207], 0
	v_mfma_f32_16x16x32_f16 v[80:83], v[180:183], v[204:207], 0
	v_mfma_f32_16x16x32_f16 v[68:71], v[172:175], v[212:215], 0
	v_mfma_f32_16x16x32_f16 v[64:67], v[180:183], v[212:215], 0
	v_mfma_f32_16x16x32_f16 v[116:119], v[176:179], v[192:195], v[116:119]
	v_mfma_f32_16x16x32_f16 v[112:115], v[184:187], v[192:195], v[112:115]
	v_mfma_f32_16x16x32_f16 v[100:103], v[176:179], v[200:203], v[100:103]
	v_mfma_f32_16x16x32_f16 v[96:99], v[184:187], v[200:203], v[96:99]
	v_mfma_f32_16x16x32_f16 v[84:87], v[176:179], v[208:211], v[84:87]
	v_mfma_f32_16x16x32_f16 v[80:83], v[184:187], v[208:211], v[80:83]
	v_mfma_f32_16x16x32_f16 v[68:71], v[176:179], v[216:219], v[68:71]
	v_mfma_f32_16x16x32_f16 v[64:67], v[184:187], v[216:219], v[64:67]
	s_barrier
	s_add_i32 s86, s67, s66
	v_lshl_add_u64 v[142:143], s[42:43], 0, v[130:131]
	s_mov_b32 m0, s86
	ds_read_b128 v[188:191], v154 offset:16384
	ds_read_b128 v[192:195], v154 offset:17408
	ds_read_b128 v[196:199], v154 offset:18432
	ds_read_b128 v[200:203], v154 offset:19456
	ds_read_b128 v[204:207], v154 offset:20480
	ds_read_b128 v[208:211], v154 offset:21504
	ds_read_b128 v[212:215], v154 offset:22528
	ds_read_b128 v[216:219], v154 offset:23552
	global_load_lds_dwordx4 v[142:143], off
	s_add_i32 m0, s86, 0x2000
	s_add_u32 s86, s42, 0x40000
	v_lshl_add_u64 v[220:221], s[42:43], 0, v[134:135]
	s_addc_u32 s87, s43, 0
	s_add_i32 s88, s70, s66
	global_load_lds_dwordx4 v[220:221], off
	v_lshl_add_u64 v[222:223], s[86:87], 0, v[130:131]
	s_mov_b32 m0, s88
	v_lshl_add_u64 v[224:225], s[44:45], 0, v[132:133]
	global_load_lds_dwordx4 v[222:223], off
	v_lshl_add_u64 v[222:223], s[86:87], 0, v[134:135]
	s_add_i32 m0, s88, 0x2000
	s_nop 0
	global_load_lds_dwordx4 v[222:223], off
	v_lshl_add_u64 v[222:223], s[44:45], 0, v[128:129]
	s_mov_b32 m0, s3
	s_nop 0
	global_load_lds_dwordx4 v[222:223], off
	s_mov_b32 m0, s31
	s_nop 0
	global_load_lds_dwordx4 v[224:225], off
	s_waitcnt vmcnt(8)
	s_waitcnt lgkmcnt(0)
	s_barrier
	s_waitcnt lgkmcnt(0)
	v_mfma_f32_16x16x32_f16 v[60:63], v[156:159], v[188:191], 0
	v_mfma_f32_16x16x32_f16 v[56:59], v[164:167], v[188:191], 0
	v_mfma_f32_16x16x32_f16 v[44:47], v[156:159], v[196:199], 0
	v_mfma_f32_16x16x32_f16 v[40:43], v[164:167], v[196:199], 0
	v_mfma_f32_16x16x32_f16 v[28:31], v[156:159], v[204:207], 0
	v_mfma_f32_16x16x32_f16 v[24:27], v[164:167], v[204:207], 0
	v_mfma_f32_16x16x32_f16 v[12:15], v[156:159], v[212:215], 0
	v_mfma_f32_16x16x32_f16 v[8:11], v[164:167], v[212:215], 0
	v_mfma_f32_16x16x32_f16 v[60:63], v[160:163], v[192:195], v[60:63]
	v_mfma_f32_16x16x32_f16 v[56:59], v[168:171], v[192:195], v[56:59]
	v_mfma_f32_16x16x32_f16 v[44:47], v[160:163], v[200:203], v[44:47]
	v_mfma_f32_16x16x32_f16 v[40:43], v[168:171], v[200:203], v[40:43]
	v_mfma_f32_16x16x32_f16 v[28:31], v[160:163], v[208:211], v[28:31]
	v_mfma_f32_16x16x32_f16 v[24:27], v[168:171], v[208:211], v[24:27]
	v_mfma_f32_16x16x32_f16 v[12:15], v[160:163], v[216:219], v[12:15]
	v_mfma_f32_16x16x32_f16 v[8:11], v[168:171], v[216:219], v[8:11]
	v_mfma_f32_16x16x32_f16 v[52:55], v[172:175], v[188:191], 0
	v_mfma_f32_16x16x32_f16 v[48:51], v[180:183], v[188:191], 0
	v_mfma_f32_16x16x32_f16 v[36:39], v[172:175], v[196:199], 0
	v_mfma_f32_16x16x32_f16 v[32:35], v[180:183], v[196:199], 0
	v_mfma_f32_16x16x32_f16 v[20:23], v[172:175], v[204:207], 0
	v_mfma_f32_16x16x32_f16 v[16:19], v[180:183], v[204:207], 0
	v_mfma_f32_16x16x32_f16 v[4:7], v[172:175], v[212:215], 0
	v_mfma_f32_16x16x32_f16 v[0:3], v[180:183], v[212:215], 0
	v_mfma_f32_16x16x32_f16 v[52:55], v[176:179], v[192:195], v[52:55]
	v_mfma_f32_16x16x32_f16 v[48:51], v[184:187], v[192:195], v[48:51]
	v_mfma_f32_16x16x32_f16 v[36:39], v[176:179], v[200:203], v[36:39]
	v_mfma_f32_16x16x32_f16 v[32:35], v[184:187], v[200:203], v[32:35]
	v_mfma_f32_16x16x32_f16 v[20:23], v[176:179], v[208:211], v[20:23]
	v_mfma_f32_16x16x32_f16 v[16:19], v[184:187], v[208:211], v[16:19]
	v_mfma_f32_16x16x32_f16 v[4:7], v[176:179], v[216:219], v[4:7]
	v_mfma_f32_16x16x32_f16 v[0:3], v[184:187], v[216:219], v[0:3]
	s_barrier
	s_add_i32 s86, 0, 0x18000
	v_add_u32_e32 v136, s86, v144
	ds_read_b128 v[156:159], v136
	ds_read_b128 v[160:163], v136 offset:1024
	ds_read_b128 v[164:167], v136 offset:2048
	ds_read_b128 v[168:171], v136 offset:3072
	ds_read_b128 v[172:175], v155
	ds_read_b128 v[176:179], v155 offset:1024
	ds_read_b128 v[180:183], v155 offset:2048
	ds_read_b128 v[184:187], v155 offset:3072
	s_add_u32 s44, s44, 0x40000
	s_addc_u32 s45, s45, 0
	s_mov_b32 m0, s46
	v_lshl_add_u64 v[226:227], s[44:45], 0, v[128:129]
	ds_read_b128 v[188:191], v154 offset:32768
	ds_read_b128 v[192:195], v154 offset:33792
	ds_read_b128 v[196:199], v154 offset:34816
	ds_read_b128 v[200:203], v154 offset:35840
	ds_read_b128 v[204:207], v154 offset:36864
	ds_read_b128 v[208:211], v154 offset:37888
	ds_read_b128 v[212:215], v154 offset:38912
	ds_read_b128 v[216:219], v154 offset:39936
	global_load_lds_dwordx4 v[226:227], off
	v_lshl_add_u64 v[226:227], s[44:45], 0, v[132:133]
	s_mov_b32 m0, s47
	s_nop 0
	global_load_lds_dwordx4 v[226:227], off
	s_waitcnt vmcnt(8)
	s_waitcnt lgkmcnt(0)
	s_barrier
	s_waitcnt lgkmcnt(0)
	v_mfma_f32_16x16x32_f16 v[124:127], v[156:159], v[188:191], v[124:127]
	v_mfma_f32_16x16x32_f16 v[120:123], v[164:167], v[188:191], v[120:123]
	v_mfma_f32_16x16x32_f16 v[108:111], v[156:159], v[196:199], v[108:111]
	v_mfma_f32_16x16x32_f16 v[104:107], v[164:167], v[196:199], v[104:107]
	v_mfma_f32_16x16x32_f16 v[92:95], v[156:159], v[204:207], v[92:95]
	v_mfma_f32_16x16x32_f16 v[88:91], v[164:167], v[204:207], v[88:91]
	v_mfma_f32_16x16x32_f16 v[76:79], v[156:159], v[212:215], v[76:79]
	v_mfma_f32_16x16x32_f16 v[72:75], v[164:167], v[212:215], v[72:75]
	v_mfma_f32_16x16x32_f16 v[124:127], v[160:163], v[192:195], v[124:127]
	v_mfma_f32_16x16x32_f16 v[120:123], v[168:171], v[192:195], v[120:123]
	v_mfma_f32_16x16x32_f16 v[108:111], v[160:163], v[200:203], v[108:111]
	v_mfma_f32_16x16x32_f16 v[104:107], v[168:171], v[200:203], v[104:107]
	v_mfma_f32_16x16x32_f16 v[92:95], v[160:163], v[208:211], v[92:95]
	v_mfma_f32_16x16x32_f16 v[88:91], v[168:171], v[208:211], v[88:91]
	v_mfma_f32_16x16x32_f16 v[76:79], v[160:163], v[216:219], v[76:79]
	v_mfma_f32_16x16x32_f16 v[72:75], v[168:171], v[216:219], v[72:75]
	v_mfma_f32_16x16x32_f16 v[116:119], v[172:175], v[188:191], v[116:119]
	v_mfma_f32_16x16x32_f16 v[112:115], v[180:183], v[188:191], v[112:115]
	v_mfma_f32_16x16x32_f16 v[100:103], v[172:175], v[196:199], v[100:103]
	v_mfma_f32_16x16x32_f16 v[96:99], v[180:183], v[196:199], v[96:99]
	v_mfma_f32_16x16x32_f16 v[84:87], v[172:175], v[204:207], v[84:87]
	v_mfma_f32_16x16x32_f16 v[80:83], v[180:183], v[204:207], v[80:83]
	v_mfma_f32_16x16x32_f16 v[68:71], v[172:175], v[212:215], v[68:71]
	v_mfma_f32_16x16x32_f16 v[64:67], v[180:183], v[212:215], v[64:67]
	v_mfma_f32_16x16x32_f16 v[116:119], v[176:179], v[192:195], v[116:119]
	v_mfma_f32_16x16x32_f16 v[112:115], v[184:187], v[192:195], v[112:115]
	v_mfma_f32_16x16x32_f16 v[100:103], v[176:179], v[200:203], v[100:103]
	v_mfma_f32_16x16x32_f16 v[96:99], v[184:187], v[200:203], v[96:99]
	v_mfma_f32_16x16x32_f16 v[84:87], v[176:179], v[208:211], v[84:87]
	v_mfma_f32_16x16x32_f16 v[80:83], v[184:187], v[208:211], v[80:83]
	v_mfma_f32_16x16x32_f16 v[68:71], v[176:179], v[216:219], v[68:71]
	v_mfma_f32_16x16x32_f16 v[64:67], v[184:187], v[216:219], v[64:67]
	s_barrier
	s_add_i32 s44, s86, s66
	v_lshl_add_u64 v[142:143], v[142:143], 0, s[6:7]
	s_mov_b32 m0, s44
	ds_read_b128 v[188:191], v154 offset:49152
	ds_read_b128 v[192:195], v154 offset:50176
	ds_read_b128 v[196:199], v154 offset:51200
	ds_read_b128 v[200:203], v154 offset:52224
	ds_read_b128 v[204:207], v154 offset:53248
	ds_read_b128 v[208:211], v154 offset:54272
	ds_read_b128 v[212:215], v154 offset:55296
	ds_read_b128 v[216:219], v154 offset:56320
	global_load_lds_dwordx4 v[142:143], off
	s_add_i32 m0, s44, 0x2000
	s_add_u32 s42, s42, 0x40080
	v_lshl_add_u64 v[142:143], v[220:221], 0, s[6:7]
	s_addc_u32 s43, s43, 0
	s_add_i32 s44, s71, s66
	global_load_lds_dwordx4 v[142:143], off
	v_lshl_add_u64 v[142:143], s[42:43], 0, v[130:131]
	s_mov_b32 m0, s44
	s_nop 0
	global_load_lds_dwordx4 v[142:143], off
	v_lshl_add_u64 v[142:143], s[42:43], 0, v[134:135]
	s_add_i32 m0, s44, 0x2000
	s_nop 0
	global_load_lds_dwordx4 v[142:143], off
	v_lshl_add_u64 v[142:143], v[222:223], 0, s[6:7]
	s_mov_b32 m0, s48
	s_nop 0
	global_load_lds_dwordx4 v[142:143], off
	v_lshl_add_u64 v[142:143], v[224:225], 0, s[6:7]
	s_mov_b32 m0, s49
	s_nop 0
	global_load_lds_dwordx4 v[142:143], off
	s_waitcnt vmcnt(8)
	s_waitcnt lgkmcnt(0)
	s_barrier
	s_waitcnt lgkmcnt(0)
	v_mfma_f32_16x16x32_f16 v[60:63], v[156:159], v[188:191], v[60:63]
	v_mfma_f32_16x16x32_f16 v[56:59], v[164:167], v[188:191], v[56:59]
	v_mfma_f32_16x16x32_f16 v[44:47], v[156:159], v[196:199], v[44:47]
	v_mfma_f32_16x16x32_f16 v[40:43], v[164:167], v[196:199], v[40:43]
	v_mfma_f32_16x16x32_f16 v[28:31], v[156:159], v[204:207], v[28:31]
	v_mfma_f32_16x16x32_f16 v[24:27], v[164:167], v[204:207], v[24:27]
	v_mfma_f32_16x16x32_f16 v[12:15], v[156:159], v[212:215], v[12:15]
	v_mfma_f32_16x16x32_f16 v[8:11], v[164:167], v[212:215], v[8:11]
	v_mfma_f32_16x16x32_f16 v[60:63], v[160:163], v[192:195], v[60:63]
	v_mfma_f32_16x16x32_f16 v[56:59], v[168:171], v[192:195], v[56:59]
	v_mfma_f32_16x16x32_f16 v[44:47], v[160:163], v[200:203], v[44:47]
	v_mfma_f32_16x16x32_f16 v[40:43], v[168:171], v[200:203], v[40:43]
	v_mfma_f32_16x16x32_f16 v[28:31], v[160:163], v[208:211], v[28:31]
	v_mfma_f32_16x16x32_f16 v[24:27], v[168:171], v[208:211], v[24:27]
	v_mfma_f32_16x16x32_f16 v[12:15], v[160:163], v[216:219], v[12:15]
	v_mfma_f32_16x16x32_f16 v[8:11], v[168:171], v[216:219], v[8:11]
	v_mfma_f32_16x16x32_f16 v[52:55], v[172:175], v[188:191], v[52:55]
	v_mfma_f32_16x16x32_f16 v[48:51], v[180:183], v[188:191], v[48:51]
	v_mfma_f32_16x16x32_f16 v[36:39], v[172:175], v[196:199], v[36:39]
	v_mfma_f32_16x16x32_f16 v[32:35], v[180:183], v[196:199], v[32:35]
	v_mfma_f32_16x16x32_f16 v[20:23], v[172:175], v[204:207], v[20:23]
	v_mfma_f32_16x16x32_f16 v[16:19], v[180:183], v[204:207], v[16:19]
	v_mfma_f32_16x16x32_f16 v[4:7], v[172:175], v[212:215], v[4:7]
	v_mfma_f32_16x16x32_f16 v[0:3], v[180:183], v[212:215], v[0:3]
	v_mfma_f32_16x16x32_f16 v[52:55], v[176:179], v[192:195], v[52:55]
	v_mfma_f32_16x16x32_f16 v[48:51], v[184:187], v[192:195], v[48:51]
	v_mfma_f32_16x16x32_f16 v[36:39], v[176:179], v[200:203], v[36:39]
	v_mfma_f32_16x16x32_f16 v[32:35], v[184:187], v[200:203], v[32:35]
	v_mfma_f32_16x16x32_f16 v[20:23], v[176:179], v[208:211], v[20:23]
	v_mfma_f32_16x16x32_f16 v[16:19], v[184:187], v[208:211], v[16:19]
	v_mfma_f32_16x16x32_f16 v[4:7], v[176:179], v[216:219], v[4:7]
	v_mfma_f32_16x16x32_f16 v[0:3], v[184:187], v[216:219], v[0:3]
	s_add_i32 s85, s85, 2
	s_add_u32 s34, s34, 0x100
	s_addc_u32 s35, s35, 0
	s_add_u32 s83, s83, 0x100
	s_addc_u32 s84, s84, 0
	s_cmp_gt_u32 s85, 13
.LBB0_1044:
	s_barrier
	v_add_u32_e32 v136, s67, v144
	ds_read_b128 v[156:159], v136
	ds_read_b128 v[160:163], v136 offset:1024
	ds_read_b128 v[164:167], v136 offset:2048
	ds_read_b128 v[168:171], v136 offset:3072
	ds_read_b128 v[172:175], v153
	ds_read_b128 v[176:179], v153 offset:1024
	ds_read_b128 v[180:183], v153 offset:2048
	ds_read_b128 v[184:187], v153 offset:3072
	s_add_u32 s42, s34, 0xfffc0080
	s_addc_u32 s43, s35, -1
	s_cmp_eq_u32 s85, 12
	s_cselect_b32 s45, s5, s43
	s_cselect_b32 s44, s29, s42
	s_cselect_b32 s43, s33, s84
	s_cselect_b32 s42, s82, s83
	v_lshl_add_u64 v[142:143], s[34:35], 0, v[138:139]
	s_add_i32 m0, s3, 0xc000
	ds_read_b128 v[188:191], v154
	ds_read_b128 v[192:195], v154 offset:1024
	ds_read_b128 v[196:199], v154 offset:2048
	ds_read_b128 v[200:203], v154 offset:3072
	ds_read_b128 v[204:207], v154 offset:4096
	ds_read_b128 v[208:211], v154 offset:5120
	ds_read_b128 v[212:215], v154 offset:6144
	ds_read_b128 v[216:219], v154 offset:7168
	global_load_lds_dwordx4 v[142:143], off
	v_lshl_add_u64 v[142:143], s[34:35], 0, v[140:141]
	s_add_i32 m0, s3, 0xe000
	s_nop 0
	global_load_lds_dwordx4 v[142:143], off
	s_waitcnt vmcnt(8)
	s_waitcnt lgkmcnt(0)
	s_barrier
	s_waitcnt lgkmcnt(0)
	v_mfma_f32_16x16x32_f16 v[124:127], v[156:159], v[188:191], v[124:127]
	v_mfma_f32_16x16x32_f16 v[120:123], v[164:167], v[188:191], v[120:123]
	v_mfma_f32_16x16x32_f16 v[108:111], v[156:159], v[196:199], v[108:111]
	v_mfma_f32_16x16x32_f16 v[104:107], v[164:167], v[196:199], v[104:107]
	v_mfma_f32_16x16x32_f16 v[92:95], v[156:159], v[204:207], v[92:95]
	v_mfma_f32_16x16x32_f16 v[88:91], v[164:167], v[204:207], v[88:91]
	v_mfma_f32_16x16x32_f16 v[76:79], v[156:159], v[212:215], v[76:79]
	v_mfma_f32_16x16x32_f16 v[72:75], v[164:167], v[212:215], v[72:75]
	v_mfma_f32_16x16x32_f16 v[124:127], v[160:163], v[192:195], v[124:127]
	v_mfma_f32_16x16x32_f16 v[120:123], v[168:171], v[192:195], v[120:123]
	v_mfma_f32_16x16x32_f16 v[108:111], v[160:163], v[200:203], v[108:111]
	v_mfma_f32_16x16x32_f16 v[104:107], v[168:171], v[200:203], v[104:107]
	v_mfma_f32_16x16x32_f16 v[92:95], v[160:163], v[208:211], v[92:95]
	v_mfma_f32_16x16x32_f16 v[88:91], v[168:171], v[208:211], v[88:91]
	v_mfma_f32_16x16x32_f16 v[76:79], v[160:163], v[216:219], v[76:79]
	v_mfma_f32_16x16x32_f16 v[72:75], v[168:171], v[216:219], v[72:75]
	v_mfma_f32_16x16x32_f16 v[116:119], v[172:175], v[188:191], v[116:119]
	v_mfma_f32_16x16x32_f16 v[112:115], v[180:183], v[188:191], v[112:115]
	v_mfma_f32_16x16x32_f16 v[100:103], v[172:175], v[196:199], v[100:103]
	v_mfma_f32_16x16x32_f16 v[96:99], v[180:183], v[196:199], v[96:99]
	v_mfma_f32_16x16x32_f16 v[84:87], v[172:175], v[204:207], v[84:87]
	v_mfma_f32_16x16x32_f16 v[80:83], v[180:183], v[204:207], v[80:83]
	v_mfma_f32_16x16x32_f16 v[68:71], v[172:175], v[212:215], v[68:71]
	v_mfma_f32_16x16x32_f16 v[64:67], v[180:183], v[212:215], v[64:67]
	v_mfma_f32_16x16x32_f16 v[116:119], v[176:179], v[192:195], v[116:119]
	v_mfma_f32_16x16x32_f16 v[112:115], v[184:187], v[192:195], v[112:115]
	v_mfma_f32_16x16x32_f16 v[100:103], v[176:179], v[200:203], v[100:103]
	v_mfma_f32_16x16x32_f16 v[96:99], v[184:187], v[200:203], v[96:99]
	v_mfma_f32_16x16x32_f16 v[84:87], v[176:179], v[208:211], v[84:87]
	v_mfma_f32_16x16x32_f16 v[80:83], v[184:187], v[208:211], v[80:83]
	v_mfma_f32_16x16x32_f16 v[68:71], v[176:179], v[216:219], v[68:71]
	v_mfma_f32_16x16x32_f16 v[64:67], v[184:187], v[216:219], v[64:67]
	s_barrier
	s_add_i32 s86, s67, s66
	v_lshl_add_u64 v[142:143], s[42:43], 0, v[130:131]
	s_mov_b32 m0, s86
	ds_read_b128 v[188:191], v154 offset:16384
	ds_read_b128 v[192:195], v154 offset:17408
	ds_read_b128 v[196:199], v154 offset:18432
	ds_read_b128 v[200:203], v154 offset:19456
	ds_read_b128 v[204:207], v154 offset:20480
	ds_read_b128 v[208:211], v154 offset:21504
	ds_read_b128 v[212:215], v154 offset:22528
	ds_read_b128 v[216:219], v154 offset:23552
	global_load_lds_dwordx4 v[142:143], off
	s_add_i32 m0, s86, 0x2000
	s_add_u32 s86, s42, 0x40000
	v_lshl_add_u64 v[220:221], s[42:43], 0, v[134:135]
	s_addc_u32 s87, s43, 0
	s_add_i32 s88, s70, s66
	global_load_lds_dwordx4 v[220:221], off
	v_lshl_add_u64 v[222:223], s[86:87], 0, v[130:131]
	s_mov_b32 m0, s88
	v_lshl_add_u64 v[224:225], s[44:45], 0, v[132:133]
	global_load_lds_dwordx4 v[222:223], off
	v_lshl_add_u64 v[222:223], s[86:87], 0, v[134:135]
	s_add_i32 m0, s88, 0x2000
	s_nop 0
	global_load_lds_dwordx4 v[222:223], off
	v_lshl_add_u64 v[222:223], s[44:45], 0, v[128:129]
	s_mov_b32 m0, s3
	s_nop 0
	global_load_lds_dwordx4 v[222:223], off
	s_mov_b32 m0, s31
	s_nop 0
	global_load_lds_dwordx4 v[224:225], off
	s_waitcnt vmcnt(8)
	s_waitcnt lgkmcnt(0)
	s_barrier
	s_waitcnt lgkmcnt(0)
	v_mfma_f32_16x16x32_f16 v[60:63], v[156:159], v[188:191], v[60:63]
	v_mfma_f32_16x16x32_f16 v[56:59], v[164:167], v[188:191], v[56:59]
	v_mfma_f32_16x16x32_f16 v[44:47], v[156:159], v[196:199], v[44:47]
	v_mfma_f32_16x16x32_f16 v[40:43], v[164:167], v[196:199], v[40:43]
	v_mfma_f32_16x16x32_f16 v[28:31], v[156:159], v[204:207], v[28:31]
	v_mfma_f32_16x16x32_f16 v[24:27], v[164:167], v[204:207], v[24:27]
	v_mfma_f32_16x16x32_f16 v[12:15], v[156:159], v[212:215], v[12:15]
	v_mfma_f32_16x16x32_f16 v[8:11], v[164:167], v[212:215], v[8:11]
	v_mfma_f32_16x16x32_f16 v[60:63], v[160:163], v[192:195], v[60:63]
	v_mfma_f32_16x16x32_f16 v[56:59], v[168:171], v[192:195], v[56:59]
	v_mfma_f32_16x16x32_f16 v[44:47], v[160:163], v[200:203], v[44:47]
	v_mfma_f32_16x16x32_f16 v[40:43], v[168:171], v[200:203], v[40:43]
	v_mfma_f32_16x16x32_f16 v[28:31], v[160:163], v[208:211], v[28:31]
	v_mfma_f32_16x16x32_f16 v[24:27], v[168:171], v[208:211], v[24:27]
	v_mfma_f32_16x16x32_f16 v[12:15], v[160:163], v[216:219], v[12:15]
	v_mfma_f32_16x16x32_f16 v[8:11], v[168:171], v[216:219], v[8:11]
	v_mfma_f32_16x16x32_f16 v[52:55], v[172:175], v[188:191], v[52:55]
	v_mfma_f32_16x16x32_f16 v[48:51], v[180:183], v[188:191], v[48:51]
	v_mfma_f32_16x16x32_f16 v[36:39], v[172:175], v[196:199], v[36:39]
	v_mfma_f32_16x16x32_f16 v[32:35], v[180:183], v[196:199], v[32:35]
	v_mfma_f32_16x16x32_f16 v[20:23], v[172:175], v[204:207], v[20:23]
	v_mfma_f32_16x16x32_f16 v[16:19], v[180:183], v[204:207], v[16:19]
	v_mfma_f32_16x16x32_f16 v[4:7], v[172:175], v[212:215], v[4:7]
	v_mfma_f32_16x16x32_f16 v[0:3], v[180:183], v[212:215], v[0:3]
	v_mfma_f32_16x16x32_f16 v[52:55], v[176:179], v[192:195], v[52:55]
	v_mfma_f32_16x16x32_f16 v[48:51], v[184:187], v[192:195], v[48:51]
	v_mfma_f32_16x16x32_f16 v[36:39], v[176:179], v[200:203], v[36:39]
	v_mfma_f32_16x16x32_f16 v[32:35], v[184:187], v[200:203], v[32:35]
	v_mfma_f32_16x16x32_f16 v[20:23], v[176:179], v[208:211], v[20:23]
	v_mfma_f32_16x16x32_f16 v[16:19], v[184:187], v[208:211], v[16:19]
	v_mfma_f32_16x16x32_f16 v[4:7], v[176:179], v[216:219], v[4:7]
	v_mfma_f32_16x16x32_f16 v[0:3], v[184:187], v[216:219], v[0:3]
	s_barrier
	s_add_i32 s86, 0, 0x18000
	v_add_u32_e32 v136, s86, v144
	ds_read_b128 v[156:159], v136
	ds_read_b128 v[160:163], v136 offset:1024
	ds_read_b128 v[164:167], v136 offset:2048
	ds_read_b128 v[168:171], v136 offset:3072
	ds_read_b128 v[172:175], v155
	ds_read_b128 v[176:179], v155 offset:1024
	ds_read_b128 v[180:183], v155 offset:2048
	ds_read_b128 v[184:187], v155 offset:3072
	s_add_u32 s44, s44, 0x40000
	s_addc_u32 s45, s45, 0
	s_mov_b32 m0, s46
	v_lshl_add_u64 v[226:227], s[44:45], 0, v[128:129]
	ds_read_b128 v[188:191], v154 offset:32768
	ds_read_b128 v[192:195], v154 offset:33792
	ds_read_b128 v[196:199], v154 offset:34816
	ds_read_b128 v[200:203], v154 offset:35840
	ds_read_b128 v[204:207], v154 offset:36864
	ds_read_b128 v[208:211], v154 offset:37888
	ds_read_b128 v[212:215], v154 offset:38912
	ds_read_b128 v[216:219], v154 offset:39936
	global_load_lds_dwordx4 v[226:227], off
	v_lshl_add_u64 v[226:227], s[44:45], 0, v[132:133]
	s_mov_b32 m0, s47
	s_nop 0
	global_load_lds_dwordx4 v[226:227], off
	s_waitcnt vmcnt(8)
	s_waitcnt lgkmcnt(0)
	s_barrier
	s_waitcnt lgkmcnt(0)
	v_mfma_f32_16x16x32_f16 v[124:127], v[156:159], v[188:191], v[124:127]
	v_mfma_f32_16x16x32_f16 v[120:123], v[164:167], v[188:191], v[120:123]
	v_mfma_f32_16x16x32_f16 v[108:111], v[156:159], v[196:199], v[108:111]
	v_mfma_f32_16x16x32_f16 v[104:107], v[164:167], v[196:199], v[104:107]
	v_mfma_f32_16x16x32_f16 v[92:95], v[156:159], v[204:207], v[92:95]
	v_mfma_f32_16x16x32_f16 v[88:91], v[164:167], v[204:207], v[88:91]
	v_mfma_f32_16x16x32_f16 v[76:79], v[156:159], v[212:215], v[76:79]
	v_mfma_f32_16x16x32_f16 v[72:75], v[164:167], v[212:215], v[72:75]
	v_mfma_f32_16x16x32_f16 v[124:127], v[160:163], v[192:195], v[124:127]
	v_mfma_f32_16x16x32_f16 v[120:123], v[168:171], v[192:195], v[120:123]
	v_mfma_f32_16x16x32_f16 v[108:111], v[160:163], v[200:203], v[108:111]
	v_mfma_f32_16x16x32_f16 v[104:107], v[168:171], v[200:203], v[104:107]
	v_mfma_f32_16x16x32_f16 v[92:95], v[160:163], v[208:211], v[92:95]
	v_mfma_f32_16x16x32_f16 v[88:91], v[168:171], v[208:211], v[88:91]
	v_mfma_f32_16x16x32_f16 v[76:79], v[160:163], v[216:219], v[76:79]
	v_mfma_f32_16x16x32_f16 v[72:75], v[168:171], v[216:219], v[72:75]
	v_mfma_f32_16x16x32_f16 v[116:119], v[172:175], v[188:191], v[116:119]
	v_mfma_f32_16x16x32_f16 v[112:115], v[180:183], v[188:191], v[112:115]
	v_mfma_f32_16x16x32_f16 v[100:103], v[172:175], v[196:199], v[100:103]
	v_mfma_f32_16x16x32_f16 v[96:99], v[180:183], v[196:199], v[96:99]
	v_mfma_f32_16x16x32_f16 v[84:87], v[172:175], v[204:207], v[84:87]
	v_mfma_f32_16x16x32_f16 v[80:83], v[180:183], v[204:207], v[80:83]
	v_mfma_f32_16x16x32_f16 v[68:71], v[172:175], v[212:215], v[68:71]
	v_mfma_f32_16x16x32_f16 v[64:67], v[180:183], v[212:215], v[64:67]
	v_mfma_f32_16x16x32_f16 v[116:119], v[176:179], v[192:195], v[116:119]
	v_mfma_f32_16x16x32_f16 v[112:115], v[184:187], v[192:195], v[112:115]
	v_mfma_f32_16x16x32_f16 v[100:103], v[176:179], v[200:203], v[100:103]
	v_mfma_f32_16x16x32_f16 v[96:99], v[184:187], v[200:203], v[96:99]
	v_mfma_f32_16x16x32_f16 v[84:87], v[176:179], v[208:211], v[84:87]
	v_mfma_f32_16x16x32_f16 v[80:83], v[184:187], v[208:211], v[80:83]
	v_mfma_f32_16x16x32_f16 v[68:71], v[176:179], v[216:219], v[68:71]
	v_mfma_f32_16x16x32_f16 v[64:67], v[184:187], v[216:219], v[64:67]
	s_barrier
	s_add_i32 s44, s86, s66
	v_lshl_add_u64 v[142:143], v[142:143], 0, s[6:7]
	s_mov_b32 m0, s44
	ds_read_b128 v[188:191], v154 offset:49152
	ds_read_b128 v[192:195], v154 offset:50176
	ds_read_b128 v[196:199], v154 offset:51200
	ds_read_b128 v[200:203], v154 offset:52224
	ds_read_b128 v[204:207], v154 offset:53248
	ds_read_b128 v[208:211], v154 offset:54272
	ds_read_b128 v[212:215], v154 offset:55296
	ds_read_b128 v[216:219], v154 offset:56320
	global_load_lds_dwordx4 v[142:143], off
	s_add_i32 m0, s44, 0x2000
	s_add_u32 s42, s42, 0x40080
	v_lshl_add_u64 v[142:143], v[220:221], 0, s[6:7]
	s_addc_u32 s43, s43, 0
	s_add_i32 s44, s71, s66
	global_load_lds_dwordx4 v[142:143], off
	v_lshl_add_u64 v[142:143], s[42:43], 0, v[130:131]
	s_mov_b32 m0, s44
	s_nop 0
	global_load_lds_dwordx4 v[142:143], off
	v_lshl_add_u64 v[142:143], s[42:43], 0, v[134:135]
	s_add_i32 m0, s44, 0x2000
	s_nop 0
	global_load_lds_dwordx4 v[142:143], off
	v_lshl_add_u64 v[142:143], v[222:223], 0, s[6:7]
	s_mov_b32 m0, s48
	s_nop 0
	global_load_lds_dwordx4 v[142:143], off
	v_lshl_add_u64 v[142:143], v[224:225], 0, s[6:7]
	s_mov_b32 m0, s49
	s_nop 0
	global_load_lds_dwordx4 v[142:143], off
	s_waitcnt vmcnt(8)
	s_waitcnt lgkmcnt(0)
	s_barrier
	s_waitcnt lgkmcnt(0)
	v_mfma_f32_16x16x32_f16 v[60:63], v[156:159], v[188:191], v[60:63]
	v_mfma_f32_16x16x32_f16 v[56:59], v[164:167], v[188:191], v[56:59]
	v_mfma_f32_16x16x32_f16 v[44:47], v[156:159], v[196:199], v[44:47]
	v_mfma_f32_16x16x32_f16 v[40:43], v[164:167], v[196:199], v[40:43]
	v_mfma_f32_16x16x32_f16 v[28:31], v[156:159], v[204:207], v[28:31]
	v_mfma_f32_16x16x32_f16 v[24:27], v[164:167], v[204:207], v[24:27]
	v_mfma_f32_16x16x32_f16 v[12:15], v[156:159], v[212:215], v[12:15]
	v_mfma_f32_16x16x32_f16 v[8:11], v[164:167], v[212:215], v[8:11]
	v_mfma_f32_16x16x32_f16 v[60:63], v[160:163], v[192:195], v[60:63]
	v_mfma_f32_16x16x32_f16 v[56:59], v[168:171], v[192:195], v[56:59]
	v_mfma_f32_16x16x32_f16 v[44:47], v[160:163], v[200:203], v[44:47]
	v_mfma_f32_16x16x32_f16 v[40:43], v[168:171], v[200:203], v[40:43]
	v_mfma_f32_16x16x32_f16 v[28:31], v[160:163], v[208:211], v[28:31]
	v_mfma_f32_16x16x32_f16 v[24:27], v[168:171], v[208:211], v[24:27]
	v_mfma_f32_16x16x32_f16 v[12:15], v[160:163], v[216:219], v[12:15]
	v_mfma_f32_16x16x32_f16 v[8:11], v[168:171], v[216:219], v[8:11]
	v_mfma_f32_16x16x32_f16 v[52:55], v[172:175], v[188:191], v[52:55]
	v_mfma_f32_16x16x32_f16 v[48:51], v[180:183], v[188:191], v[48:51]
	v_mfma_f32_16x16x32_f16 v[36:39], v[172:175], v[196:199], v[36:39]
	v_mfma_f32_16x16x32_f16 v[32:35], v[180:183], v[196:199], v[32:35]
	v_mfma_f32_16x16x32_f16 v[20:23], v[172:175], v[204:207], v[20:23]
	v_mfma_f32_16x16x32_f16 v[16:19], v[180:183], v[204:207], v[16:19]
	v_mfma_f32_16x16x32_f16 v[4:7], v[172:175], v[212:215], v[4:7]
	v_mfma_f32_16x16x32_f16 v[0:3], v[180:183], v[212:215], v[0:3]
	v_mfma_f32_16x16x32_f16 v[52:55], v[176:179], v[192:195], v[52:55]
	v_mfma_f32_16x16x32_f16 v[48:51], v[184:187], v[192:195], v[48:51]
	v_mfma_f32_16x16x32_f16 v[36:39], v[176:179], v[200:203], v[36:39]
	v_mfma_f32_16x16x32_f16 v[32:35], v[184:187], v[200:203], v[32:35]
	v_mfma_f32_16x16x32_f16 v[20:23], v[176:179], v[208:211], v[20:23]
	v_mfma_f32_16x16x32_f16 v[16:19], v[184:187], v[208:211], v[16:19]
	v_mfma_f32_16x16x32_f16 v[4:7], v[176:179], v[216:219], v[4:7]
	v_mfma_f32_16x16x32_f16 v[0:3], v[184:187], v[216:219], v[0:3]
	s_add_i32 s85, s85, 2
	s_add_u32 s34, s34, 0x100
	s_addc_u32 s35, s35, 0
	s_add_u32 s83, s83, 0x100
	s_addc_u32 s84, s84, 0
	s_cmp_gt_u32 s85, 13
	s_cbranch_scc0 .LBB0_1044
	s_barrier
	s_and_b64 vcc, exec, s[26:27]
	s_cbranch_vccz .LBB0_1047
	s_barrier

.LBB0_1231:
	v_and_b32_e32 v142, 15, v2
	v_and_b32_e32 v143, 48, v2
	v_lshlrev_b32_e32 v2, 2, v2
	s_lshl_b32 s14, s14, 21
	v_lshl_or_b32 v7, v142, 6, v143
	v_and_b32_e32 v2, 32, v2
	s_and_b32 s14, s14, 0x3800000
	s_lshl_b32 s15, s15, 19
	v_bitop3_b32 v8, v7, s52, v2 bitop3:0xde
	v_bitop3_b32 v144, v7, s53, v2 bitop3:0xde
	s_add_i32 s14, s14, s15
	v_lshlrev_b32_e32 v2, 14, v0
	s_add_u32 s38, s76, s14
	v_and_b32_e32 v2, 0xffff8000, v2
	s_addc_u32 s39, s77, 0
	v_lshl_add_u32 v1, v1, 11, v2
	v_and_b32_e32 v0, 1, v0
	v_lshl_or_b32 v0, v0, 6, v1
	s_add_u32 s14, s3, s14
	v_lshl_add_u32 v0, v3, 1, v0
	v_mov_b32_e32 v1, v129
	s_addc_u32 s15, s28, 0
	v_lshl_add_u64 v[136:137], s[14:15], 0, v[0:1]
	v_lshlrev_b32_e32 v0, 14, v4
	v_and_b32_e32 v0, 0xffff8000, v0
	v_lshl_add_u32 v0, v5, 11, v0
	v_and_b32_e32 v1, 1, v4
	v_lshl_or_b32 v0, v1, 6, v0
	s_waitcnt vmcnt(8)
	s_barrier
	s_waitcnt vmcnt(6)
	v_lshl_add_u32 v0, v6, 1, v0
	v_mov_b32_e32 v1, v129
	v_lshl_add_u64 v[138:139], s[14:15], 0, v[0:1]
	s_add_u32 s40, s29, s16
	s_addc_u32 s41, s33, 0
	s_mov_b32 s42, -2
	s_mov_b64 s[14:15], 0
	v_add_u32_e32 v145, 0, v8
	s_barrier
	s_add_u32 s16, s38, s14
	s_addc_u32 s17, s39, s15
	s_add_u32 s16, s16, 0x13d00100
	s_addc_u32 s17, s17, 0
	s_add_u32 s43, s40, s14
	s_addc_u32 s44, s41, s15
	s_cmpk_eq_i32 s14, 0x700
	s_cselect_b32 s19, s11, s17
	s_cselect_b32 s18, s10, s16
	s_cselect_b32 s17, s13, s44
	s_cselect_b32 s16, s12, s43
	s_add_i32 s43, 0, 0x14000
	v_add_u32_e32 v158, s67, v144
	v_add_u32_e32 v174, s43, v144
	ds_read_b128 v[146:149], v158
	ds_read_b128 v[150:153], v158 offset:1024
	ds_read_b128 v[154:157], v158 offset:2048
	ds_read_b128 v[158:161], v158 offset:3072
	ds_read_b128 v[162:165], v174
	ds_read_b128 v[166:169], v174 offset:1024
	ds_read_b128 v[170:173], v174 offset:2048
	ds_read_b128 v[174:177], v174 offset:3072
	v_lshl_add_u64 v[210:211], v[136:137], 0, s[14:15]
	s_add_i32 m0, s30, 0xc000
	ds_read_b128 v[178:181], v145
	ds_read_b128 v[182:185], v145 offset:1024
	ds_read_b128 v[186:189], v145 offset:2048
	ds_read_b128 v[190:193], v145 offset:3072
	ds_read_b128 v[194:197], v145 offset:4096
	ds_read_b128 v[198:201], v145 offset:5120
	ds_read_b128 v[202:205], v145 offset:6144
	ds_read_b128 v[206:209], v145 offset:7168
	global_load_lds_dwordx4 v[210:211], off
	v_lshl_add_u64 v[210:211], v[138:139], 0, s[14:15]
	s_add_i32 m0, s30, 0xe000
	s_nop 0
	global_load_lds_dwordx4 v[210:211], off
	s_waitcnt vmcnt(8)
	s_waitcnt lgkmcnt(0)
	s_barrier
	s_waitcnt lgkmcnt(0)
	v_mfma_f32_16x16x32_f16 v[124:127], v[146:149], v[178:181], 0
	v_mfma_f32_16x16x32_f16 v[120:123], v[154:157], v[178:181], 0
	v_mfma_f32_16x16x32_f16 v[108:111], v[146:149], v[186:189], 0
	v_mfma_f32_16x16x32_f16 v[104:107], v[154:157], v[186:189], 0
	v_mfma_f32_16x16x32_f16 v[92:95], v[146:149], v[194:197], 0
	v_mfma_f32_16x16x32_f16 v[88:91], v[154:157], v[194:197], 0
	v_mfma_f32_16x16x32_f16 v[76:79], v[146:149], v[202:205], 0
	v_mfma_f32_16x16x32_f16 v[72:75], v[154:157], v[202:205], 0
	v_mfma_f32_16x16x32_f16 v[124:127], v[150:153], v[182:185], v[124:127]
	v_mfma_f32_16x16x32_f16 v[120:123], v[158:161], v[182:185], v[120:123]
	v_mfma_f32_16x16x32_f16 v[108:111], v[150:153], v[190:193], v[108:111]
	v_mfma_f32_16x16x32_f16 v[104:107], v[158:161], v[190:193], v[104:107]
	v_mfma_f32_16x16x32_f16 v[92:95], v[150:153], v[198:201], v[92:95]
	v_mfma_f32_16x16x32_f16 v[88:91], v[158:161], v[198:201], v[88:91]
	v_mfma_f32_16x16x32_f16 v[76:79], v[150:153], v[206:209], v[76:79]
	v_mfma_f32_16x16x32_f16 v[72:75], v[158:161], v[206:209], v[72:75]
	v_mfma_f32_16x16x32_f16 v[116:119], v[162:165], v[178:181], 0
	v_mfma_f32_16x16x32_f16 v[112:115], v[170:173], v[178:181], 0
	v_mfma_f32_16x16x32_f16 v[100:103], v[162:165], v[186:189], 0
	v_mfma_f32_16x16x32_f16 v[96:99], v[170:173], v[186:189], 0
	v_mfma_f32_16x16x32_f16 v[84:87], v[162:165], v[194:197], 0
	v_mfma_f32_16x16x32_f16 v[80:83], v[170:173], v[194:197], 0
	v_mfma_f32_16x16x32_f16 v[68:71], v[162:165], v[202:205], 0
	v_mfma_f32_16x16x32_f16 v[64:67], v[170:173], v[202:205], 0
	v_mfma_f32_16x16x32_f16 v[116:119], v[166:169], v[182:185], v[116:119]
	v_mfma_f32_16x16x32_f16 v[112:115], v[174:177], v[182:185], v[112:115]
	v_mfma_f32_16x16x32_f16 v[100:103], v[166:169], v[190:193], v[100:103]
	v_mfma_f32_16x16x32_f16 v[96:99], v[174:177], v[190:193], v[96:99]
	v_mfma_f32_16x16x32_f16 v[84:87], v[166:169], v[198:201], v[84:87]
	v_mfma_f32_16x16x32_f16 v[80:83], v[174:177], v[198:201], v[80:83]
	v_mfma_f32_16x16x32_f16 v[68:71], v[166:169], v[206:209], v[68:71]
	v_mfma_f32_16x16x32_f16 v[64:67], v[174:177], v[206:209], v[64:67]
	s_barrier
	s_add_i32 s44, s67, s66
	v_lshl_add_u64 v[210:211], s[16:17], 0, v[128:129]
	s_mov_b32 m0, s44
	ds_read_b128 v[178:181], v145 offset:16384
	ds_read_b128 v[182:185], v145 offset:17408
	ds_read_b128 v[186:189], v145 offset:18432
	ds_read_b128 v[190:193], v145 offset:19456
	ds_read_b128 v[194:197], v145 offset:20480
	ds_read_b128 v[198:201], v145 offset:21504
	ds_read_b128 v[202:205], v145 offset:22528
	ds_read_b128 v[206:209], v145 offset:23552
	global_load_lds_dwordx4 v[210:211], off
	s_add_i32 m0, s44, 0x2000
	s_add_u32 s44, s16, 0x40000
	v_lshl_add_u64 v[212:213], s[16:17], 0, v[134:135]
	s_addc_u32 s45, s17, 0
	s_add_i32 s43, s43, s66
	global_load_lds_dwordx4 v[212:213], off
	v_lshl_add_u64 v[214:215], s[44:45], 0, v[128:129]
	s_mov_b32 m0, s43
	v_lshl_add_u64 v[216:217], s[18:19], 0, v[132:133]
	global_load_lds_dwordx4 v[214:215], off
	v_lshl_add_u64 v[214:215], s[44:45], 0, v[134:135]
	s_add_i32 m0, s43, 0x2000
	s_nop 0
	global_load_lds_dwordx4 v[214:215], off
	v_lshl_add_u64 v[214:215], s[18:19], 0, v[130:131]
	s_mov_b32 m0, s30
	s_nop 0
	global_load_lds_dwordx4 v[214:215], off
	s_mov_b32 m0, s31
	s_nop 0
	global_load_lds_dwordx4 v[216:217], off
	s_waitcnt vmcnt(8)
	s_waitcnt lgkmcnt(0)
	s_barrier
	s_waitcnt lgkmcnt(0)
	v_mfma_f32_16x16x32_f16 v[60:63], v[146:149], v[178:181], 0
	v_mfma_f32_16x16x32_f16 v[56:59], v[154:157], v[178:181], 0
	v_mfma_f32_16x16x32_f16 v[44:47], v[146:149], v[186:189], 0
	v_mfma_f32_16x16x32_f16 v[40:43], v[154:157], v[186:189], 0
	v_mfma_f32_16x16x32_f16 v[28:31], v[146:149], v[194:197], 0
	v_mfma_f32_16x16x32_f16 v[24:27], v[154:157], v[194:197], 0
	v_mfma_f32_16x16x32_f16 v[12:15], v[146:149], v[202:205], 0
	v_mfma_f32_16x16x32_f16 v[8:11], v[154:157], v[202:205], 0
	v_mfma_f32_16x16x32_f16 v[60:63], v[150:153], v[182:185], v[60:63]
	v_mfma_f32_16x16x32_f16 v[56:59], v[158:161], v[182:185], v[56:59]
	v_mfma_f32_16x16x32_f16 v[44:47], v[150:153], v[190:193], v[44:47]
	v_mfma_f32_16x16x32_f16 v[40:43], v[158:161], v[190:193], v[40:43]
	v_mfma_f32_16x16x32_f16 v[28:31], v[150:153], v[198:201], v[28:31]
	v_mfma_f32_16x16x32_f16 v[24:27], v[158:161], v[198:201], v[24:27]
	v_mfma_f32_16x16x32_f16 v[12:15], v[150:153], v[206:209], v[12:15]
	v_mfma_f32_16x16x32_f16 v[8:11], v[158:161], v[206:209], v[8:11]
	v_mfma_f32_16x16x32_f16 v[52:55], v[162:165], v[178:181], 0
	v_mfma_f32_16x16x32_f16 v[48:51], v[170:173], v[178:181], 0
	v_mfma_f32_16x16x32_f16 v[36:39], v[162:165], v[186:189], 0
	v_mfma_f32_16x16x32_f16 v[32:35], v[170:173], v[186:189], 0
	v_mfma_f32_16x16x32_f16 v[20:23], v[162:165], v[194:197], 0
	v_mfma_f32_16x16x32_f16 v[16:19], v[170:173], v[194:197], 0
	v_mfma_f32_16x16x32_f16 v[4:7], v[162:165], v[202:205], 0
	v_mfma_f32_16x16x32_f16 v[0:3], v[170:173], v[202:205], 0
	v_mfma_f32_16x16x32_f16 v[52:55], v[166:169], v[182:185], v[52:55]
	v_mfma_f32_16x16x32_f16 v[48:51], v[174:177], v[182:185], v[48:51]
	v_mfma_f32_16x16x32_f16 v[36:39], v[166:169], v[190:193], v[36:39]
	v_mfma_f32_16x16x32_f16 v[32:35], v[174:177], v[190:193], v[32:35]
	v_mfma_f32_16x16x32_f16 v[20:23], v[166:169], v[198:201], v[20:23]
	v_mfma_f32_16x16x32_f16 v[16:19], v[174:177], v[198:201], v[16:19]
	v_mfma_f32_16x16x32_f16 v[4:7], v[166:169], v[206:209], v[4:7]
	v_mfma_f32_16x16x32_f16 v[0:3], v[174:177], v[206:209], v[0:3]
	s_barrier
	s_add_i32 s43, 0, 0x18000
	s_add_i32 s44, 0, 0x1c000
	v_add_u32_e32 v158, s43, v144
	v_add_u32_e32 v174, s44, v144
	ds_read_b128 v[146:149], v158
	ds_read_b128 v[150:153], v158 offset:1024
	ds_read_b128 v[154:157], v158 offset:2048
	ds_read_b128 v[158:161], v158 offset:3072
	ds_read_b128 v[162:165], v174
	ds_read_b128 v[166:169], v174 offset:1024
	ds_read_b128 v[170:173], v174 offset:2048
	ds_read_b128 v[174:177], v174 offset:3072
	s_add_u32 s18, s18, 0x40000
	s_addc_u32 s19, s19, 0
	s_mov_b32 m0, s34
	v_lshl_add_u64 v[218:219], s[18:19], 0, v[130:131]
	ds_read_b128 v[178:181], v145 offset:32768
	ds_read_b128 v[182:185], v145 offset:33792
	ds_read_b128 v[186:189], v145 offset:34816
	ds_read_b128 v[190:193], v145 offset:35840
	ds_read_b128 v[194:197], v145 offset:36864
	ds_read_b128 v[198:201], v145 offset:37888
	ds_read_b128 v[202:205], v145 offset:38912
	ds_read_b128 v[206:209], v145 offset:39936
	global_load_lds_dwordx4 v[218:219], off
	v_lshl_add_u64 v[218:219], s[18:19], 0, v[132:133]
	s_mov_b32 m0, s35
	s_nop 0
	global_load_lds_dwordx4 v[218:219], off
	s_waitcnt vmcnt(8)
	s_waitcnt lgkmcnt(0)
	s_barrier
	s_waitcnt lgkmcnt(0)
	v_mfma_f32_16x16x32_f16 v[124:127], v[146:149], v[178:181], v[124:127]
	v_mfma_f32_16x16x32_f16 v[120:123], v[154:157], v[178:181], v[120:123]
	v_mfma_f32_16x16x32_f16 v[108:111], v[146:149], v[186:189], v[108:111]
	v_mfma_f32_16x16x32_f16 v[104:107], v[154:157], v[186:189], v[104:107]
	v_mfma_f32_16x16x32_f16 v[92:95], v[146:149], v[194:197], v[92:95]
	v_mfma_f32_16x16x32_f16 v[88:91], v[154:157], v[194:197], v[88:91]
	v_mfma_f32_16x16x32_f16 v[76:79], v[146:149], v[202:205], v[76:79]
	v_mfma_f32_16x16x32_f16 v[72:75], v[154:157], v[202:205], v[72:75]
	v_mfma_f32_16x16x32_f16 v[124:127], v[150:153], v[182:185], v[124:127]
	v_mfma_f32_16x16x32_f16 v[120:123], v[158:161], v[182:185], v[120:123]
	v_mfma_f32_16x16x32_f16 v[108:111], v[150:153], v[190:193], v[108:111]
	v_mfma_f32_16x16x32_f16 v[104:107], v[158:161], v[190:193], v[104:107]
	v_mfma_f32_16x16x32_f16 v[92:95], v[150:153], v[198:201], v[92:95]
	v_mfma_f32_16x16x32_f16 v[88:91], v[158:161], v[198:201], v[88:91]
	v_mfma_f32_16x16x32_f16 v[76:79], v[150:153], v[206:209], v[76:79]
	v_mfma_f32_16x16x32_f16 v[72:75], v[158:161], v[206:209], v[72:75]
	v_mfma_f32_16x16x32_f16 v[116:119], v[162:165], v[178:181], v[116:119]
	v_mfma_f32_16x16x32_f16 v[112:115], v[170:173], v[178:181], v[112:115]
	v_mfma_f32_16x16x32_f16 v[100:103], v[162:165], v[186:189], v[100:103]
	v_mfma_f32_16x16x32_f16 v[96:99], v[170:173], v[186:189], v[96:99]
	v_mfma_f32_16x16x32_f16 v[84:87], v[162:165], v[194:197], v[84:87]
	v_mfma_f32_16x16x32_f16 v[80:83], v[170:173], v[194:197], v[80:83]
	v_mfma_f32_16x16x32_f16 v[68:71], v[162:165], v[202:205], v[68:71]
	v_mfma_f32_16x16x32_f16 v[64:67], v[170:173], v[202:205], v[64:67]
	v_mfma_f32_16x16x32_f16 v[116:119], v[166:169], v[182:185], v[116:119]
	v_mfma_f32_16x16x32_f16 v[112:115], v[174:177], v[182:185], v[112:115]
	v_mfma_f32_16x16x32_f16 v[100:103], v[166:169], v[190:193], v[100:103]
	v_mfma_f32_16x16x32_f16 v[96:99], v[174:177], v[190:193], v[96:99]
	v_mfma_f32_16x16x32_f16 v[84:87], v[166:169], v[198:201], v[84:87]
	v_mfma_f32_16x16x32_f16 v[80:83], v[174:177], v[198:201], v[80:83]
	v_mfma_f32_16x16x32_f16 v[68:71], v[166:169], v[206:209], v[68:71]
	v_mfma_f32_16x16x32_f16 v[64:67], v[174:177], v[206:209], v[64:67]
	s_barrier
	s_add_i32 s18, s43, s66
	v_lshl_add_u64 v[210:211], v[210:211], 0, s[6:7]
	s_mov_b32 m0, s18
	ds_read_b128 v[178:181], v145 offset:49152
	ds_read_b128 v[182:185], v145 offset:50176
	ds_read_b128 v[186:189], v145 offset:51200
	ds_read_b128 v[190:193], v145 offset:52224
	ds_read_b128 v[194:197], v145 offset:53248
	ds_read_b128 v[198:201], v145 offset:54272
	ds_read_b128 v[202:205], v145 offset:55296
	ds_read_b128 v[206:209], v145 offset:56320
	global_load_lds_dwordx4 v[210:211], off
	s_add_i32 m0, s18, 0x2000
	s_add_u32 s16, s16, 0x40080
	v_lshl_add_u64 v[210:211], v[212:213], 0, s[6:7]
	s_addc_u32 s17, s17, 0
	s_add_i32 s18, s44, s66
	global_load_lds_dwordx4 v[210:211], off
	v_lshl_add_u64 v[210:211], s[16:17], 0, v[128:129]
	s_mov_b32 m0, s18
	s_nop 0
	global_load_lds_dwordx4 v[210:211], off
	v_lshl_add_u64 v[210:211], s[16:17], 0, v[134:135]
	s_add_i32 m0, s18, 0x2000
	s_nop 0
	global_load_lds_dwordx4 v[210:211], off
	v_lshl_add_u64 v[210:211], v[214:215], 0, s[6:7]
	s_mov_b32 m0, s36
	s_nop 0
	global_load_lds_dwordx4 v[210:211], off
	v_lshl_add_u64 v[210:211], v[216:217], 0, s[6:7]
	s_mov_b32 m0, s37
	s_nop 0
	global_load_lds_dwordx4 v[210:211], off
	s_waitcnt vmcnt(8)
	s_waitcnt lgkmcnt(0)
	s_barrier
	s_waitcnt lgkmcnt(0)
	v_mfma_f32_16x16x32_f16 v[60:63], v[146:149], v[178:181], v[60:63]
	v_mfma_f32_16x16x32_f16 v[56:59], v[154:157], v[178:181], v[56:59]
	v_mfma_f32_16x16x32_f16 v[44:47], v[146:149], v[186:189], v[44:47]
	v_mfma_f32_16x16x32_f16 v[40:43], v[154:157], v[186:189], v[40:43]
	v_mfma_f32_16x16x32_f16 v[28:31], v[146:149], v[194:197], v[28:31]
	v_mfma_f32_16x16x32_f16 v[24:27], v[154:157], v[194:197], v[24:27]
	v_mfma_f32_16x16x32_f16 v[12:15], v[146:149], v[202:205], v[12:15]
	v_mfma_f32_16x16x32_f16 v[8:11], v[154:157], v[202:205], v[8:11]
	v_mfma_f32_16x16x32_f16 v[60:63], v[150:153], v[182:185], v[60:63]
	v_mfma_f32_16x16x32_f16 v[56:59], v[158:161], v[182:185], v[56:59]
	v_mfma_f32_16x16x32_f16 v[44:47], v[150:153], v[190:193], v[44:47]
	v_mfma_f32_16x16x32_f16 v[40:43], v[158:161], v[190:193], v[40:43]
	v_mfma_f32_16x16x32_f16 v[28:31], v[150:153], v[198:201], v[28:31]
	v_mfma_f32_16x16x32_f16 v[24:27], v[158:161], v[198:201], v[24:27]
	v_mfma_f32_16x16x32_f16 v[12:15], v[150:153], v[206:209], v[12:15]
	v_mfma_f32_16x16x32_f16 v[8:11], v[158:161], v[206:209], v[8:11]
	v_mfma_f32_16x16x32_f16 v[52:55], v[162:165], v[178:181], v[52:55]
	v_mfma_f32_16x16x32_f16 v[48:51], v[170:173], v[178:181], v[48:51]
	v_mfma_f32_16x16x32_f16 v[36:39], v[162:165], v[186:189], v[36:39]
	v_mfma_f32_16x16x32_f16 v[32:35], v[170:173], v[186:189], v[32:35]
	v_mfma_f32_16x16x32_f16 v[20:23], v[162:165], v[194:197], v[20:23]
	v_mfma_f32_16x16x32_f16 v[16:19], v[170:173], v[194:197], v[16:19]
	v_mfma_f32_16x16x32_f16 v[4:7], v[162:165], v[202:205], v[4:7]
	v_mfma_f32_16x16x32_f16 v[0:3], v[170:173], v[202:205], v[0:3]
	v_mfma_f32_16x16x32_f16 v[52:55], v[166:169], v[182:185], v[52:55]
	v_mfma_f32_16x16x32_f16 v[48:51], v[174:177], v[182:185], v[48:51]
	v_mfma_f32_16x16x32_f16 v[36:39], v[166:169], v[190:193], v[36:39]
	v_mfma_f32_16x16x32_f16 v[32:35], v[174:177], v[190:193], v[32:35]
	v_mfma_f32_16x16x32_f16 v[20:23], v[166:169], v[198:201], v[20:23]
	v_mfma_f32_16x16x32_f16 v[16:19], v[174:177], v[198:201], v[16:19]
	v_mfma_f32_16x16x32_f16 v[4:7], v[166:169], v[206:209], v[4:7]
	v_mfma_f32_16x16x32_f16 v[0:3], v[174:177], v[206:209], v[0:3]
	s_add_i32 s42, s42, 2
	s_add_u32 s14, s14, 0x100
	s_addc_u32 s15, s15, 0
	s_cmp_gt_u32 s42, 13
.LBB0_1232:
	s_barrier
	s_add_u32 s16, s38, s14
	s_addc_u32 s17, s39, s15
	s_add_u32 s16, s16, 0x13d00100
	s_addc_u32 s17, s17, 0
	s_add_u32 s43, s40, s14
	s_addc_u32 s44, s41, s15
	s_cmpk_eq_i32 s14, 0x700
	s_cselect_b32 s19, s11, s17
	s_cselect_b32 s18, s10, s16
	s_cselect_b32 s17, s13, s44
	s_cselect_b32 s16, s12, s43
	s_add_i32 s43, 0, 0x14000
	v_add_u32_e32 v158, s67, v144
	v_add_u32_e32 v174, s43, v144
	ds_read_b128 v[146:149], v158
	ds_read_b128 v[150:153], v158 offset:1024
	ds_read_b128 v[154:157], v158 offset:2048
	ds_read_b128 v[158:161], v158 offset:3072
	ds_read_b128 v[162:165], v174
	ds_read_b128 v[166:169], v174 offset:1024
	ds_read_b128 v[170:173], v174 offset:2048
	ds_read_b128 v[174:177], v174 offset:3072
	v_lshl_add_u64 v[210:211], v[136:137], 0, s[14:15]
	s_add_i32 m0, s30, 0xc000
	ds_read_b128 v[178:181], v145
	ds_read_b128 v[182:185], v145 offset:1024
	ds_read_b128 v[186:189], v145 offset:2048
	ds_read_b128 v[190:193], v145 offset:3072
	ds_read_b128 v[194:197], v145 offset:4096
	ds_read_b128 v[198:201], v145 offset:5120
	ds_read_b128 v[202:205], v145 offset:6144
	ds_read_b128 v[206:209], v145 offset:7168
	global_load_lds_dwordx4 v[210:211], off
	v_lshl_add_u64 v[210:211], v[138:139], 0, s[14:15]
	s_add_i32 m0, s30, 0xe000
	s_nop 0
	global_load_lds_dwordx4 v[210:211], off
	s_waitcnt vmcnt(8)
	s_waitcnt lgkmcnt(0)
	s_barrier
	s_waitcnt lgkmcnt(0)
	v_mfma_f32_16x16x32_f16 v[124:127], v[146:149], v[178:181], v[124:127]
	v_mfma_f32_16x16x32_f16 v[120:123], v[154:157], v[178:181], v[120:123]
	v_mfma_f32_16x16x32_f16 v[108:111], v[146:149], v[186:189], v[108:111]
	v_mfma_f32_16x16x32_f16 v[104:107], v[154:157], v[186:189], v[104:107]
	v_mfma_f32_16x16x32_f16 v[92:95], v[146:149], v[194:197], v[92:95]
	v_mfma_f32_16x16x32_f16 v[88:91], v[154:157], v[194:197], v[88:91]
	v_mfma_f32_16x16x32_f16 v[76:79], v[146:149], v[202:205], v[76:79]
	v_mfma_f32_16x16x32_f16 v[72:75], v[154:157], v[202:205], v[72:75]
	v_mfma_f32_16x16x32_f16 v[124:127], v[150:153], v[182:185], v[124:127]
	v_mfma_f32_16x16x32_f16 v[120:123], v[158:161], v[182:185], v[120:123]
	v_mfma_f32_16x16x32_f16 v[108:111], v[150:153], v[190:193], v[108:111]
	v_mfma_f32_16x16x32_f16 v[104:107], v[158:161], v[190:193], v[104:107]
	v_mfma_f32_16x16x32_f16 v[92:95], v[150:153], v[198:201], v[92:95]
	v_mfma_f32_16x16x32_f16 v[88:91], v[158:161], v[198:201], v[88:91]
	v_mfma_f32_16x16x32_f16 v[76:79], v[150:153], v[206:209], v[76:79]
	v_mfma_f32_16x16x32_f16 v[72:75], v[158:161], v[206:209], v[72:75]
	v_mfma_f32_16x16x32_f16 v[116:119], v[162:165], v[178:181], v[116:119]
	v_mfma_f32_16x16x32_f16 v[112:115], v[170:173], v[178:181], v[112:115]
	v_mfma_f32_16x16x32_f16 v[100:103], v[162:165], v[186:189], v[100:103]
	v_mfma_f32_16x16x32_f16 v[96:99], v[170:173], v[186:189], v[96:99]
	v_mfma_f32_16x16x32_f16 v[84:87], v[162:165], v[194:197], v[84:87]
	v_mfma_f32_16x16x32_f16 v[80:83], v[170:173], v[194:197], v[80:83]
	v_mfma_f32_16x16x32_f16 v[68:71], v[162:165], v[202:205], v[68:71]
	v_mfma_f32_16x16x32_f16 v[64:67], v[170:173], v[202:205], v[64:67]
	v_mfma_f32_16x16x32_f16 v[116:119], v[166:169], v[182:185], v[116:119]
	v_mfma_f32_16x16x32_f16 v[112:115], v[174:177], v[182:185], v[112:115]
	v_mfma_f32_16x16x32_f16 v[100:103], v[166:169], v[190:193], v[100:103]
	v_mfma_f32_16x16x32_f16 v[96:99], v[174:177], v[190:193], v[96:99]
	v_mfma_f32_16x16x32_f16 v[84:87], v[166:169], v[198:201], v[84:87]
	v_mfma_f32_16x16x32_f16 v[80:83], v[174:177], v[198:201], v[80:83]
	v_mfma_f32_16x16x32_f16 v[68:71], v[166:169], v[206:209], v[68:71]
	v_mfma_f32_16x16x32_f16 v[64:67], v[174:177], v[206:209], v[64:67]
	s_barrier
	s_add_i32 s44, s67, s66
	v_lshl_add_u64 v[210:211], s[16:17], 0, v[128:129]
	s_mov_b32 m0, s44
	ds_read_b128 v[178:181], v145 offset:16384
	ds_read_b128 v[182:185], v145 offset:17408
	ds_read_b128 v[186:189], v145 offset:18432
	ds_read_b128 v[190:193], v145 offset:19456
	ds_read_b128 v[194:197], v145 offset:20480
	ds_read_b128 v[198:201], v145 offset:21504
	ds_read_b128 v[202:205], v145 offset:22528
	ds_read_b128 v[206:209], v145 offset:23552
	global_load_lds_dwordx4 v[210:211], off
	s_add_i32 m0, s44, 0x2000
	s_add_u32 s44, s16, 0x40000
	v_lshl_add_u64 v[212:213], s[16:17], 0, v[134:135]
	s_addc_u32 s45, s17, 0
	s_add_i32 s43, s43, s66
	global_load_lds_dwordx4 v[212:213], off
	v_lshl_add_u64 v[214:215], s[44:45], 0, v[128:129]
	s_mov_b32 m0, s43
	v_lshl_add_u64 v[216:217], s[18:19], 0, v[132:133]
	global_load_lds_dwordx4 v[214:215], off
	v_lshl_add_u64 v[214:215], s[44:45], 0, v[134:135]
	s_add_i32 m0, s43, 0x2000
	s_nop 0
	global_load_lds_dwordx4 v[214:215], off
	v_lshl_add_u64 v[214:215], s[18:19], 0, v[130:131]
	s_mov_b32 m0, s30
	s_nop 0
	global_load_lds_dwordx4 v[214:215], off
	s_mov_b32 m0, s31
	s_nop 0
	global_load_lds_dwordx4 v[216:217], off
	s_waitcnt vmcnt(8)
	s_waitcnt lgkmcnt(0)
	s_barrier
	s_waitcnt lgkmcnt(0)
	v_mfma_f32_16x16x32_f16 v[60:63], v[146:149], v[178:181], v[60:63]
	v_mfma_f32_16x16x32_f16 v[56:59], v[154:157], v[178:181], v[56:59]
	v_mfma_f32_16x16x32_f16 v[44:47], v[146:149], v[186:189], v[44:47]
	v_mfma_f32_16x16x32_f16 v[40:43], v[154:157], v[186:189], v[40:43]
	v_mfma_f32_16x16x32_f16 v[28:31], v[146:149], v[194:197], v[28:31]
	v_mfma_f32_16x16x32_f16 v[24:27], v[154:157], v[194:197], v[24:27]
	v_mfma_f32_16x16x32_f16 v[12:15], v[146:149], v[202:205], v[12:15]
	v_mfma_f32_16x16x32_f16 v[8:11], v[154:157], v[202:205], v[8:11]
	v_mfma_f32_16x16x32_f16 v[60:63], v[150:153], v[182:185], v[60:63]
	v_mfma_f32_16x16x32_f16 v[56:59], v[158:161], v[182:185], v[56:59]
	v_mfma_f32_16x16x32_f16 v[44:47], v[150:153], v[190:193], v[44:47]
	v_mfma_f32_16x16x32_f16 v[40:43], v[158:161], v[190:193], v[40:43]
	v_mfma_f32_16x16x32_f16 v[28:31], v[150:153], v[198:201], v[28:31]
	v_mfma_f32_16x16x32_f16 v[24:27], v[158:161], v[198:201], v[24:27]
	v_mfma_f32_16x16x32_f16 v[12:15], v[150:153], v[206:209], v[12:15]
	v_mfma_f32_16x16x32_f16 v[8:11], v[158:161], v[206:209], v[8:11]
	v_mfma_f32_16x16x32_f16 v[52:55], v[162:165], v[178:181], v[52:55]
	v_mfma_f32_16x16x32_f16 v[48:51], v[170:173], v[178:181], v[48:51]
	v_mfma_f32_16x16x32_f16 v[36:39], v[162:165], v[186:189], v[36:39]
	v_mfma_f32_16x16x32_f16 v[32:35], v[170:173], v[186:189], v[32:35]
	v_mfma_f32_16x16x32_f16 v[20:23], v[162:165], v[194:197], v[20:23]
	v_mfma_f32_16x16x32_f16 v[16:19], v[170:173], v[194:197], v[16:19]
	v_mfma_f32_16x16x32_f16 v[4:7], v[162:165], v[202:205], v[4:7]
	v_mfma_f32_16x16x32_f16 v[0:3], v[170:173], v[202:205], v[0:3]
	v_mfma_f32_16x16x32_f16 v[52:55], v[166:169], v[182:185], v[52:55]
	v_mfma_f32_16x16x32_f16 v[48:51], v[174:177], v[182:185], v[48:51]
	v_mfma_f32_16x16x32_f16 v[36:39], v[166:169], v[190:193], v[36:39]
	v_mfma_f32_16x16x32_f16 v[32:35], v[174:177], v[190:193], v[32:35]
	v_mfma_f32_16x16x32_f16 v[20:23], v[166:169], v[198:201], v[20:23]
	v_mfma_f32_16x16x32_f16 v[16:19], v[174:177], v[198:201], v[16:19]
	v_mfma_f32_16x16x32_f16 v[4:7], v[166:169], v[206:209], v[4:7]
	v_mfma_f32_16x16x32_f16 v[0:3], v[174:177], v[206:209], v[0:3]
	s_barrier
	s_add_i32 s43, 0, 0x18000
	s_add_i32 s44, 0, 0x1c000
	v_add_u32_e32 v158, s43, v144
	v_add_u32_e32 v174, s44, v144
	ds_read_b128 v[146:149], v158
	ds_read_b128 v[150:153], v158 offset:1024
	ds_read_b128 v[154:157], v158 offset:2048
	ds_read_b128 v[158:161], v158 offset:3072
	ds_read_b128 v[162:165], v174
	ds_read_b128 v[166:169], v174 offset:1024
	ds_read_b128 v[170:173], v174 offset:2048
	ds_read_b128 v[174:177], v174 offset:3072
	s_add_u32 s18, s18, 0x40000
	s_addc_u32 s19, s19, 0
	s_mov_b32 m0, s34
	v_lshl_add_u64 v[218:219], s[18:19], 0, v[130:131]
	ds_read_b128 v[178:181], v145 offset:32768
	ds_read_b128 v[182:185], v145 offset:33792
	ds_read_b128 v[186:189], v145 offset:34816
	ds_read_b128 v[190:193], v145 offset:35840
	ds_read_b128 v[194:197], v145 offset:36864
	ds_read_b128 v[198:201], v145 offset:37888
	ds_read_b128 v[202:205], v145 offset:38912
	ds_read_b128 v[206:209], v145 offset:39936
	global_load_lds_dwordx4 v[218:219], off
	v_lshl_add_u64 v[218:219], s[18:19], 0, v[132:133]
	s_mov_b32 m0, s35
	s_nop 0
	global_load_lds_dwordx4 v[218:219], off
	s_waitcnt vmcnt(8)
	s_waitcnt lgkmcnt(0)
	s_barrier
	s_waitcnt lgkmcnt(0)
	v_mfma_f32_16x16x32_f16 v[124:127], v[146:149], v[178:181], v[124:127]
	v_mfma_f32_16x16x32_f16 v[120:123], v[154:157], v[178:181], v[120:123]
	v_mfma_f32_16x16x32_f16 v[108:111], v[146:149], v[186:189], v[108:111]
	v_mfma_f32_16x16x32_f16 v[104:107], v[154:157], v[186:189], v[104:107]
	v_mfma_f32_16x16x32_f16 v[92:95], v[146:149], v[194:197], v[92:95]
	v_mfma_f32_16x16x32_f16 v[88:91], v[154:157], v[194:197], v[88:91]
	v_mfma_f32_16x16x32_f16 v[76:79], v[146:149], v[202:205], v[76:79]
	v_mfma_f32_16x16x32_f16 v[72:75], v[154:157], v[202:205], v[72:75]
	v_mfma_f32_16x16x32_f16 v[124:127], v[150:153], v[182:185], v[124:127]
	v_mfma_f32_16x16x32_f16 v[120:123], v[158:161], v[182:185], v[120:123]
	v_mfma_f32_16x16x32_f16 v[108:111], v[150:153], v[190:193], v[108:111]
	v_mfma_f32_16x16x32_f16 v[104:107], v[158:161], v[190:193], v[104:107]
	v_mfma_f32_16x16x32_f16 v[92:95], v[150:153], v[198:201], v[92:95]
	v_mfma_f32_16x16x32_f16 v[88:91], v[158:161], v[198:201], v[88:91]
	v_mfma_f32_16x16x32_f16 v[76:79], v[150:153], v[206:209], v[76:79]
	v_mfma_f32_16x16x32_f16 v[72:75], v[158:161], v[206:209], v[72:75]
	v_mfma_f32_16x16x32_f16 v[116:119], v[162:165], v[178:181], v[116:119]
	v_mfma_f32_16x16x32_f16 v[112:115], v[170:173], v[178:181], v[112:115]
	v_mfma_f32_16x16x32_f16 v[100:103], v[162:165], v[186:189], v[100:103]
	v_mfma_f32_16x16x32_f16 v[96:99], v[170:173], v[186:189], v[96:99]
	v_mfma_f32_16x16x32_f16 v[84:87], v[162:165], v[194:197], v[84:87]
	v_mfma_f32_16x16x32_f16 v[80:83], v[170:173], v[194:197], v[80:83]
	v_mfma_f32_16x16x32_f16 v[68:71], v[162:165], v[202:205], v[68:71]
	v_mfma_f32_16x16x32_f16 v[64:67], v[170:173], v[202:205], v[64:67]
	v_mfma_f32_16x16x32_f16 v[116:119], v[166:169], v[182:185], v[116:119]
	v_mfma_f32_16x16x32_f16 v[112:115], v[174:177], v[182:185], v[112:115]
	v_mfma_f32_16x16x32_f16 v[100:103], v[166:169], v[190:193], v[100:103]
	v_mfma_f32_16x16x32_f16 v[96:99], v[174:177], v[190:193], v[96:99]
	v_mfma_f32_16x16x32_f16 v[84:87], v[166:169], v[198:201], v[84:87]
	v_mfma_f32_16x16x32_f16 v[80:83], v[174:177], v[198:201], v[80:83]
	v_mfma_f32_16x16x32_f16 v[68:71], v[166:169], v[206:209], v[68:71]
	v_mfma_f32_16x16x32_f16 v[64:67], v[174:177], v[206:209], v[64:67]
	s_barrier
	s_add_i32 s18, s43, s66
	v_lshl_add_u64 v[210:211], v[210:211], 0, s[6:7]
	s_mov_b32 m0, s18
	ds_read_b128 v[178:181], v145 offset:49152
	ds_read_b128 v[182:185], v145 offset:50176
	ds_read_b128 v[186:189], v145 offset:51200
	ds_read_b128 v[190:193], v145 offset:52224
	ds_read_b128 v[194:197], v145 offset:53248
	ds_read_b128 v[198:201], v145 offset:54272
	ds_read_b128 v[202:205], v145 offset:55296
	ds_read_b128 v[206:209], v145 offset:56320
	global_load_lds_dwordx4 v[210:211], off
	s_add_i32 m0, s18, 0x2000
	s_add_u32 s16, s16, 0x40080
	v_lshl_add_u64 v[210:211], v[212:213], 0, s[6:7]
	s_addc_u32 s17, s17, 0
	s_add_i32 s18, s44, s66
	global_load_lds_dwordx4 v[210:211], off
	v_lshl_add_u64 v[210:211], s[16:17], 0, v[128:129]
	s_mov_b32 m0, s18
	s_nop 0
	global_load_lds_dwordx4 v[210:211], off
	v_lshl_add_u64 v[210:211], s[16:17], 0, v[134:135]
	s_add_i32 m0, s18, 0x2000
	s_nop 0
	global_load_lds_dwordx4 v[210:211], off
	v_lshl_add_u64 v[210:211], v[214:215], 0, s[6:7]
	s_mov_b32 m0, s36
	s_nop 0
	global_load_lds_dwordx4 v[210:211], off
	v_lshl_add_u64 v[210:211], v[216:217], 0, s[6:7]
	s_mov_b32 m0, s37
	s_nop 0
	global_load_lds_dwordx4 v[210:211], off
	s_waitcnt vmcnt(8)
	s_waitcnt lgkmcnt(0)
	s_barrier
	s_waitcnt lgkmcnt(0)
	v_mfma_f32_16x16x32_f16 v[60:63], v[146:149], v[178:181], v[60:63]
	v_mfma_f32_16x16x32_f16 v[56:59], v[154:157], v[178:181], v[56:59]
	v_mfma_f32_16x16x32_f16 v[44:47], v[146:149], v[186:189], v[44:47]
	v_mfma_f32_16x16x32_f16 v[40:43], v[154:157], v[186:189], v[40:43]
	v_mfma_f32_16x16x32_f16 v[28:31], v[146:149], v[194:197], v[28:31]
	v_mfma_f32_16x16x32_f16 v[24:27], v[154:157], v[194:197], v[24:27]
	v_mfma_f32_16x16x32_f16 v[12:15], v[146:149], v[202:205], v[12:15]
	v_mfma_f32_16x16x32_f16 v[8:11], v[154:157], v[202:205], v[8:11]
	v_mfma_f32_16x16x32_f16 v[60:63], v[150:153], v[182:185], v[60:63]
	v_mfma_f32_16x16x32_f16 v[56:59], v[158:161], v[182:185], v[56:59]
	v_mfma_f32_16x16x32_f16 v[44:47], v[150:153], v[190:193], v[44:47]
	v_mfma_f32_16x16x32_f16 v[40:43], v[158:161], v[190:193], v[40:43]
	v_mfma_f32_16x16x32_f16 v[28:31], v[150:153], v[198:201], v[28:31]
	v_mfma_f32_16x16x32_f16 v[24:27], v[158:161], v[198:201], v[24:27]
	v_mfma_f32_16x16x32_f16 v[12:15], v[150:153], v[206:209], v[12:15]
	v_mfma_f32_16x16x32_f16 v[8:11], v[158:161], v[206:209], v[8:11]
	v_mfma_f32_16x16x32_f16 v[52:55], v[162:165], v[178:181], v[52:55]
	v_mfma_f32_16x16x32_f16 v[48:51], v[170:173], v[178:181], v[48:51]
	v_mfma_f32_16x16x32_f16 v[36:39], v[162:165], v[186:189], v[36:39]
	v_mfma_f32_16x16x32_f16 v[32:35], v[170:173], v[186:189], v[32:35]
	v_mfma_f32_16x16x32_f16 v[20:23], v[162:165], v[194:197], v[20:23]
	v_mfma_f32_16x16x32_f16 v[16:19], v[170:173], v[194:197], v[16:19]
	v_mfma_f32_16x16x32_f16 v[4:7], v[162:165], v[202:205], v[4:7]
	v_mfma_f32_16x16x32_f16 v[0:3], v[170:173], v[202:205], v[0:3]
	v_mfma_f32_16x16x32_f16 v[52:55], v[166:169], v[182:185], v[52:55]
	v_mfma_f32_16x16x32_f16 v[48:51], v[174:177], v[182:185], v[48:51]
	v_mfma_f32_16x16x32_f16 v[36:39], v[166:169], v[190:193], v[36:39]
	v_mfma_f32_16x16x32_f16 v[32:35], v[174:177], v[190:193], v[32:35]
	v_mfma_f32_16x16x32_f16 v[20:23], v[166:169], v[198:201], v[20:23]
	v_mfma_f32_16x16x32_f16 v[16:19], v[174:177], v[198:201], v[16:19]
	v_mfma_f32_16x16x32_f16 v[4:7], v[166:169], v[206:209], v[4:7]
	v_mfma_f32_16x16x32_f16 v[0:3], v[174:177], v[206:209], v[0:3]
	s_add_i32 s42, s42, 2
	s_add_u32 s14, s14, 0x100
	s_addc_u32 s15, s15, 0
	s_cmp_gt_u32 s42, 13
	s_cbranch_scc0 .LBB0_1232
	s_barrier
	s_and_b64 vcc, exec, s[26:27]
	s_cbranch_vccz .LBB0_1235
	s_barrier

.LBB0_1328:
	v_bfe_u32 v144, v1, 4, 2
	v_and_b32_e32 v7, 15, v1
	v_lshlrev_b32_e32 v145, 4, v144
	v_lshlrev_b32_e32 v1, 2, v1
	v_or_b32_e32 v146, s54, v7
	v_lshl_or_b32 v7, v7, 6, v145
	v_and_b32_e32 v1, 32, v1
	v_bitop3_b32 v147, v7, s56, v1 bitop3:0xde
	v_lshlrev_b32_e32 v1, 14, v0
	s_add_u32 s41, s76, s26
	v_and_b32_e32 v1, 0xffff8000, v1
	s_addc_u32 s42, s77, s27
	v_lshl_add_u32 v1, v2, 11, v1
	v_and_b32_e32 v0, 1, v0
	v_lshl_or_b32 v0, v0, 6, v1
	s_add_u32 s26, s60, s26
	v_lshl_add_u32 v0, v3, 1, v0
	v_mov_b32_e32 v1, v129
	s_addc_u32 s27, s61, s27
	v_lshl_add_u64 v[136:137], s[26:27], 0, v[0:1]
	v_lshlrev_b32_e32 v0, 14, v4
	v_and_b32_e32 v0, 0xffff8000, v0
	v_lshl_add_u32 v0, v5, 11, v0
	v_and_b32_e32 v1, 1, v4
	v_lshlrev_b32_e32 v8, 6, v146
	v_lshlrev_b32_e32 v9, 2, v146
	v_lshl_or_b32 v0, v1, 6, v0
	v_and_or_b32 v8, v8, s66, v145
	v_and_b32_e32 v9, 32, v9
	s_waitcnt vmcnt(8)
	s_barrier
	s_waitcnt vmcnt(6)
	v_lshl_add_u32 v0, v6, 1, v0
	v_mov_b32_e32 v1, v129
	v_bitop3_b32 v7, v8, s55, v9 bitop3:0xde
	v_lshl_add_u64 v[138:139], s[26:27], 0, v[0:1]
	s_add_u32 s43, s62, s28
	s_addc_u32 s44, s63, 0
	s_mov_b32 s45, -2
	s_mov_b64 s[26:27], 0
	v_add_u32_e32 v148, 0, v7
	s_barrier
	s_add_u32 s28, s41, s26
	s_addc_u32 s29, s42, s27
	s_add_u32 s28, s28, 0x7a00100
	s_addc_u32 s29, s29, 0
	s_add_u32 s46, s43, s26
	s_addc_u32 s47, s44, s27
	s_add_i32 s48, 0, 0x10000
	s_cmpk_eq_i32 s26, 0x700
	s_cselect_b32 s31, s25, s29
	s_cselect_b32 s30, s24, s28
	v_add_u32_e32 v149, s48, v147
	s_cselect_b32 s29, s1, s47
	s_cselect_b32 s28, s0, s46
	s_add_i32 s49, 0, 0x14000
	ds_read_b128 v[150:153], v149
	ds_read_b128 v[154:157], v149 offset:1024
	ds_read_b128 v[158:161], v149 offset:2048
	ds_read_b128 v[162:165], v149 offset:3072
	v_add_u32_e32 v149, s49, v147
	ds_read_b128 v[166:169], v149
	ds_read_b128 v[170:173], v149 offset:1024
	ds_read_b128 v[174:177], v149 offset:2048
	ds_read_b128 v[178:181], v149 offset:3072
	v_lshl_add_u64 v[214:215], v[136:137], 0, s[26:27]
	s_add_i32 m0, s35, 0xc000
	ds_read_b128 v[182:185], v148
	ds_read_b128 v[186:189], v148 offset:1024
	ds_read_b128 v[190:193], v148 offset:2048
	ds_read_b128 v[194:197], v148 offset:3072
	ds_read_b128 v[198:201], v148 offset:4096
	ds_read_b128 v[202:205], v148 offset:5120
	ds_read_b128 v[206:209], v148 offset:6144
	ds_read_b128 v[210:213], v148 offset:7168
	global_load_lds_dwordx4 v[214:215], off
	v_lshl_add_u64 v[214:215], v[138:139], 0, s[26:27]
	s_add_i32 m0, s35, 0xe000
	s_nop 0
	global_load_lds_dwordx4 v[214:215], off
	s_waitcnt vmcnt(8)
	s_waitcnt lgkmcnt(0)
	s_barrier
	s_waitcnt lgkmcnt(0)
	v_mfma_f32_16x16x32_f16 v[124:127], v[150:153], v[182:185], 0
	v_mfma_f32_16x16x32_f16 v[120:123], v[158:161], v[182:185], 0
	v_mfma_f32_16x16x32_f16 v[108:111], v[150:153], v[190:193], 0
	v_mfma_f32_16x16x32_f16 v[104:107], v[158:161], v[190:193], 0
	v_mfma_f32_16x16x32_f16 v[92:95], v[150:153], v[198:201], 0
	v_mfma_f32_16x16x32_f16 v[88:91], v[158:161], v[198:201], 0
	v_mfma_f32_16x16x32_f16 v[76:79], v[150:153], v[206:209], 0
	v_mfma_f32_16x16x32_f16 v[72:75], v[158:161], v[206:209], 0
	v_mfma_f32_16x16x32_f16 v[124:127], v[154:157], v[186:189], v[124:127]
	v_mfma_f32_16x16x32_f16 v[120:123], v[162:165], v[186:189], v[120:123]
	v_mfma_f32_16x16x32_f16 v[108:111], v[154:157], v[194:197], v[108:111]
	v_mfma_f32_16x16x32_f16 v[104:107], v[162:165], v[194:197], v[104:107]
	v_mfma_f32_16x16x32_f16 v[92:95], v[154:157], v[202:205], v[92:95]
	v_mfma_f32_16x16x32_f16 v[88:91], v[162:165], v[202:205], v[88:91]
	v_mfma_f32_16x16x32_f16 v[76:79], v[154:157], v[210:213], v[76:79]
	v_mfma_f32_16x16x32_f16 v[72:75], v[162:165], v[210:213], v[72:75]
	v_mfma_f32_16x16x32_f16 v[116:119], v[166:169], v[182:185], 0
	v_mfma_f32_16x16x32_f16 v[112:115], v[174:177], v[182:185], 0
	v_mfma_f32_16x16x32_f16 v[100:103], v[166:169], v[190:193], 0
	v_mfma_f32_16x16x32_f16 v[96:99], v[174:177], v[190:193], 0
	v_mfma_f32_16x16x32_f16 v[84:87], v[166:169], v[198:201], 0
	v_mfma_f32_16x16x32_f16 v[80:83], v[174:177], v[198:201], 0
	v_mfma_f32_16x16x32_f16 v[68:71], v[166:169], v[206:209], 0
	v_mfma_f32_16x16x32_f16 v[64:67], v[174:177], v[206:209], 0
	v_mfma_f32_16x16x32_f16 v[116:119], v[170:173], v[186:189], v[116:119]
	v_mfma_f32_16x16x32_f16 v[112:115], v[178:181], v[186:189], v[112:115]
	v_mfma_f32_16x16x32_f16 v[100:103], v[170:173], v[194:197], v[100:103]
	v_mfma_f32_16x16x32_f16 v[96:99], v[178:181], v[194:197], v[96:99]
	v_mfma_f32_16x16x32_f16 v[84:87], v[170:173], v[202:205], v[84:87]
	v_mfma_f32_16x16x32_f16 v[80:83], v[178:181], v[202:205], v[80:83]
	v_mfma_f32_16x16x32_f16 v[68:71], v[170:173], v[210:213], v[68:71]
	v_mfma_f32_16x16x32_f16 v[64:67], v[178:181], v[210:213], v[64:67]
	s_barrier
	s_add_i32 s46, s48, s53
	v_lshl_add_u64 v[214:215], s[28:29], 0, v[128:129]
	s_mov_b32 m0, s46
	ds_read_b128 v[182:185], v148 offset:16384
	ds_read_b128 v[186:189], v148 offset:17408
	ds_read_b128 v[190:193], v148 offset:18432
	ds_read_b128 v[194:197], v148 offset:19456
	ds_read_b128 v[198:201], v148 offset:20480
	ds_read_b128 v[202:205], v148 offset:21504
	ds_read_b128 v[206:209], v148 offset:22528
	ds_read_b128 v[210:213], v148 offset:23552
	global_load_lds_dwordx4 v[214:215], off
	s_add_i32 m0, s46, 0x2000
	s_add_u32 s46, s28, 0x40000
	v_lshl_add_u64 v[216:217], s[28:29], 0, v[134:135]
	s_addc_u32 s47, s29, 0
	s_add_i32 s48, s49, s53
	global_load_lds_dwordx4 v[216:217], off
	v_lshl_add_u64 v[218:219], s[46:47], 0, v[128:129]
	s_mov_b32 m0, s48
	v_lshl_add_u64 v[220:221], s[30:31], 0, v[132:133]
	global_load_lds_dwordx4 v[218:219], off
	v_lshl_add_u64 v[218:219], s[46:47], 0, v[134:135]
	s_add_i32 m0, s48, 0x2000
	s_nop 0
	global_load_lds_dwordx4 v[218:219], off
	v_lshl_add_u64 v[218:219], s[30:31], 0, v[130:131]
	s_mov_b32 m0, s35
	s_nop 0
	global_load_lds_dwordx4 v[218:219], off
	s_mov_b32 m0, s36
	s_nop 0
	global_load_lds_dwordx4 v[220:221], off
	s_waitcnt vmcnt(8)
	s_waitcnt lgkmcnt(0)
	s_barrier
	s_waitcnt lgkmcnt(0)
	v_mfma_f32_16x16x32_f16 v[60:63], v[150:153], v[182:185], 0
	v_mfma_f32_16x16x32_f16 v[56:59], v[158:161], v[182:185], 0
	v_mfma_f32_16x16x32_f16 v[44:47], v[150:153], v[190:193], 0
	v_mfma_f32_16x16x32_f16 v[40:43], v[158:161], v[190:193], 0
	v_mfma_f32_16x16x32_f16 v[28:31], v[150:153], v[198:201], 0
	v_mfma_f32_16x16x32_f16 v[24:27], v[158:161], v[198:201], 0
	v_mfma_f32_16x16x32_f16 v[12:15], v[150:153], v[206:209], 0
	v_mfma_f32_16x16x32_f16 v[8:11], v[158:161], v[206:209], 0
	v_mfma_f32_16x16x32_f16 v[60:63], v[154:157], v[186:189], v[60:63]
	v_mfma_f32_16x16x32_f16 v[56:59], v[162:165], v[186:189], v[56:59]
	v_mfma_f32_16x16x32_f16 v[44:47], v[154:157], v[194:197], v[44:47]
	v_mfma_f32_16x16x32_f16 v[40:43], v[162:165], v[194:197], v[40:43]
	v_mfma_f32_16x16x32_f16 v[28:31], v[154:157], v[202:205], v[28:31]
	v_mfma_f32_16x16x32_f16 v[24:27], v[162:165], v[202:205], v[24:27]
	v_mfma_f32_16x16x32_f16 v[12:15], v[154:157], v[210:213], v[12:15]
	v_mfma_f32_16x16x32_f16 v[8:11], v[162:165], v[210:213], v[8:11]
	v_mfma_f32_16x16x32_f16 v[52:55], v[166:169], v[182:185], 0
	v_mfma_f32_16x16x32_f16 v[48:51], v[174:177], v[182:185], 0
	v_mfma_f32_16x16x32_f16 v[36:39], v[166:169], v[190:193], 0
	v_mfma_f32_16x16x32_f16 v[32:35], v[174:177], v[190:193], 0
	v_mfma_f32_16x16x32_f16 v[20:23], v[166:169], v[198:201], 0
	v_mfma_f32_16x16x32_f16 v[16:19], v[174:177], v[198:201], 0
	v_mfma_f32_16x16x32_f16 v[4:7], v[166:169], v[206:209], 0
	v_mfma_f32_16x16x32_f16 v[0:3], v[174:177], v[206:209], 0
	v_mfma_f32_16x16x32_f16 v[52:55], v[170:173], v[186:189], v[52:55]
	v_mfma_f32_16x16x32_f16 v[48:51], v[178:181], v[186:189], v[48:51]
	v_mfma_f32_16x16x32_f16 v[36:39], v[170:173], v[194:197], v[36:39]
	v_mfma_f32_16x16x32_f16 v[32:35], v[178:181], v[194:197], v[32:35]
	v_mfma_f32_16x16x32_f16 v[20:23], v[170:173], v[202:205], v[20:23]
	v_mfma_f32_16x16x32_f16 v[16:19], v[178:181], v[202:205], v[16:19]
	v_mfma_f32_16x16x32_f16 v[4:7], v[170:173], v[210:213], v[4:7]
	v_mfma_f32_16x16x32_f16 v[0:3], v[178:181], v[210:213], v[0:3]
	s_barrier
	s_add_i32 s46, 0, 0x18000
	v_add_u32_e32 v149, s46, v147
	s_add_i32 s47, 0, 0x1c000
	ds_read_b128 v[150:153], v149
	ds_read_b128 v[154:157], v149 offset:1024
	ds_read_b128 v[158:161], v149 offset:2048
	ds_read_b128 v[162:165], v149 offset:3072
	v_add_u32_e32 v149, s47, v147
	ds_read_b128 v[166:169], v149
	ds_read_b128 v[170:173], v149 offset:1024
	ds_read_b128 v[174:177], v149 offset:2048
	ds_read_b128 v[178:181], v149 offset:3072
	s_add_u32 s30, s30, 0x40000
	s_addc_u32 s31, s31, 0
	s_mov_b32 m0, s37
	v_lshl_add_u64 v[222:223], s[30:31], 0, v[130:131]
	ds_read_b128 v[182:185], v148 offset:32768
	ds_read_b128 v[186:189], v148 offset:33792
	ds_read_b128 v[190:193], v148 offset:34816
	ds_read_b128 v[194:197], v148 offset:35840
	ds_read_b128 v[198:201], v148 offset:36864
	ds_read_b128 v[202:205], v148 offset:37888
	ds_read_b128 v[206:209], v148 offset:38912
	ds_read_b128 v[210:213], v148 offset:39936
	global_load_lds_dwordx4 v[222:223], off
	v_lshl_add_u64 v[222:223], s[30:31], 0, v[132:133]
	s_mov_b32 m0, s38
	s_nop 0
	global_load_lds_dwordx4 v[222:223], off
	s_waitcnt vmcnt(8)
	s_waitcnt lgkmcnt(0)
	s_barrier
	s_waitcnt lgkmcnt(0)
	v_mfma_f32_16x16x32_f16 v[124:127], v[150:153], v[182:185], v[124:127]
	v_mfma_f32_16x16x32_f16 v[120:123], v[158:161], v[182:185], v[120:123]
	v_mfma_f32_16x16x32_f16 v[108:111], v[150:153], v[190:193], v[108:111]
	v_mfma_f32_16x16x32_f16 v[104:107], v[158:161], v[190:193], v[104:107]
	v_mfma_f32_16x16x32_f16 v[92:95], v[150:153], v[198:201], v[92:95]
	v_mfma_f32_16x16x32_f16 v[88:91], v[158:161], v[198:201], v[88:91]
	v_mfma_f32_16x16x32_f16 v[76:79], v[150:153], v[206:209], v[76:79]
	v_mfma_f32_16x16x32_f16 v[72:75], v[158:161], v[206:209], v[72:75]
	v_mfma_f32_16x16x32_f16 v[124:127], v[154:157], v[186:189], v[124:127]
	v_mfma_f32_16x16x32_f16 v[120:123], v[162:165], v[186:189], v[120:123]
	v_mfma_f32_16x16x32_f16 v[108:111], v[154:157], v[194:197], v[108:111]
	v_mfma_f32_16x16x32_f16 v[104:107], v[162:165], v[194:197], v[104:107]
	v_mfma_f32_16x16x32_f16 v[92:95], v[154:157], v[202:205], v[92:95]
	v_mfma_f32_16x16x32_f16 v[88:91], v[162:165], v[202:205], v[88:91]
	v_mfma_f32_16x16x32_f16 v[76:79], v[154:157], v[210:213], v[76:79]
	v_mfma_f32_16x16x32_f16 v[72:75], v[162:165], v[210:213], v[72:75]
	v_mfma_f32_16x16x32_f16 v[116:119], v[166:169], v[182:185], v[116:119]
	v_mfma_f32_16x16x32_f16 v[112:115], v[174:177], v[182:185], v[112:115]
	v_mfma_f32_16x16x32_f16 v[100:103], v[166:169], v[190:193], v[100:103]
	v_mfma_f32_16x16x32_f16 v[96:99], v[174:177], v[190:193], v[96:99]
	v_mfma_f32_16x16x32_f16 v[84:87], v[166:169], v[198:201], v[84:87]
	v_mfma_f32_16x16x32_f16 v[80:83], v[174:177], v[198:201], v[80:83]
	v_mfma_f32_16x16x32_f16 v[68:71], v[166:169], v[206:209], v[68:71]
	v_mfma_f32_16x16x32_f16 v[64:67], v[174:177], v[206:209], v[64:67]
	v_mfma_f32_16x16x32_f16 v[116:119], v[170:173], v[186:189], v[116:119]
	v_mfma_f32_16x16x32_f16 v[112:115], v[178:181], v[186:189], v[112:115]
	v_mfma_f32_16x16x32_f16 v[100:103], v[170:173], v[194:197], v[100:103]
	v_mfma_f32_16x16x32_f16 v[96:99], v[178:181], v[194:197], v[96:99]
	v_mfma_f32_16x16x32_f16 v[84:87], v[170:173], v[202:205], v[84:87]
	v_mfma_f32_16x16x32_f16 v[80:83], v[178:181], v[202:205], v[80:83]
	v_mfma_f32_16x16x32_f16 v[68:71], v[170:173], v[210:213], v[68:71]
	v_mfma_f32_16x16x32_f16 v[64:67], v[178:181], v[210:213], v[64:67]
	s_barrier
	s_add_i32 s30, s46, s53
	v_lshl_add_u64 v[214:215], v[214:215], 0, s[20:21]
	s_mov_b32 m0, s30
	ds_read_b128 v[182:185], v148 offset:49152
	ds_read_b128 v[186:189], v148 offset:50176
	ds_read_b128 v[190:193], v148 offset:51200
	ds_read_b128 v[194:197], v148 offset:52224
	ds_read_b128 v[198:201], v148 offset:53248
	ds_read_b128 v[202:205], v148 offset:54272
	ds_read_b128 v[206:209], v148 offset:55296
	ds_read_b128 v[210:213], v148 offset:56320
	global_load_lds_dwordx4 v[214:215], off
	s_add_i32 m0, s30, 0x2000
	s_add_u32 s28, s28, 0x40080
	v_lshl_add_u64 v[214:215], v[216:217], 0, s[20:21]
	s_addc_u32 s29, s29, 0
	s_add_i32 s30, s47, s53
	global_load_lds_dwordx4 v[214:215], off
	v_lshl_add_u64 v[214:215], s[28:29], 0, v[128:129]
	s_mov_b32 m0, s30
	s_nop 0
	global_load_lds_dwordx4 v[214:215], off
	v_lshl_add_u64 v[214:215], s[28:29], 0, v[134:135]
	s_add_i32 m0, s30, 0x2000
	s_nop 0
	global_load_lds_dwordx4 v[214:215], off
	v_lshl_add_u64 v[214:215], v[218:219], 0, s[20:21]
	s_mov_b32 m0, s39
	s_nop 0
	global_load_lds_dwordx4 v[214:215], off
	v_lshl_add_u64 v[214:215], v[220:221], 0, s[20:21]
	s_mov_b32 m0, s40
	s_nop 0
	global_load_lds_dwordx4 v[214:215], off
	s_waitcnt vmcnt(8)
	s_waitcnt lgkmcnt(0)
	s_barrier
	s_waitcnt lgkmcnt(0)
	v_mfma_f32_16x16x32_f16 v[60:63], v[150:153], v[182:185], v[60:63]
	v_mfma_f32_16x16x32_f16 v[56:59], v[158:161], v[182:185], v[56:59]
	v_mfma_f32_16x16x32_f16 v[44:47], v[150:153], v[190:193], v[44:47]
	v_mfma_f32_16x16x32_f16 v[40:43], v[158:161], v[190:193], v[40:43]
	v_mfma_f32_16x16x32_f16 v[28:31], v[150:153], v[198:201], v[28:31]
	v_mfma_f32_16x16x32_f16 v[24:27], v[158:161], v[198:201], v[24:27]
	v_mfma_f32_16x16x32_f16 v[12:15], v[150:153], v[206:209], v[12:15]
	v_mfma_f32_16x16x32_f16 v[8:11], v[158:161], v[206:209], v[8:11]
	v_mfma_f32_16x16x32_f16 v[60:63], v[154:157], v[186:189], v[60:63]
	v_mfma_f32_16x16x32_f16 v[56:59], v[162:165], v[186:189], v[56:59]
	v_mfma_f32_16x16x32_f16 v[44:47], v[154:157], v[194:197], v[44:47]
	v_mfma_f32_16x16x32_f16 v[40:43], v[162:165], v[194:197], v[40:43]
	v_mfma_f32_16x16x32_f16 v[28:31], v[154:157], v[202:205], v[28:31]
	v_mfma_f32_16x16x32_f16 v[24:27], v[162:165], v[202:205], v[24:27]
	v_mfma_f32_16x16x32_f16 v[12:15], v[154:157], v[210:213], v[12:15]
	v_mfma_f32_16x16x32_f16 v[8:11], v[162:165], v[210:213], v[8:11]
	v_mfma_f32_16x16x32_f16 v[52:55], v[166:169], v[182:185], v[52:55]
	v_mfma_f32_16x16x32_f16 v[48:51], v[174:177], v[182:185], v[48:51]
	v_mfma_f32_16x16x32_f16 v[36:39], v[166:169], v[190:193], v[36:39]
	v_mfma_f32_16x16x32_f16 v[32:35], v[174:177], v[190:193], v[32:35]
	v_mfma_f32_16x16x32_f16 v[20:23], v[166:169], v[198:201], v[20:23]
	v_mfma_f32_16x16x32_f16 v[16:19], v[174:177], v[198:201], v[16:19]
	v_mfma_f32_16x16x32_f16 v[4:7], v[166:169], v[206:209], v[4:7]
	v_mfma_f32_16x16x32_f16 v[0:3], v[174:177], v[206:209], v[0:3]
	v_mfma_f32_16x16x32_f16 v[52:55], v[170:173], v[186:189], v[52:55]
	v_mfma_f32_16x16x32_f16 v[48:51], v[178:181], v[186:189], v[48:51]
	v_mfma_f32_16x16x32_f16 v[36:39], v[170:173], v[194:197], v[36:39]
	v_mfma_f32_16x16x32_f16 v[32:35], v[178:181], v[194:197], v[32:35]
	v_mfma_f32_16x16x32_f16 v[20:23], v[170:173], v[202:205], v[20:23]
	v_mfma_f32_16x16x32_f16 v[16:19], v[178:181], v[202:205], v[16:19]
	v_mfma_f32_16x16x32_f16 v[4:7], v[170:173], v[210:213], v[4:7]
	v_mfma_f32_16x16x32_f16 v[0:3], v[178:181], v[210:213], v[0:3]
	s_add_i32 s45, s45, 2
	s_add_u32 s26, s26, 0x100
	s_addc_u32 s27, s27, 0
	s_cmp_gt_u32 s45, 13
.LBB0_1329:
	s_barrier
	s_add_u32 s28, s41, s26
	s_addc_u32 s29, s42, s27
	s_add_u32 s28, s28, 0x7a00100
	s_addc_u32 s29, s29, 0
	s_add_u32 s46, s43, s26
	s_addc_u32 s47, s44, s27
	s_add_i32 s48, 0, 0x10000
	s_cmpk_eq_i32 s26, 0x700
	s_cselect_b32 s31, s25, s29
	s_cselect_b32 s30, s24, s28
	v_add_u32_e32 v149, s48, v147
	s_cselect_b32 s29, s1, s47
	s_cselect_b32 s28, s0, s46
	s_add_i32 s49, 0, 0x14000
	ds_read_b128 v[150:153], v149
	ds_read_b128 v[154:157], v149 offset:1024
	ds_read_b128 v[158:161], v149 offset:2048
	ds_read_b128 v[162:165], v149 offset:3072
	v_add_u32_e32 v149, s49, v147
	ds_read_b128 v[166:169], v149
	ds_read_b128 v[170:173], v149 offset:1024
	ds_read_b128 v[174:177], v149 offset:2048
	ds_read_b128 v[178:181], v149 offset:3072
	v_lshl_add_u64 v[214:215], v[136:137], 0, s[26:27]
	s_add_i32 m0, s35, 0xc000
	ds_read_b128 v[182:185], v148
	ds_read_b128 v[186:189], v148 offset:1024
	ds_read_b128 v[190:193], v148 offset:2048
	ds_read_b128 v[194:197], v148 offset:3072
	ds_read_b128 v[198:201], v148 offset:4096
	ds_read_b128 v[202:205], v148 offset:5120
	ds_read_b128 v[206:209], v148 offset:6144
	ds_read_b128 v[210:213], v148 offset:7168
	global_load_lds_dwordx4 v[214:215], off
	v_lshl_add_u64 v[214:215], v[138:139], 0, s[26:27]
	s_add_i32 m0, s35, 0xe000
	s_nop 0
	global_load_lds_dwordx4 v[214:215], off
	s_waitcnt vmcnt(8)
	s_waitcnt lgkmcnt(0)
	s_barrier
	s_waitcnt lgkmcnt(0)
	v_mfma_f32_16x16x32_f16 v[124:127], v[150:153], v[182:185], v[124:127]
	v_mfma_f32_16x16x32_f16 v[120:123], v[158:161], v[182:185], v[120:123]
	v_mfma_f32_16x16x32_f16 v[108:111], v[150:153], v[190:193], v[108:111]
	v_mfma_f32_16x16x32_f16 v[104:107], v[158:161], v[190:193], v[104:107]
	v_mfma_f32_16x16x32_f16 v[92:95], v[150:153], v[198:201], v[92:95]
	v_mfma_f32_16x16x32_f16 v[88:91], v[158:161], v[198:201], v[88:91]
	v_mfma_f32_16x16x32_f16 v[76:79], v[150:153], v[206:209], v[76:79]
	v_mfma_f32_16x16x32_f16 v[72:75], v[158:161], v[206:209], v[72:75]
	v_mfma_f32_16x16x32_f16 v[124:127], v[154:157], v[186:189], v[124:127]
	v_mfma_f32_16x16x32_f16 v[120:123], v[162:165], v[186:189], v[120:123]
	v_mfma_f32_16x16x32_f16 v[108:111], v[154:157], v[194:197], v[108:111]
	v_mfma_f32_16x16x32_f16 v[104:107], v[162:165], v[194:197], v[104:107]
	v_mfma_f32_16x16x32_f16 v[92:95], v[154:157], v[202:205], v[92:95]
	v_mfma_f32_16x16x32_f16 v[88:91], v[162:165], v[202:205], v[88:91]
	v_mfma_f32_16x16x32_f16 v[76:79], v[154:157], v[210:213], v[76:79]
	v_mfma_f32_16x16x32_f16 v[72:75], v[162:165], v[210:213], v[72:75]
	v_mfma_f32_16x16x32_f16 v[116:119], v[166:169], v[182:185], v[116:119]
	v_mfma_f32_16x16x32_f16 v[112:115], v[174:177], v[182:185], v[112:115]
	v_mfma_f32_16x16x32_f16 v[100:103], v[166:169], v[190:193], v[100:103]
	v_mfma_f32_16x16x32_f16 v[96:99], v[174:177], v[190:193], v[96:99]
	v_mfma_f32_16x16x32_f16 v[84:87], v[166:169], v[198:201], v[84:87]
	v_mfma_f32_16x16x32_f16 v[80:83], v[174:177], v[198:201], v[80:83]
	v_mfma_f32_16x16x32_f16 v[68:71], v[166:169], v[206:209], v[68:71]
	v_mfma_f32_16x16x32_f16 v[64:67], v[174:177], v[206:209], v[64:67]
	v_mfma_f32_16x16x32_f16 v[116:119], v[170:173], v[186:189], v[116:119]
	v_mfma_f32_16x16x32_f16 v[112:115], v[178:181], v[186:189], v[112:115]
	v_mfma_f32_16x16x32_f16 v[100:103], v[170:173], v[194:197], v[100:103]
	v_mfma_f32_16x16x32_f16 v[96:99], v[178:181], v[194:197], v[96:99]
	v_mfma_f32_16x16x32_f16 v[84:87], v[170:173], v[202:205], v[84:87]
	v_mfma_f32_16x16x32_f16 v[80:83], v[178:181], v[202:205], v[80:83]
	v_mfma_f32_16x16x32_f16 v[68:71], v[170:173], v[210:213], v[68:71]
	v_mfma_f32_16x16x32_f16 v[64:67], v[178:181], v[210:213], v[64:67]
	s_barrier
	s_add_i32 s46, s48, s53
	v_lshl_add_u64 v[214:215], s[28:29], 0, v[128:129]
	s_mov_b32 m0, s46
	ds_read_b128 v[182:185], v148 offset:16384
	ds_read_b128 v[186:189], v148 offset:17408
	ds_read_b128 v[190:193], v148 offset:18432
	ds_read_b128 v[194:197], v148 offset:19456
	ds_read_b128 v[198:201], v148 offset:20480
	ds_read_b128 v[202:205], v148 offset:21504
	ds_read_b128 v[206:209], v148 offset:22528
	ds_read_b128 v[210:213], v148 offset:23552
	global_load_lds_dwordx4 v[214:215], off
	s_add_i32 m0, s46, 0x2000
	s_add_u32 s46, s28, 0x40000
	v_lshl_add_u64 v[216:217], s[28:29], 0, v[134:135]
	s_addc_u32 s47, s29, 0
	s_add_i32 s48, s49, s53
	global_load_lds_dwordx4 v[216:217], off
	v_lshl_add_u64 v[218:219], s[46:47], 0, v[128:129]
	s_mov_b32 m0, s48
	v_lshl_add_u64 v[220:221], s[30:31], 0, v[132:133]
	global_load_lds_dwordx4 v[218:219], off
	v_lshl_add_u64 v[218:219], s[46:47], 0, v[134:135]
	s_add_i32 m0, s48, 0x2000
	s_nop 0
	global_load_lds_dwordx4 v[218:219], off
	v_lshl_add_u64 v[218:219], s[30:31], 0, v[130:131]
	s_mov_b32 m0, s35
	s_nop 0
	global_load_lds_dwordx4 v[218:219], off
	s_mov_b32 m0, s36
	s_nop 0
	global_load_lds_dwordx4 v[220:221], off
	s_waitcnt vmcnt(8)
	s_waitcnt lgkmcnt(0)
	s_barrier
	s_waitcnt lgkmcnt(0)
	v_mfma_f32_16x16x32_f16 v[60:63], v[150:153], v[182:185], v[60:63]
	v_mfma_f32_16x16x32_f16 v[56:59], v[158:161], v[182:185], v[56:59]
	v_mfma_f32_16x16x32_f16 v[44:47], v[150:153], v[190:193], v[44:47]
	v_mfma_f32_16x16x32_f16 v[40:43], v[158:161], v[190:193], v[40:43]
	v_mfma_f32_16x16x32_f16 v[28:31], v[150:153], v[198:201], v[28:31]
	v_mfma_f32_16x16x32_f16 v[24:27], v[158:161], v[198:201], v[24:27]
	v_mfma_f32_16x16x32_f16 v[12:15], v[150:153], v[206:209], v[12:15]
	v_mfma_f32_16x16x32_f16 v[8:11], v[158:161], v[206:209], v[8:11]
	v_mfma_f32_16x16x32_f16 v[60:63], v[154:157], v[186:189], v[60:63]
	v_mfma_f32_16x16x32_f16 v[56:59], v[162:165], v[186:189], v[56:59]
	v_mfma_f32_16x16x32_f16 v[44:47], v[154:157], v[194:197], v[44:47]
	v_mfma_f32_16x16x32_f16 v[40:43], v[162:165], v[194:197], v[40:43]
	v_mfma_f32_16x16x32_f16 v[28:31], v[154:157], v[202:205], v[28:31]
	v_mfma_f32_16x16x32_f16 v[24:27], v[162:165], v[202:205], v[24:27]
	v_mfma_f32_16x16x32_f16 v[12:15], v[154:157], v[210:213], v[12:15]
	v_mfma_f32_16x16x32_f16 v[8:11], v[162:165], v[210:213], v[8:11]
	v_mfma_f32_16x16x32_f16 v[52:55], v[166:169], v[182:185], v[52:55]
	v_mfma_f32_16x16x32_f16 v[48:51], v[174:177], v[182:185], v[48:51]
	v_mfma_f32_16x16x32_f16 v[36:39], v[166:169], v[190:193], v[36:39]
	v_mfma_f32_16x16x32_f16 v[32:35], v[174:177], v[190:193], v[32:35]
	v_mfma_f32_16x16x32_f16 v[20:23], v[166:169], v[198:201], v[20:23]
	v_mfma_f32_16x16x32_f16 v[16:19], v[174:177], v[198:201], v[16:19]
	v_mfma_f32_16x16x32_f16 v[4:7], v[166:169], v[206:209], v[4:7]
	v_mfma_f32_16x16x32_f16 v[0:3], v[174:177], v[206:209], v[0:3]
	v_mfma_f32_16x16x32_f16 v[52:55], v[170:173], v[186:189], v[52:55]
	v_mfma_f32_16x16x32_f16 v[48:51], v[178:181], v[186:189], v[48:51]
	v_mfma_f32_16x16x32_f16 v[36:39], v[170:173], v[194:197], v[36:39]
	v_mfma_f32_16x16x32_f16 v[32:35], v[178:181], v[194:197], v[32:35]
	v_mfma_f32_16x16x32_f16 v[20:23], v[170:173], v[202:205], v[20:23]
	v_mfma_f32_16x16x32_f16 v[16:19], v[178:181], v[202:205], v[16:19]
	v_mfma_f32_16x16x32_f16 v[4:7], v[170:173], v[210:213], v[4:7]
	v_mfma_f32_16x16x32_f16 v[0:3], v[178:181], v[210:213], v[0:3]
	s_barrier
	s_add_i32 s46, 0, 0x18000
	v_add_u32_e32 v149, s46, v147
	s_add_i32 s47, 0, 0x1c000
	ds_read_b128 v[150:153], v149
	ds_read_b128 v[154:157], v149 offset:1024
	ds_read_b128 v[158:161], v149 offset:2048
	ds_read_b128 v[162:165], v149 offset:3072
	v_add_u32_e32 v149, s47, v147
	ds_read_b128 v[166:169], v149
	ds_read_b128 v[170:173], v149 offset:1024
	ds_read_b128 v[174:177], v149 offset:2048
	ds_read_b128 v[178:181], v149 offset:3072
	s_add_u32 s30, s30, 0x40000
	s_addc_u32 s31, s31, 0
	s_mov_b32 m0, s37
	v_lshl_add_u64 v[222:223], s[30:31], 0, v[130:131]
	ds_read_b128 v[182:185], v148 offset:32768
	ds_read_b128 v[186:189], v148 offset:33792
	ds_read_b128 v[190:193], v148 offset:34816
	ds_read_b128 v[194:197], v148 offset:35840
	ds_read_b128 v[198:201], v148 offset:36864
	ds_read_b128 v[202:205], v148 offset:37888
	ds_read_b128 v[206:209], v148 offset:38912
	ds_read_b128 v[210:213], v148 offset:39936
	global_load_lds_dwordx4 v[222:223], off
	v_lshl_add_u64 v[222:223], s[30:31], 0, v[132:133]
	s_mov_b32 m0, s38
	s_nop 0
	global_load_lds_dwordx4 v[222:223], off
	s_waitcnt vmcnt(8)
	s_waitcnt lgkmcnt(0)
	s_barrier
	s_waitcnt lgkmcnt(0)
	v_mfma_f32_16x16x32_f16 v[124:127], v[150:153], v[182:185], v[124:127]
	v_mfma_f32_16x16x32_f16 v[120:123], v[158:161], v[182:185], v[120:123]
	v_mfma_f32_16x16x32_f16 v[108:111], v[150:153], v[190:193], v[108:111]
	v_mfma_f32_16x16x32_f16 v[104:107], v[158:161], v[190:193], v[104:107]
	v_mfma_f32_16x16x32_f16 v[92:95], v[150:153], v[198:201], v[92:95]
	v_mfma_f32_16x16x32_f16 v[88:91], v[158:161], v[198:201], v[88:91]
	v_mfma_f32_16x16x32_f16 v[76:79], v[150:153], v[206:209], v[76:79]
	v_mfma_f32_16x16x32_f16 v[72:75], v[158:161], v[206:209], v[72:75]
	v_mfma_f32_16x16x32_f16 v[124:127], v[154:157], v[186:189], v[124:127]
	v_mfma_f32_16x16x32_f16 v[120:123], v[162:165], v[186:189], v[120:123]
	v_mfma_f32_16x16x32_f16 v[108:111], v[154:157], v[194:197], v[108:111]
	v_mfma_f32_16x16x32_f16 v[104:107], v[162:165], v[194:197], v[104:107]
	v_mfma_f32_16x16x32_f16 v[92:95], v[154:157], v[202:205], v[92:95]
	v_mfma_f32_16x16x32_f16 v[88:91], v[162:165], v[202:205], v[88:91]
	v_mfma_f32_16x16x32_f16 v[76:79], v[154:157], v[210:213], v[76:79]
	v_mfma_f32_16x16x32_f16 v[72:75], v[162:165], v[210:213], v[72:75]
	v_mfma_f32_16x16x32_f16 v[116:119], v[166:169], v[182:185], v[116:119]
	v_mfma_f32_16x16x32_f16 v[112:115], v[174:177], v[182:185], v[112:115]
	v_mfma_f32_16x16x32_f16 v[100:103], v[166:169], v[190:193], v[100:103]
	v_mfma_f32_16x16x32_f16 v[96:99], v[174:177], v[190:193], v[96:99]
	v_mfma_f32_16x16x32_f16 v[84:87], v[166:169], v[198:201], v[84:87]
	v_mfma_f32_16x16x32_f16 v[80:83], v[174:177], v[198:201], v[80:83]
	v_mfma_f32_16x16x32_f16 v[68:71], v[166:169], v[206:209], v[68:71]
	v_mfma_f32_16x16x32_f16 v[64:67], v[174:177], v[206:209], v[64:67]
	v_mfma_f32_16x16x32_f16 v[116:119], v[170:173], v[186:189], v[116:119]
	v_mfma_f32_16x16x32_f16 v[112:115], v[178:181], v[186:189], v[112:115]
	v_mfma_f32_16x16x32_f16 v[100:103], v[170:173], v[194:197], v[100:103]
	v_mfma_f32_16x16x32_f16 v[96:99], v[178:181], v[194:197], v[96:99]
	v_mfma_f32_16x16x32_f16 v[84:87], v[170:173], v[202:205], v[84:87]
	v_mfma_f32_16x16x32_f16 v[80:83], v[178:181], v[202:205], v[80:83]
	v_mfma_f32_16x16x32_f16 v[68:71], v[170:173], v[210:213], v[68:71]
	v_mfma_f32_16x16x32_f16 v[64:67], v[178:181], v[210:213], v[64:67]
	s_barrier
	s_add_i32 s30, s46, s53
	v_lshl_add_u64 v[214:215], v[214:215], 0, s[20:21]
	s_mov_b32 m0, s30
	ds_read_b128 v[182:185], v148 offset:49152
	ds_read_b128 v[186:189], v148 offset:50176
	ds_read_b128 v[190:193], v148 offset:51200
	ds_read_b128 v[194:197], v148 offset:52224
	ds_read_b128 v[198:201], v148 offset:53248
	ds_read_b128 v[202:205], v148 offset:54272
	ds_read_b128 v[206:209], v148 offset:55296
	ds_read_b128 v[210:213], v148 offset:56320
	global_load_lds_dwordx4 v[214:215], off
	s_add_i32 m0, s30, 0x2000
	s_add_u32 s28, s28, 0x40080
	v_lshl_add_u64 v[214:215], v[216:217], 0, s[20:21]
	s_addc_u32 s29, s29, 0
	s_add_i32 s30, s47, s53
	global_load_lds_dwordx4 v[214:215], off
	v_lshl_add_u64 v[214:215], s[28:29], 0, v[128:129]
	s_mov_b32 m0, s30
	s_nop 0
	global_load_lds_dwordx4 v[214:215], off
	v_lshl_add_u64 v[214:215], s[28:29], 0, v[134:135]
	s_add_i32 m0, s30, 0x2000
	s_nop 0
	global_load_lds_dwordx4 v[214:215], off
	v_lshl_add_u64 v[214:215], v[218:219], 0, s[20:21]
	s_mov_b32 m0, s39
	s_nop 0
	global_load_lds_dwordx4 v[214:215], off
	v_lshl_add_u64 v[214:215], v[220:221], 0, s[20:21]
	s_mov_b32 m0, s40
	s_nop 0
	global_load_lds_dwordx4 v[214:215], off
	s_waitcnt vmcnt(8)
	s_waitcnt lgkmcnt(0)
	s_barrier
	s_waitcnt lgkmcnt(0)
	v_mfma_f32_16x16x32_f16 v[60:63], v[150:153], v[182:185], v[60:63]
	v_mfma_f32_16x16x32_f16 v[56:59], v[158:161], v[182:185], v[56:59]
	v_mfma_f32_16x16x32_f16 v[44:47], v[150:153], v[190:193], v[44:47]
	v_mfma_f32_16x16x32_f16 v[40:43], v[158:161], v[190:193], v[40:43]
	v_mfma_f32_16x16x32_f16 v[28:31], v[150:153], v[198:201], v[28:31]
	v_mfma_f32_16x16x32_f16 v[24:27], v[158:161], v[198:201], v[24:27]
	v_mfma_f32_16x16x32_f16 v[12:15], v[150:153], v[206:209], v[12:15]
	v_mfma_f32_16x16x32_f16 v[8:11], v[158:161], v[206:209], v[8:11]
	v_mfma_f32_16x16x32_f16 v[60:63], v[154:157], v[186:189], v[60:63]
	v_mfma_f32_16x16x32_f16 v[56:59], v[162:165], v[186:189], v[56:59]
	v_mfma_f32_16x16x32_f16 v[44:47], v[154:157], v[194:197], v[44:47]
	v_mfma_f32_16x16x32_f16 v[40:43], v[162:165], v[194:197], v[40:43]
	v_mfma_f32_16x16x32_f16 v[28:31], v[154:157], v[202:205], v[28:31]
	v_mfma_f32_16x16x32_f16 v[24:27], v[162:165], v[202:205], v[24:27]
	v_mfma_f32_16x16x32_f16 v[12:15], v[154:157], v[210:213], v[12:15]
	v_mfma_f32_16x16x32_f16 v[8:11], v[162:165], v[210:213], v[8:11]
	v_mfma_f32_16x16x32_f16 v[52:55], v[166:169], v[182:185], v[52:55]
	v_mfma_f32_16x16x32_f16 v[48:51], v[174:177], v[182:185], v[48:51]
	v_mfma_f32_16x16x32_f16 v[36:39], v[166:169], v[190:193], v[36:39]
	v_mfma_f32_16x16x32_f16 v[32:35], v[174:177], v[190:193], v[32:35]
	v_mfma_f32_16x16x32_f16 v[20:23], v[166:169], v[198:201], v[20:23]
	v_mfma_f32_16x16x32_f16 v[16:19], v[174:177], v[198:201], v[16:19]
	v_mfma_f32_16x16x32_f16 v[4:7], v[166:169], v[206:209], v[4:7]
	v_mfma_f32_16x16x32_f16 v[0:3], v[174:177], v[206:209], v[0:3]
	v_mfma_f32_16x16x32_f16 v[52:55], v[170:173], v[186:189], v[52:55]
	v_mfma_f32_16x16x32_f16 v[48:51], v[178:181], v[186:189], v[48:51]
	v_mfma_f32_16x16x32_f16 v[36:39], v[170:173], v[194:197], v[36:39]
	v_mfma_f32_16x16x32_f16 v[32:35], v[178:181], v[194:197], v[32:35]
	v_mfma_f32_16x16x32_f16 v[20:23], v[170:173], v[202:205], v[20:23]
	v_mfma_f32_16x16x32_f16 v[16:19], v[178:181], v[202:205], v[16:19]
	v_mfma_f32_16x16x32_f16 v[4:7], v[170:173], v[210:213], v[4:7]
	v_mfma_f32_16x16x32_f16 v[0:3], v[178:181], v[210:213], v[0:3]
	s_add_i32 s45, s45, 2
	s_add_u32 s26, s26, 0x100
	s_addc_u32 s27, s27, 0
	s_cmp_gt_u32 s45, 13
	s_cbranch_scc0 .LBB0_1329
	s_barrier
	s_and_b64 vcc, exec, s[16:17]
	s_cbranch_vccz .LBB0_1332
	s_barrier

.LBB0_1428:
	s_add_u32 s22, s22, 0x40080
	s_addc_u32 s23, s23, 0
	s_add_u32 s13, s30, 0x100
	s_addc_u32 s15, s31, 0
	s_mov_b32 s51, -2
	ds_read_b128 v[158:161], v151
	ds_read_b128 v[162:165], v151 offset:1024
	ds_read_b128 v[166:169], v151 offset:2048
	ds_read_b128 v[170:173], v151 offset:3072
	ds_read_b128 v[174:177], v152
	ds_read_b128 v[178:181], v152 offset:1024
	ds_read_b128 v[182:185], v152 offset:2048
	ds_read_b128 v[186:189], v152 offset:3072
	s_add_u32 s30, s22, 0xfffc0080
	s_addc_u32 s31, s23, -1
	s_cmp_eq_u32 s51, 12
	s_cselect_b32 s35, s17, s31
	s_cselect_b32 s34, s16, s30
	s_cselect_b32 s31, s19, s15
	s_cselect_b32 s30, s18, s13
	v_lshl_add_u64 v[222:223], s[22:23], 0, v[138:139]
	s_add_i32 m0, s21, 0xc000
	ds_read_b128 v[190:193], v153
	ds_read_b128 v[194:197], v153 offset:1024
	ds_read_b128 v[198:201], v153 offset:2048
	ds_read_b128 v[202:205], v153 offset:3072
	ds_read_b128 v[206:209], v153 offset:4096
	ds_read_b128 v[210:213], v153 offset:5120
	ds_read_b128 v[214:217], v153 offset:6144
	ds_read_b128 v[218:221], v153 offset:7168
	global_load_lds_dwordx4 v[222:223], off
	v_lshl_add_u64 v[222:223], s[22:23], 0, v[140:141]
	s_add_i32 m0, s21, 0xe000
	s_nop 0
	global_load_lds_dwordx4 v[222:223], off
	s_waitcnt vmcnt(8)
	s_waitcnt lgkmcnt(0)
	s_barrier
	s_waitcnt lgkmcnt(0)
	v_mfma_f32_16x16x32_f16 v[124:127], v[158:161], v[190:193], 0
	v_mfma_f32_16x16x32_f16 v[120:123], v[166:169], v[190:193], 0
	v_mfma_f32_16x16x32_f16 v[108:111], v[158:161], v[198:201], 0
	v_mfma_f32_16x16x32_f16 v[104:107], v[166:169], v[198:201], 0
	v_mfma_f32_16x16x32_f16 v[92:95], v[158:161], v[206:209], 0
	v_mfma_f32_16x16x32_f16 v[88:91], v[166:169], v[206:209], 0
	v_mfma_f32_16x16x32_f16 v[76:79], v[158:161], v[214:217], 0
	v_mfma_f32_16x16x32_f16 v[72:75], v[166:169], v[214:217], 0
	v_mfma_f32_16x16x32_f16 v[124:127], v[162:165], v[194:197], v[124:127]
	v_mfma_f32_16x16x32_f16 v[120:123], v[170:173], v[194:197], v[120:123]
	v_mfma_f32_16x16x32_f16 v[108:111], v[162:165], v[202:205], v[108:111]
	v_mfma_f32_16x16x32_f16 v[104:107], v[170:173], v[202:205], v[104:107]
	v_mfma_f32_16x16x32_f16 v[92:95], v[162:165], v[210:213], v[92:95]
	v_mfma_f32_16x16x32_f16 v[88:91], v[170:173], v[210:213], v[88:91]
	v_mfma_f32_16x16x32_f16 v[76:79], v[162:165], v[218:221], v[76:79]
	v_mfma_f32_16x16x32_f16 v[72:75], v[170:173], v[218:221], v[72:75]
	v_mfma_f32_16x16x32_f16 v[116:119], v[174:177], v[190:193], 0
	v_mfma_f32_16x16x32_f16 v[112:115], v[182:185], v[190:193], 0
	v_mfma_f32_16x16x32_f16 v[100:103], v[174:177], v[198:201], 0
	v_mfma_f32_16x16x32_f16 v[96:99], v[182:185], v[198:201], 0
	v_mfma_f32_16x16x32_f16 v[84:87], v[174:177], v[206:209], 0
	v_mfma_f32_16x16x32_f16 v[80:83], v[182:185], v[206:209], 0
	v_mfma_f32_16x16x32_f16 v[68:71], v[174:177], v[214:217], 0
	v_mfma_f32_16x16x32_f16 v[64:67], v[182:185], v[214:217], 0
	v_mfma_f32_16x16x32_f16 v[116:119], v[178:181], v[194:197], v[116:119]
	v_mfma_f32_16x16x32_f16 v[112:115], v[186:189], v[194:197], v[112:115]
	v_mfma_f32_16x16x32_f16 v[100:103], v[178:181], v[202:205], v[100:103]
	v_mfma_f32_16x16x32_f16 v[96:99], v[186:189], v[202:205], v[96:99]
	v_mfma_f32_16x16x32_f16 v[84:87], v[178:181], v[210:213], v[84:87]
	v_mfma_f32_16x16x32_f16 v[80:83], v[186:189], v[210:213], v[80:83]
	v_mfma_f32_16x16x32_f16 v[68:71], v[178:181], v[218:221], v[68:71]
	v_mfma_f32_16x16x32_f16 v[64:67], v[186:189], v[218:221], v[64:67]
	s_barrier
	s_add_i32 s52, s46, s3
	v_lshl_add_u64 v[222:223], s[30:31], 0, v[132:133]
	s_mov_b32 m0, s52
	ds_read_b128 v[190:193], v153 offset:16384
	ds_read_b128 v[194:197], v153 offset:17408
	ds_read_b128 v[198:201], v153 offset:18432
	ds_read_b128 v[202:205], v153 offset:19456
	ds_read_b128 v[206:209], v153 offset:20480
	ds_read_b128 v[210:213], v153 offset:21504
	ds_read_b128 v[214:217], v153 offset:22528
	ds_read_b128 v[218:221], v153 offset:23552
	global_load_lds_dwordx4 v[222:223], off
	s_add_i32 m0, s52, 0x2000
	s_add_u32 s52, s30, 0x40000
	v_lshl_add_u64 v[224:225], s[30:31], 0, v[128:129]
	s_addc_u32 s53, s31, 0
	s_add_i32 s54, s47, s3
	global_load_lds_dwordx4 v[224:225], off
	v_lshl_add_u64 v[226:227], s[52:53], 0, v[132:133]
	s_mov_b32 m0, s54
	v_lshl_add_u64 v[228:229], s[34:35], 0, v[130:131]
	global_load_lds_dwordx4 v[226:227], off
	v_lshl_add_u64 v[226:227], s[52:53], 0, v[128:129]
	s_add_i32 m0, s54, 0x2000
	s_nop 0
	global_load_lds_dwordx4 v[226:227], off
	v_lshl_add_u64 v[226:227], s[34:35], 0, v[134:135]
	s_mov_b32 m0, s21
	s_nop 0
	global_load_lds_dwordx4 v[226:227], off
	s_mov_b32 m0, s40
	s_nop 0
	global_load_lds_dwordx4 v[228:229], off
	s_waitcnt vmcnt(8)
	s_waitcnt lgkmcnt(0)
	s_barrier
	s_waitcnt lgkmcnt(0)
	v_mfma_f32_16x16x32_f16 v[60:63], v[158:161], v[190:193], 0
	v_mfma_f32_16x16x32_f16 v[56:59], v[166:169], v[190:193], 0
	v_mfma_f32_16x16x32_f16 v[44:47], v[158:161], v[198:201], 0
	v_mfma_f32_16x16x32_f16 v[40:43], v[166:169], v[198:201], 0
	v_mfma_f32_16x16x32_f16 v[28:31], v[158:161], v[206:209], 0
	v_mfma_f32_16x16x32_f16 v[24:27], v[166:169], v[206:209], 0
	v_mfma_f32_16x16x32_f16 v[12:15], v[158:161], v[214:217], 0
	v_mfma_f32_16x16x32_f16 v[8:11], v[166:169], v[214:217], 0
	v_mfma_f32_16x16x32_f16 v[60:63], v[162:165], v[194:197], v[60:63]
	v_mfma_f32_16x16x32_f16 v[56:59], v[170:173], v[194:197], v[56:59]
	v_mfma_f32_16x16x32_f16 v[44:47], v[162:165], v[202:205], v[44:47]
	v_mfma_f32_16x16x32_f16 v[40:43], v[170:173], v[202:205], v[40:43]
	v_mfma_f32_16x16x32_f16 v[28:31], v[162:165], v[210:213], v[28:31]
	v_mfma_f32_16x16x32_f16 v[24:27], v[170:173], v[210:213], v[24:27]
	v_mfma_f32_16x16x32_f16 v[12:15], v[162:165], v[218:221], v[12:15]
	v_mfma_f32_16x16x32_f16 v[8:11], v[170:173], v[218:221], v[8:11]
	v_mfma_f32_16x16x32_f16 v[52:55], v[174:177], v[190:193], 0
	v_mfma_f32_16x16x32_f16 v[48:51], v[182:185], v[190:193], 0
	v_mfma_f32_16x16x32_f16 v[36:39], v[174:177], v[198:201], 0
	v_mfma_f32_16x16x32_f16 v[32:35], v[182:185], v[198:201], 0
	v_mfma_f32_16x16x32_f16 v[20:23], v[174:177], v[206:209], 0
	v_mfma_f32_16x16x32_f16 v[16:19], v[182:185], v[206:209], 0
	v_mfma_f32_16x16x32_f16 v[4:7], v[174:177], v[214:217], 0
	v_mfma_f32_16x16x32_f16 v[0:3], v[182:185], v[214:217], 0
	v_mfma_f32_16x16x32_f16 v[52:55], v[178:181], v[194:197], v[52:55]
	v_mfma_f32_16x16x32_f16 v[48:51], v[186:189], v[194:197], v[48:51]
	v_mfma_f32_16x16x32_f16 v[36:39], v[178:181], v[202:205], v[36:39]
	v_mfma_f32_16x16x32_f16 v[32:35], v[186:189], v[202:205], v[32:35]
	v_mfma_f32_16x16x32_f16 v[20:23], v[178:181], v[210:213], v[20:23]
	v_mfma_f32_16x16x32_f16 v[16:19], v[186:189], v[210:213], v[16:19]
	v_mfma_f32_16x16x32_f16 v[4:7], v[178:181], v[218:221], v[4:7]
	v_mfma_f32_16x16x32_f16 v[0:3], v[186:189], v[218:221], v[0:3]
	s_barrier
	ds_read_b128 v[158:161], v154
	ds_read_b128 v[162:165], v154 offset:1024
	ds_read_b128 v[166:169], v154 offset:2048
	ds_read_b128 v[170:173], v154 offset:3072
	ds_read_b128 v[174:177], v155
	ds_read_b128 v[178:181], v155 offset:1024
	ds_read_b128 v[182:185], v155 offset:2048
	ds_read_b128 v[186:189], v155 offset:3072
	s_add_u32 s34, s34, 0x40000
	s_addc_u32 s35, s35, 0
	s_mov_b32 m0, s41
	v_lshl_add_u64 v[230:231], s[34:35], 0, v[134:135]
	ds_read_b128 v[190:193], v153 offset:32768
	ds_read_b128 v[194:197], v153 offset:33792
	ds_read_b128 v[198:201], v153 offset:34816
	ds_read_b128 v[202:205], v153 offset:35840
	ds_read_b128 v[206:209], v153 offset:36864
	ds_read_b128 v[210:213], v153 offset:37888
	ds_read_b128 v[214:217], v153 offset:38912
	ds_read_b128 v[218:221], v153 offset:39936
	global_load_lds_dwordx4 v[230:231], off
	v_lshl_add_u64 v[230:231], s[34:35], 0, v[130:131]
	s_mov_b32 m0, s42
	s_nop 0
	global_load_lds_dwordx4 v[230:231], off
	s_waitcnt vmcnt(8)
	s_waitcnt lgkmcnt(0)
	s_barrier
	s_waitcnt lgkmcnt(0)
	v_mfma_f32_16x16x32_f16 v[124:127], v[158:161], v[190:193], v[124:127]
	v_mfma_f32_16x16x32_f16 v[120:123], v[166:169], v[190:193], v[120:123]
	v_mfma_f32_16x16x32_f16 v[108:111], v[158:161], v[198:201], v[108:111]
	v_mfma_f32_16x16x32_f16 v[104:107], v[166:169], v[198:201], v[104:107]
	v_mfma_f32_16x16x32_f16 v[92:95], v[158:161], v[206:209], v[92:95]
	v_mfma_f32_16x16x32_f16 v[88:91], v[166:169], v[206:209], v[88:91]
	v_mfma_f32_16x16x32_f16 v[76:79], v[158:161], v[214:217], v[76:79]
	v_mfma_f32_16x16x32_f16 v[72:75], v[166:169], v[214:217], v[72:75]
	v_mfma_f32_16x16x32_f16 v[124:127], v[162:165], v[194:197], v[124:127]
	v_mfma_f32_16x16x32_f16 v[120:123], v[170:173], v[194:197], v[120:123]
	v_mfma_f32_16x16x32_f16 v[108:111], v[162:165], v[202:205], v[108:111]
	v_mfma_f32_16x16x32_f16 v[104:107], v[170:173], v[202:205], v[104:107]
	v_mfma_f32_16x16x32_f16 v[92:95], v[162:165], v[210:213], v[92:95]
	v_mfma_f32_16x16x32_f16 v[88:91], v[170:173], v[210:213], v[88:91]
	v_mfma_f32_16x16x32_f16 v[76:79], v[162:165], v[218:221], v[76:79]
	v_mfma_f32_16x16x32_f16 v[72:75], v[170:173], v[218:221], v[72:75]
	v_mfma_f32_16x16x32_f16 v[116:119], v[174:177], v[190:193], v[116:119]
	v_mfma_f32_16x16x32_f16 v[112:115], v[182:185], v[190:193], v[112:115]
	v_mfma_f32_16x16x32_f16 v[100:103], v[174:177], v[198:201], v[100:103]
	v_mfma_f32_16x16x32_f16 v[96:99], v[182:185], v[198:201], v[96:99]
	v_mfma_f32_16x16x32_f16 v[84:87], v[174:177], v[206:209], v[84:87]
	v_mfma_f32_16x16x32_f16 v[80:83], v[182:185], v[206:209], v[80:83]
	v_mfma_f32_16x16x32_f16 v[68:71], v[174:177], v[214:217], v[68:71]
	v_mfma_f32_16x16x32_f16 v[64:67], v[182:185], v[214:217], v[64:67]
	v_mfma_f32_16x16x32_f16 v[116:119], v[178:181], v[194:197], v[116:119]
	v_mfma_f32_16x16x32_f16 v[112:115], v[186:189], v[194:197], v[112:115]
	v_mfma_f32_16x16x32_f16 v[100:103], v[178:181], v[202:205], v[100:103]
	v_mfma_f32_16x16x32_f16 v[96:99], v[186:189], v[202:205], v[96:99]
	v_mfma_f32_16x16x32_f16 v[84:87], v[178:181], v[210:213], v[84:87]
	v_mfma_f32_16x16x32_f16 v[80:83], v[186:189], v[210:213], v[80:83]
	v_mfma_f32_16x16x32_f16 v[68:71], v[178:181], v[218:221], v[68:71]
	v_mfma_f32_16x16x32_f16 v[64:67], v[186:189], v[218:221], v[64:67]
	s_barrier
	s_add_i32 s34, s48, s3
	v_lshl_add_u64 v[222:223], v[222:223], 0, s[10:11]
	s_mov_b32 m0, s34
	ds_read_b128 v[190:193], v153 offset:49152
	ds_read_b128 v[194:197], v153 offset:50176
	ds_read_b128 v[198:201], v153 offset:51200
	ds_read_b128 v[202:205], v153 offset:52224
	ds_read_b128 v[206:209], v153 offset:53248
	ds_read_b128 v[210:213], v153 offset:54272
	ds_read_b128 v[214:217], v153 offset:55296
	ds_read_b128 v[218:221], v153 offset:56320
	global_load_lds_dwordx4 v[222:223], off
	s_add_i32 m0, s34, 0x2000
	s_add_u32 s30, s30, 0x40080
	v_lshl_add_u64 v[222:223], v[224:225], 0, s[10:11]
	s_addc_u32 s31, s31, 0
	s_add_i32 s34, s49, s3
	global_load_lds_dwordx4 v[222:223], off
	v_lshl_add_u64 v[222:223], s[30:31], 0, v[132:133]
	s_mov_b32 m0, s34
	s_nop 0
	global_load_lds_dwordx4 v[222:223], off
	v_lshl_add_u64 v[222:223], s[30:31], 0, v[128:129]
	s_add_i32 m0, s34, 0x2000
	s_nop 0
	global_load_lds_dwordx4 v[222:223], off
	v_lshl_add_u64 v[222:223], v[226:227], 0, s[10:11]
	s_mov_b32 m0, s43
	s_nop 0
	global_load_lds_dwordx4 v[222:223], off
	v_lshl_add_u64 v[222:223], v[228:229], 0, s[10:11]
	s_mov_b32 m0, s44
	s_nop 0
	global_load_lds_dwordx4 v[222:223], off
	s_waitcnt vmcnt(8)
	s_waitcnt lgkmcnt(0)
	s_barrier
	s_waitcnt lgkmcnt(0)
	v_mfma_f32_16x16x32_f16 v[60:63], v[158:161], v[190:193], v[60:63]
	v_mfma_f32_16x16x32_f16 v[56:59], v[166:169], v[190:193], v[56:59]
	v_mfma_f32_16x16x32_f16 v[44:47], v[158:161], v[198:201], v[44:47]
	v_mfma_f32_16x16x32_f16 v[40:43], v[166:169], v[198:201], v[40:43]
	v_mfma_f32_16x16x32_f16 v[28:31], v[158:161], v[206:209], v[28:31]
	v_mfma_f32_16x16x32_f16 v[24:27], v[166:169], v[206:209], v[24:27]
	v_mfma_f32_16x16x32_f16 v[12:15], v[158:161], v[214:217], v[12:15]
	v_mfma_f32_16x16x32_f16 v[8:11], v[166:169], v[214:217], v[8:11]
	v_mfma_f32_16x16x32_f16 v[60:63], v[162:165], v[194:197], v[60:63]
	v_mfma_f32_16x16x32_f16 v[56:59], v[170:173], v[194:197], v[56:59]
	v_mfma_f32_16x16x32_f16 v[44:47], v[162:165], v[202:205], v[44:47]
	v_mfma_f32_16x16x32_f16 v[40:43], v[170:173], v[202:205], v[40:43]
	v_mfma_f32_16x16x32_f16 v[28:31], v[162:165], v[210:213], v[28:31]
	v_mfma_f32_16x16x32_f16 v[24:27], v[170:173], v[210:213], v[24:27]
	v_mfma_f32_16x16x32_f16 v[12:15], v[162:165], v[218:221], v[12:15]
	v_mfma_f32_16x16x32_f16 v[8:11], v[170:173], v[218:221], v[8:11]
	v_mfma_f32_16x16x32_f16 v[52:55], v[174:177], v[190:193], v[52:55]
	v_mfma_f32_16x16x32_f16 v[48:51], v[182:185], v[190:193], v[48:51]
	v_mfma_f32_16x16x32_f16 v[36:39], v[174:177], v[198:201], v[36:39]
	v_mfma_f32_16x16x32_f16 v[32:35], v[182:185], v[198:201], v[32:35]
	v_mfma_f32_16x16x32_f16 v[20:23], v[174:177], v[206:209], v[20:23]
	v_mfma_f32_16x16x32_f16 v[16:19], v[182:185], v[206:209], v[16:19]
	v_mfma_f32_16x16x32_f16 v[4:7], v[174:177], v[214:217], v[4:7]
	v_mfma_f32_16x16x32_f16 v[0:3], v[182:185], v[214:217], v[0:3]
	v_mfma_f32_16x16x32_f16 v[52:55], v[178:181], v[194:197], v[52:55]
	v_mfma_f32_16x16x32_f16 v[48:51], v[186:189], v[194:197], v[48:51]
	v_mfma_f32_16x16x32_f16 v[36:39], v[178:181], v[202:205], v[36:39]
	v_mfma_f32_16x16x32_f16 v[32:35], v[186:189], v[202:205], v[32:35]
	v_mfma_f32_16x16x32_f16 v[20:23], v[178:181], v[210:213], v[20:23]
	v_mfma_f32_16x16x32_f16 v[16:19], v[186:189], v[210:213], v[16:19]
	v_mfma_f32_16x16x32_f16 v[4:7], v[178:181], v[218:221], v[4:7]
	v_mfma_f32_16x16x32_f16 v[0:3], v[186:189], v[218:221], v[0:3]
	s_add_i32 s51, s51, 2
	s_add_u32 s22, s22, 0x100
	s_addc_u32 s23, s23, 0
	s_add_u32 s13, s13, 0x100
	s_addc_u32 s15, s15, 0
	s_cmp_gt_u32 s51, 13
.LBB0_1429:
	s_barrier
	ds_read_b128 v[158:161], v151
	ds_read_b128 v[162:165], v151 offset:1024
	ds_read_b128 v[166:169], v151 offset:2048
	ds_read_b128 v[170:173], v151 offset:3072
	ds_read_b128 v[174:177], v152
	ds_read_b128 v[178:181], v152 offset:1024
	ds_read_b128 v[182:185], v152 offset:2048
	ds_read_b128 v[186:189], v152 offset:3072
	s_add_u32 s30, s22, 0xfffc0080
	s_addc_u32 s31, s23, -1
	s_cmp_eq_u32 s51, 12
	s_cselect_b32 s35, s17, s31
	s_cselect_b32 s34, s16, s30
	s_cselect_b32 s31, s19, s15
	s_cselect_b32 s30, s18, s13
	v_lshl_add_u64 v[222:223], s[22:23], 0, v[138:139]
	s_add_i32 m0, s21, 0xc000
	ds_read_b128 v[190:193], v153
	ds_read_b128 v[194:197], v153 offset:1024
	ds_read_b128 v[198:201], v153 offset:2048
	ds_read_b128 v[202:205], v153 offset:3072
	ds_read_b128 v[206:209], v153 offset:4096
	ds_read_b128 v[210:213], v153 offset:5120
	ds_read_b128 v[214:217], v153 offset:6144
	ds_read_b128 v[218:221], v153 offset:7168
	global_load_lds_dwordx4 v[222:223], off
	v_lshl_add_u64 v[222:223], s[22:23], 0, v[140:141]
	s_add_i32 m0, s21, 0xe000
	s_nop 0
	global_load_lds_dwordx4 v[222:223], off
	s_waitcnt vmcnt(8)
	s_waitcnt lgkmcnt(0)
	s_barrier
	s_waitcnt lgkmcnt(0)
	v_mfma_f32_16x16x32_f16 v[124:127], v[158:161], v[190:193], v[124:127]
	v_mfma_f32_16x16x32_f16 v[120:123], v[166:169], v[190:193], v[120:123]
	v_mfma_f32_16x16x32_f16 v[108:111], v[158:161], v[198:201], v[108:111]
	v_mfma_f32_16x16x32_f16 v[104:107], v[166:169], v[198:201], v[104:107]
	v_mfma_f32_16x16x32_f16 v[92:95], v[158:161], v[206:209], v[92:95]
	v_mfma_f32_16x16x32_f16 v[88:91], v[166:169], v[206:209], v[88:91]
	v_mfma_f32_16x16x32_f16 v[76:79], v[158:161], v[214:217], v[76:79]
	v_mfma_f32_16x16x32_f16 v[72:75], v[166:169], v[214:217], v[72:75]
	v_mfma_f32_16x16x32_f16 v[124:127], v[162:165], v[194:197], v[124:127]
	v_mfma_f32_16x16x32_f16 v[120:123], v[170:173], v[194:197], v[120:123]
	v_mfma_f32_16x16x32_f16 v[108:111], v[162:165], v[202:205], v[108:111]
	v_mfma_f32_16x16x32_f16 v[104:107], v[170:173], v[202:205], v[104:107]
	v_mfma_f32_16x16x32_f16 v[92:95], v[162:165], v[210:213], v[92:95]
	v_mfma_f32_16x16x32_f16 v[88:91], v[170:173], v[210:213], v[88:91]
	v_mfma_f32_16x16x32_f16 v[76:79], v[162:165], v[218:221], v[76:79]
	v_mfma_f32_16x16x32_f16 v[72:75], v[170:173], v[218:221], v[72:75]
	v_mfma_f32_16x16x32_f16 v[116:119], v[174:177], v[190:193], v[116:119]
	v_mfma_f32_16x16x32_f16 v[112:115], v[182:185], v[190:193], v[112:115]
	v_mfma_f32_16x16x32_f16 v[100:103], v[174:177], v[198:201], v[100:103]
	v_mfma_f32_16x16x32_f16 v[96:99], v[182:185], v[198:201], v[96:99]
	v_mfma_f32_16x16x32_f16 v[84:87], v[174:177], v[206:209], v[84:87]
	v_mfma_f32_16x16x32_f16 v[80:83], v[182:185], v[206:209], v[80:83]
	v_mfma_f32_16x16x32_f16 v[68:71], v[174:177], v[214:217], v[68:71]
	v_mfma_f32_16x16x32_f16 v[64:67], v[182:185], v[214:217], v[64:67]
	v_mfma_f32_16x16x32_f16 v[116:119], v[178:181], v[194:197], v[116:119]
	v_mfma_f32_16x16x32_f16 v[112:115], v[186:189], v[194:197], v[112:115]
	v_mfma_f32_16x16x32_f16 v[100:103], v[178:181], v[202:205], v[100:103]
	v_mfma_f32_16x16x32_f16 v[96:99], v[186:189], v[202:205], v[96:99]
	v_mfma_f32_16x16x32_f16 v[84:87], v[178:181], v[210:213], v[84:87]
	v_mfma_f32_16x16x32_f16 v[80:83], v[186:189], v[210:213], v[80:83]
	v_mfma_f32_16x16x32_f16 v[68:71], v[178:181], v[218:221], v[68:71]
	v_mfma_f32_16x16x32_f16 v[64:67], v[186:189], v[218:221], v[64:67]
	s_barrier
	s_add_i32 s52, s46, s3
	v_lshl_add_u64 v[222:223], s[30:31], 0, v[132:133]
	s_mov_b32 m0, s52
	ds_read_b128 v[190:193], v153 offset:16384
	ds_read_b128 v[194:197], v153 offset:17408
	ds_read_b128 v[198:201], v153 offset:18432
	ds_read_b128 v[202:205], v153 offset:19456
	ds_read_b128 v[206:209], v153 offset:20480
	ds_read_b128 v[210:213], v153 offset:21504
	ds_read_b128 v[214:217], v153 offset:22528
	ds_read_b128 v[218:221], v153 offset:23552
	global_load_lds_dwordx4 v[222:223], off
	s_add_i32 m0, s52, 0x2000
	s_add_u32 s52, s30, 0x40000
	v_lshl_add_u64 v[224:225], s[30:31], 0, v[128:129]
	s_addc_u32 s53, s31, 0
	s_add_i32 s54, s47, s3
	global_load_lds_dwordx4 v[224:225], off
	v_lshl_add_u64 v[226:227], s[52:53], 0, v[132:133]
	s_mov_b32 m0, s54
	v_lshl_add_u64 v[228:229], s[34:35], 0, v[130:131]
	global_load_lds_dwordx4 v[226:227], off
	v_lshl_add_u64 v[226:227], s[52:53], 0, v[128:129]
	s_add_i32 m0, s54, 0x2000
	s_nop 0
	global_load_lds_dwordx4 v[226:227], off
	v_lshl_add_u64 v[226:227], s[34:35], 0, v[134:135]
	s_mov_b32 m0, s21
	s_nop 0
	global_load_lds_dwordx4 v[226:227], off
	s_mov_b32 m0, s40
	s_nop 0
	global_load_lds_dwordx4 v[228:229], off
	s_waitcnt vmcnt(8)
	s_waitcnt lgkmcnt(0)
	s_barrier
	s_waitcnt lgkmcnt(0)
	v_mfma_f32_16x16x32_f16 v[60:63], v[158:161], v[190:193], v[60:63]
	v_mfma_f32_16x16x32_f16 v[56:59], v[166:169], v[190:193], v[56:59]
	v_mfma_f32_16x16x32_f16 v[44:47], v[158:161], v[198:201], v[44:47]
	v_mfma_f32_16x16x32_f16 v[40:43], v[166:169], v[198:201], v[40:43]
	v_mfma_f32_16x16x32_f16 v[28:31], v[158:161], v[206:209], v[28:31]
	v_mfma_f32_16x16x32_f16 v[24:27], v[166:169], v[206:209], v[24:27]
	v_mfma_f32_16x16x32_f16 v[12:15], v[158:161], v[214:217], v[12:15]
	v_mfma_f32_16x16x32_f16 v[8:11], v[166:169], v[214:217], v[8:11]
	v_mfma_f32_16x16x32_f16 v[60:63], v[162:165], v[194:197], v[60:63]
	v_mfma_f32_16x16x32_f16 v[56:59], v[170:173], v[194:197], v[56:59]
	v_mfma_f32_16x16x32_f16 v[44:47], v[162:165], v[202:205], v[44:47]
	v_mfma_f32_16x16x32_f16 v[40:43], v[170:173], v[202:205], v[40:43]
	v_mfma_f32_16x16x32_f16 v[28:31], v[162:165], v[210:213], v[28:31]
	v_mfma_f32_16x16x32_f16 v[24:27], v[170:173], v[210:213], v[24:27]
	v_mfma_f32_16x16x32_f16 v[12:15], v[162:165], v[218:221], v[12:15]
	v_mfma_f32_16x16x32_f16 v[8:11], v[170:173], v[218:221], v[8:11]
	v_mfma_f32_16x16x32_f16 v[52:55], v[174:177], v[190:193], v[52:55]
	v_mfma_f32_16x16x32_f16 v[48:51], v[182:185], v[190:193], v[48:51]
	v_mfma_f32_16x16x32_f16 v[36:39], v[174:177], v[198:201], v[36:39]
	v_mfma_f32_16x16x32_f16 v[32:35], v[182:185], v[198:201], v[32:35]
	v_mfma_f32_16x16x32_f16 v[20:23], v[174:177], v[206:209], v[20:23]
	v_mfma_f32_16x16x32_f16 v[16:19], v[182:185], v[206:209], v[16:19]
	v_mfma_f32_16x16x32_f16 v[4:7], v[174:177], v[214:217], v[4:7]
	v_mfma_f32_16x16x32_f16 v[0:3], v[182:185], v[214:217], v[0:3]
	v_mfma_f32_16x16x32_f16 v[52:55], v[178:181], v[194:197], v[52:55]
	v_mfma_f32_16x16x32_f16 v[48:51], v[186:189], v[194:197], v[48:51]
	v_mfma_f32_16x16x32_f16 v[36:39], v[178:181], v[202:205], v[36:39]
	v_mfma_f32_16x16x32_f16 v[32:35], v[186:189], v[202:205], v[32:35]
	v_mfma_f32_16x16x32_f16 v[20:23], v[178:181], v[210:213], v[20:23]
	v_mfma_f32_16x16x32_f16 v[16:19], v[186:189], v[210:213], v[16:19]
	v_mfma_f32_16x16x32_f16 v[4:7], v[178:181], v[218:221], v[4:7]
	v_mfma_f32_16x16x32_f16 v[0:3], v[186:189], v[218:221], v[0:3]
	s_barrier
	ds_read_b128 v[158:161], v154
	ds_read_b128 v[162:165], v154 offset:1024
	ds_read_b128 v[166:169], v154 offset:2048
	ds_read_b128 v[170:173], v154 offset:3072
	ds_read_b128 v[174:177], v155
	ds_read_b128 v[178:181], v155 offset:1024
	ds_read_b128 v[182:185], v155 offset:2048
	ds_read_b128 v[186:189], v155 offset:3072
	s_add_u32 s34, s34, 0x40000
	s_addc_u32 s35, s35, 0
	s_mov_b32 m0, s41
	v_lshl_add_u64 v[230:231], s[34:35], 0, v[134:135]
	ds_read_b128 v[190:193], v153 offset:32768
	ds_read_b128 v[194:197], v153 offset:33792
	ds_read_b128 v[198:201], v153 offset:34816
	ds_read_b128 v[202:205], v153 offset:35840
	ds_read_b128 v[206:209], v153 offset:36864
	ds_read_b128 v[210:213], v153 offset:37888
	ds_read_b128 v[214:217], v153 offset:38912
	ds_read_b128 v[218:221], v153 offset:39936
	global_load_lds_dwordx4 v[230:231], off
	v_lshl_add_u64 v[230:231], s[34:35], 0, v[130:131]
	s_mov_b32 m0, s42
	s_nop 0
	global_load_lds_dwordx4 v[230:231], off
	s_waitcnt vmcnt(8)
	s_waitcnt lgkmcnt(0)
	s_barrier
	s_waitcnt lgkmcnt(0)
	v_mfma_f32_16x16x32_f16 v[124:127], v[158:161], v[190:193], v[124:127]
	v_mfma_f32_16x16x32_f16 v[120:123], v[166:169], v[190:193], v[120:123]
	v_mfma_f32_16x16x32_f16 v[108:111], v[158:161], v[198:201], v[108:111]
	v_mfma_f32_16x16x32_f16 v[104:107], v[166:169], v[198:201], v[104:107]
	v_mfma_f32_16x16x32_f16 v[92:95], v[158:161], v[206:209], v[92:95]
	v_mfma_f32_16x16x32_f16 v[88:91], v[166:169], v[206:209], v[88:91]
	v_mfma_f32_16x16x32_f16 v[76:79], v[158:161], v[214:217], v[76:79]
	v_mfma_f32_16x16x32_f16 v[72:75], v[166:169], v[214:217], v[72:75]
	v_mfma_f32_16x16x32_f16 v[124:127], v[162:165], v[194:197], v[124:127]
	v_mfma_f32_16x16x32_f16 v[120:123], v[170:173], v[194:197], v[120:123]
	v_mfma_f32_16x16x32_f16 v[108:111], v[162:165], v[202:205], v[108:111]
	v_mfma_f32_16x16x32_f16 v[104:107], v[170:173], v[202:205], v[104:107]
	v_mfma_f32_16x16x32_f16 v[92:95], v[162:165], v[210:213], v[92:95]
	v_mfma_f32_16x16x32_f16 v[88:91], v[170:173], v[210:213], v[88:91]
	v_mfma_f32_16x16x32_f16 v[76:79], v[162:165], v[218:221], v[76:79]
	v_mfma_f32_16x16x32_f16 v[72:75], v[170:173], v[218:221], v[72:75]
	v_mfma_f32_16x16x32_f16 v[116:119], v[174:177], v[190:193], v[116:119]
	v_mfma_f32_16x16x32_f16 v[112:115], v[182:185], v[190:193], v[112:115]
	v_mfma_f32_16x16x32_f16 v[100:103], v[174:177], v[198:201], v[100:103]
	v_mfma_f32_16x16x32_f16 v[96:99], v[182:185], v[198:201], v[96:99]
	v_mfma_f32_16x16x32_f16 v[84:87], v[174:177], v[206:209], v[84:87]
	v_mfma_f32_16x16x32_f16 v[80:83], v[182:185], v[206:209], v[80:83]
	v_mfma_f32_16x16x32_f16 v[68:71], v[174:177], v[214:217], v[68:71]
	v_mfma_f32_16x16x32_f16 v[64:67], v[182:185], v[214:217], v[64:67]
	v_mfma_f32_16x16x32_f16 v[116:119], v[178:181], v[194:197], v[116:119]
	v_mfma_f32_16x16x32_f16 v[112:115], v[186:189], v[194:197], v[112:115]
	v_mfma_f32_16x16x32_f16 v[100:103], v[178:181], v[202:205], v[100:103]
	v_mfma_f32_16x16x32_f16 v[96:99], v[186:189], v[202:205], v[96:99]
	v_mfma_f32_16x16x32_f16 v[84:87], v[178:181], v[210:213], v[84:87]
	v_mfma_f32_16x16x32_f16 v[80:83], v[186:189], v[210:213], v[80:83]
	v_mfma_f32_16x16x32_f16 v[68:71], v[178:181], v[218:221], v[68:71]
	v_mfma_f32_16x16x32_f16 v[64:67], v[186:189], v[218:221], v[64:67]
	s_barrier
	s_add_i32 s34, s48, s3
	v_lshl_add_u64 v[222:223], v[222:223], 0, s[10:11]
	s_mov_b32 m0, s34
	ds_read_b128 v[190:193], v153 offset:49152
	ds_read_b128 v[194:197], v153 offset:50176
	ds_read_b128 v[198:201], v153 offset:51200
	ds_read_b128 v[202:205], v153 offset:52224
	ds_read_b128 v[206:209], v153 offset:53248
	ds_read_b128 v[210:213], v153 offset:54272
	ds_read_b128 v[214:217], v153 offset:55296
	ds_read_b128 v[218:221], v153 offset:56320
	global_load_lds_dwordx4 v[222:223], off
	s_add_i32 m0, s34, 0x2000
	s_add_u32 s30, s30, 0x40080
	v_lshl_add_u64 v[222:223], v[224:225], 0, s[10:11]
	s_addc_u32 s31, s31, 0
	s_add_i32 s34, s49, s3
	global_load_lds_dwordx4 v[222:223], off
	v_lshl_add_u64 v[222:223], s[30:31], 0, v[132:133]
	s_mov_b32 m0, s34
	s_nop 0
	global_load_lds_dwordx4 v[222:223], off
	v_lshl_add_u64 v[222:223], s[30:31], 0, v[128:129]
	s_add_i32 m0, s34, 0x2000
	s_nop 0
	global_load_lds_dwordx4 v[222:223], off
	v_lshl_add_u64 v[222:223], v[226:227], 0, s[10:11]
	s_mov_b32 m0, s43
	s_nop 0
	global_load_lds_dwordx4 v[222:223], off
	v_lshl_add_u64 v[222:223], v[228:229], 0, s[10:11]
	s_mov_b32 m0, s44
	s_nop 0
	global_load_lds_dwordx4 v[222:223], off
	s_waitcnt vmcnt(8)
	s_waitcnt lgkmcnt(0)
	s_barrier
	s_waitcnt lgkmcnt(0)
	v_mfma_f32_16x16x32_f16 v[60:63], v[158:161], v[190:193], v[60:63]
	v_mfma_f32_16x16x32_f16 v[56:59], v[166:169], v[190:193], v[56:59]
	v_mfma_f32_16x16x32_f16 v[44:47], v[158:161], v[198:201], v[44:47]
	v_mfma_f32_16x16x32_f16 v[40:43], v[166:169], v[198:201], v[40:43]
	v_mfma_f32_16x16x32_f16 v[28:31], v[158:161], v[206:209], v[28:31]
	v_mfma_f32_16x16x32_f16 v[24:27], v[166:169], v[206:209], v[24:27]
	v_mfma_f32_16x16x32_f16 v[12:15], v[158:161], v[214:217], v[12:15]
	v_mfma_f32_16x16x32_f16 v[8:11], v[166:169], v[214:217], v[8:11]
	v_mfma_f32_16x16x32_f16 v[60:63], v[162:165], v[194:197], v[60:63]
	v_mfma_f32_16x16x32_f16 v[56:59], v[170:173], v[194:197], v[56:59]
	v_mfma_f32_16x16x32_f16 v[44:47], v[162:165], v[202:205], v[44:47]
	v_mfma_f32_16x16x32_f16 v[40:43], v[170:173], v[202:205], v[40:43]
	v_mfma_f32_16x16x32_f16 v[28:31], v[162:165], v[210:213], v[28:31]
	v_mfma_f32_16x16x32_f16 v[24:27], v[170:173], v[210:213], v[24:27]
	v_mfma_f32_16x16x32_f16 v[12:15], v[162:165], v[218:221], v[12:15]
	v_mfma_f32_16x16x32_f16 v[8:11], v[170:173], v[218:221], v[8:11]
	v_mfma_f32_16x16x32_f16 v[52:55], v[174:177], v[190:193], v[52:55]
	v_mfma_f32_16x16x32_f16 v[48:51], v[182:185], v[190:193], v[48:51]
	v_mfma_f32_16x16x32_f16 v[36:39], v[174:177], v[198:201], v[36:39]
	v_mfma_f32_16x16x32_f16 v[32:35], v[182:185], v[198:201], v[32:35]
	v_mfma_f32_16x16x32_f16 v[20:23], v[174:177], v[206:209], v[20:23]
	v_mfma_f32_16x16x32_f16 v[16:19], v[182:185], v[206:209], v[16:19]
	v_mfma_f32_16x16x32_f16 v[4:7], v[174:177], v[214:217], v[4:7]
	v_mfma_f32_16x16x32_f16 v[0:3], v[182:185], v[214:217], v[0:3]
	v_mfma_f32_16x16x32_f16 v[52:55], v[178:181], v[194:197], v[52:55]
	v_mfma_f32_16x16x32_f16 v[48:51], v[186:189], v[194:197], v[48:51]
	v_mfma_f32_16x16x32_f16 v[36:39], v[178:181], v[202:205], v[36:39]
	v_mfma_f32_16x16x32_f16 v[32:35], v[186:189], v[202:205], v[32:35]
	v_mfma_f32_16x16x32_f16 v[20:23], v[178:181], v[210:213], v[20:23]
	v_mfma_f32_16x16x32_f16 v[16:19], v[186:189], v[210:213], v[16:19]
	v_mfma_f32_16x16x32_f16 v[4:7], v[178:181], v[218:221], v[4:7]
	v_mfma_f32_16x16x32_f16 v[0:3], v[186:189], v[218:221], v[0:3]
	s_add_i32 s51, s51, 2
	s_add_u32 s22, s22, 0x100
	s_addc_u32 s23, s23, 0
	s_add_u32 s13, s13, 0x100
	s_addc_u32 s15, s15, 0
	s_cmp_gt_u32 s51, 13
	s_cbranch_scc0 .LBB0_1429
	s_barrier
	s_and_b64 vcc, exec, s[26:27]
	s_cbranch_vccz .LBB0_1432
	s_barrier
